# GEMM K-loops restructured: 8 phases of 16 MFMA merged into 4 phases of 32 MFMA (8 barriers per iteration instead of 16, regrouped LDS-DMA issue, uniform vmcnt(8)); plus r/ggla load hoist in gla_sample
# speedup vs baseline: 1.0111x; 1.0111x over previous
; #define PG8_STAGE(bufoff, gbase, voff) do { _Pragma("unroll") for (int _i = 0; _i < 2; ++_i) \
;         __builtin_amdgcn_global_load_lds((const unsigned*)((const char*)(gbase) + (voff)[_i]), (LAS unsigned*)(lds + (bufoff) + ldsw + _i * 8192), 16, 0, 0); } while (0)
; #define PG8_LDA(dst, b, h) do { _Pragma("unroll") for (int m = 0; m < 4; ++m) _Pragma("unroll") for (int k = 0; k < 2; ++k) dst[m][k] = *(const LAS bf16x8*)(lds + PG8_SA(b, h) + aoff + m * 2048 + k * 1024); } while (0)
; #define PG8_LDB(dst, b, h) do { _Pragma("unroll") for (int n = 0; n < 2; ++n) _Pragma("unroll") for (int k = 0; k < 2; ++k) dst[n][k] = *(const LAS bf16x8*)(lds + PG8_SB(b, h) + boff + n * 2048 + k * 1024); } while (0)
; #define PG8_MMA(ai, bj, At, Bt) do { __builtin_amdgcn_s_setprio(1); _Pragma("unroll") for (int m = 0; m < 4; ++m) _Pragma("unroll") for (int n = 0; n < 2; ++n) _Pragma("unroll") for (int k = 0; k < 2; ++k) \
;         acc[ai][bj][m][n] = __builtin_amdgcn_mfma_f32_16x16x32_bf16(Bt[n][k], At[m][k], acc[ai][bj][m][n], 0, 0, 0); __builtin_amdgcn_s_setprio(0); } while (0)
; #define PG8_WAIT_V(n) asm volatile("s_waitcnt vmcnt(" #n ")" ::: "memory")
; #define PG8_WAIT_L(n) asm volatile("s_waitcnt lgkmcnt(" #n ")" ::: "memory")
; #define PG8_BAR __builtin_amdgcn_s_barrier()
; #define PG8_SCHED __builtin_amdgcn_sched_barrier(0)
; template <class Epi>
; __device__ __forceinline__ void gemm_phase(LAS unsigned char* lds, const Gemm g, const StaticOrder& S, const Epi& E) {
;     ...
;             PG8_LDB(B0, 0, 0); PG8_SCHED; PG8_LDA(At, 0, 0); PG8_STAGE(PG8_SA(1, 1), a1 + hstepA, voffA);
;             PG8_WAIT_L(8); PG8_BAR; PG8_WAIT_L(0); PG8_MMA(0, 0, At, B0); PG8_BAR; PG8_SCHED;
;             PG8_LDB(B1, 0, 1); PG8_STAGE(PG8_SB(0, 0), b2, voffB);
;             PG8_BAR; PG8_WAIT_L(0); PG8_MMA(0, 1, At, B1); PG8_BAR;
;             PG8_LDA(At, 0, 1); PG8_STAGE(PG8_SA(0, 0), a2, voffA);
;             PG8_BAR; PG8_WAIT_L(0); PG8_MMA(1, 0, At, B0); PG8_BAR; PG8_SCHED;
;             PG8_STAGE(PG8_SB(0, 1), b2 + hstepB, voffB);
;             PG8_WAIT_V(6); PG8_BAR; PG8_MMA(1, 1, At, B1); PG8_BAR;
.LBB0_119:
	ds_read_b128 v[146:149], v154
	ds_read_b128 v[158:161], v154 offset:1024
	ds_read_b128 v[162:165], v154 offset:2048
	ds_read_b128 v[166:169], v154 offset:3072
	s_add_u32 s55, s62, 0xfffc0080
	s_addc_u32 s61, s63, -1
	s_cmp_eq_u32 s33, 12
	s_cselect_b32 s67, s57, s61
	s_cselect_b32 s66, s56, s55
	s_cselect_b32 s65, s59, s31
	s_cselect_b32 s64, s58, s9
	v_lshl_add_u64 v[202:203], s[62:63], 0, v[138:139]
	s_add_i32 m0, s68, 0xc000
	ds_read_b128 v[170:173], v155
	ds_read_b128 v[174:177], v155 offset:1024
	ds_read_b128 v[178:181], v155 offset:2048
	ds_read_b128 v[182:185], v155 offset:3072
	ds_read_b128 v[186:189], v155 offset:4096
	ds_read_b128 v[190:193], v155 offset:5120
	ds_read_b128 v[194:197], v155 offset:6144
	ds_read_b128 v[198:201], v155 offset:7168
	global_load_lds_dwordx4 v[202:203], off
	v_lshl_add_u64 v[202:203], s[62:63], 0, v[140:141]
	s_add_i32 m0, s68, 0xe000
	s_nop 0
	global_load_lds_dwordx4 v[202:203], off
	ds_read_b128 v[202:205], v156
	ds_read_b128 v[206:209], v156 offset:1024
	ds_read_b128 v[210:213], v156 offset:2048
	ds_read_b128 v[214:217], v156 offset:3072
	s_waitcnt vmcnt(8) lgkmcnt(0)
	s_barrier
	s_setprio 1
	v_mfma_f32_16x16x32_bf16 v[124:127], v[146:149], v[170:173], v[124:127]
	v_mfma_f32_16x16x32_bf16 v[120:123], v[162:165], v[170:173], v[120:123]
	v_mfma_f32_16x16x32_bf16 v[108:111], v[146:149], v[178:181], v[108:111]
	v_mfma_f32_16x16x32_bf16 v[104:107], v[162:165], v[178:181], v[104:107]
	v_mfma_f32_16x16x32_bf16 v[92:95], v[146:149], v[186:189], v[92:95]
	v_mfma_f32_16x16x32_bf16 v[88:91], v[162:165], v[186:189], v[88:91]
	v_mfma_f32_16x16x32_bf16 v[76:79], v[146:149], v[194:197], v[76:79]
	v_mfma_f32_16x16x32_bf16 v[72:75], v[162:165], v[194:197], v[72:75]
	v_mfma_f32_16x16x32_bf16 v[124:127], v[158:161], v[174:177], v[124:127]
	v_mfma_f32_16x16x32_bf16 v[120:123], v[166:169], v[174:177], v[120:123]
	v_mfma_f32_16x16x32_bf16 v[108:111], v[158:161], v[182:185], v[108:111]
	v_mfma_f32_16x16x32_bf16 v[104:107], v[166:169], v[182:185], v[104:107]
	v_mfma_f32_16x16x32_bf16 v[92:95], v[158:161], v[190:193], v[92:95]
	v_mfma_f32_16x16x32_bf16 v[88:91], v[166:169], v[190:193], v[88:91]
	v_mfma_f32_16x16x32_bf16 v[76:79], v[158:161], v[198:201], v[76:79]
	v_mfma_f32_16x16x32_bf16 v[72:75], v[166:169], v[198:201], v[72:75]
	v_mfma_f32_16x16x32_bf16 v[116:119], v[202:205], v[170:173], v[116:119]
	v_mfma_f32_16x16x32_bf16 v[112:115], v[210:213], v[170:173], v[112:115]
	v_mfma_f32_16x16x32_bf16 v[100:103], v[202:205], v[178:181], v[100:103]
	v_mfma_f32_16x16x32_bf16 v[96:99], v[210:213], v[178:181], v[96:99]
	v_mfma_f32_16x16x32_bf16 v[84:87], v[202:205], v[186:189], v[84:87]
	v_mfma_f32_16x16x32_bf16 v[80:83], v[210:213], v[186:189], v[80:83]
	v_mfma_f32_16x16x32_bf16 v[68:71], v[202:205], v[194:197], v[68:71]
	v_mfma_f32_16x16x32_bf16 v[64:67], v[210:213], v[194:197], v[64:67]
	v_mfma_f32_16x16x32_bf16 v[116:119], v[206:209], v[174:177], v[116:119]
	v_mfma_f32_16x16x32_bf16 v[112:115], v[214:217], v[174:177], v[112:115]
	v_mfma_f32_16x16x32_bf16 v[100:103], v[206:209], v[182:185], v[100:103]
	v_mfma_f32_16x16x32_bf16 v[96:99], v[214:217], v[182:185], v[96:99]
	v_mfma_f32_16x16x32_bf16 v[84:87], v[206:209], v[190:193], v[84:87]
	v_mfma_f32_16x16x32_bf16 v[80:83], v[214:217], v[190:193], v[80:83]
	v_mfma_f32_16x16x32_bf16 v[68:71], v[206:209], v[198:201], v[68:71]
	v_mfma_f32_16x16x32_bf16 v[64:67], v[214:217], v[198:201], v[64:67]
	s_setprio 0
	s_barrier
	s_add_i32 s55, s78, s35
	v_lshl_add_u64 v[218:219], s[64:65], 0, v[132:133]
	s_mov_b32 m0, s55
	global_load_lds_dwordx4 v[218:219], off
	v_lshl_add_u64 v[220:221], s[64:65], 0, v[136:137]
	s_add_i32 m0, s55, 0x2000
	s_nop 0
	global_load_lds_dwordx4 v[220:221], off
	s_mov_b32 m0, s68
	v_lshl_add_u64 v[222:223], s[66:67], 0, v[130:131]
	ds_read_b128 v[170:173], v155 offset:16384
	ds_read_b128 v[174:177], v155 offset:17408
	ds_read_b128 v[178:181], v155 offset:18432
	ds_read_b128 v[182:185], v155 offset:19456
	ds_read_b128 v[186:189], v155 offset:20480
	ds_read_b128 v[190:193], v155 offset:21504
	ds_read_b128 v[194:197], v155 offset:22528
	ds_read_b128 v[198:201], v155 offset:23552
	global_load_lds_dwordx4 v[222:223], off
	v_lshl_add_u64 v[224:225], s[66:67], 0, v[134:135]
	s_mov_b32 m0, s69
	s_nop 0
	global_load_lds_dwordx4 v[224:225], off
	s_add_u32 s82, s64, 0x40000
	s_addc_u32 s83, s65, 0
	s_add_i32 s55, s79, s35
	v_lshl_add_u64 v[240:241], s[82:83], 0, v[132:133]
	s_mov_b32 m0, s55
	s_nop 0
	global_load_lds_dwordx4 v[240:241], off
	v_lshl_add_u64 v[240:241], s[82:83], 0, v[136:137]
	s_add_i32 m0, s55, 0x2000
	s_nop 0
	global_load_lds_dwordx4 v[240:241], off
	s_waitcnt vmcnt(8) lgkmcnt(0)
	s_barrier
; #define PG8_STAGE(bufoff, gbase, voff) do { _Pragma("unroll") for (int _i = 0; _i < 2; ++_i) \
;         __builtin_amdgcn_global_load_lds((const unsigned*)((const char*)(gbase) + (voff)[_i]), (LAS unsigned*)(lds + (bufoff) + ldsw + _i * 8192), 16, 0, 0); } while (0)
; #define PG8_LDA(dst, b, h) do { _Pragma("unroll") for (int m = 0; m < 4; ++m) _Pragma("unroll") for (int k = 0; k < 2; ++k) dst[m][k] = *(const LAS bf16x8*)(lds + PG8_SA(b, h) + aoff + m * 2048 + k * 1024); } while (0)
; #define PG8_LDB(dst, b, h) do { _Pragma("unroll") for (int n = 0; n < 2; ++n) _Pragma("unroll") for (int k = 0; k < 2; ++k) dst[n][k] = *(const LAS bf16x8*)(lds + PG8_SB(b, h) + boff + n * 2048 + k * 1024); } while (0)
; #define PG8_MMA(ai, bj, At, Bt) do { __builtin_amdgcn_s_setprio(1); _Pragma("unroll") for (int m = 0; m < 4; ++m) _Pragma("unroll") for (int n = 0; n < 2; ++n) _Pragma("unroll") for (int k = 0; k < 2; ++k) \
;         acc[ai][bj][m][n] = __builtin_amdgcn_mfma_f32_16x16x32_bf16(Bt[n][k], At[m][k], acc[ai][bj][m][n], 0, 0, 0); __builtin_amdgcn_s_setprio(0); } while (0)
; #define PG8_WAIT_V(n) asm volatile("s_waitcnt vmcnt(" #n ")" ::: "memory")
; #define PG8_WAIT_L(n) asm volatile("s_waitcnt lgkmcnt(" #n ")" ::: "memory")
; #define PG8_BAR __builtin_amdgcn_s_barrier()
; #define PG8_SCHED __builtin_amdgcn_sched_barrier(0)
; template <class Epi>
; __device__ __forceinline__ void gemm_phase(LAS unsigned char* lds, const Gemm g, const StaticOrder& S, const Epi& E) {
;     ...
;             PG8_BAR; PG8_WAIT_L(0); PG8_MMA(1, 0, At, B0); PG8_BAR; PG8_SCHED;
;             PG8_STAGE(PG8_SB(0, 1), b2 + hstepB, voffB);
;             PG8_WAIT_V(6); PG8_BAR; PG8_MMA(1, 1, At, B1); PG8_BAR;
;             PG8_LDB(B0, 1, 0); PG8_SCHED; PG8_LDA(At, 1, 0); PG8_STAGE(PG8_SA(0, 1), a2 + hstepA, voffA);
;             PG8_WAIT_L(8); PG8_BAR; PG8_WAIT_L(0); PG8_MMA(0, 0, At, B0); PG8_BAR; PG8_SCHED;
	s_setprio 1
	v_mfma_f32_16x16x32_bf16 v[60:63], v[146:149], v[170:173], v[60:63]
	v_mfma_f32_16x16x32_bf16 v[56:59], v[162:165], v[170:173], v[56:59]
	v_mfma_f32_16x16x32_bf16 v[44:47], v[146:149], v[178:181], v[44:47]
	v_mfma_f32_16x16x32_bf16 v[40:43], v[162:165], v[178:181], v[40:43]
	v_mfma_f32_16x16x32_bf16 v[28:31], v[146:149], v[186:189], v[28:31]
	v_mfma_f32_16x16x32_bf16 v[24:27], v[162:165], v[186:189], v[24:27]
	v_mfma_f32_16x16x32_bf16 v[12:15], v[146:149], v[194:197], v[12:15]
	v_mfma_f32_16x16x32_bf16 v[8:11], v[162:165], v[194:197], v[8:11]
	v_mfma_f32_16x16x32_bf16 v[60:63], v[158:161], v[174:177], v[60:63]
	v_mfma_f32_16x16x32_bf16 v[56:59], v[166:169], v[174:177], v[56:59]
	v_mfma_f32_16x16x32_bf16 v[44:47], v[158:161], v[182:185], v[44:47]
	v_mfma_f32_16x16x32_bf16 v[40:43], v[166:169], v[182:185], v[40:43]
	v_mfma_f32_16x16x32_bf16 v[28:31], v[158:161], v[190:193], v[28:31]
	v_mfma_f32_16x16x32_bf16 v[24:27], v[166:169], v[190:193], v[24:27]
	v_mfma_f32_16x16x32_bf16 v[12:15], v[158:161], v[198:201], v[12:15]
	v_mfma_f32_16x16x32_bf16 v[8:11], v[166:169], v[198:201], v[8:11]
	v_mfma_f32_16x16x32_bf16 v[52:55], v[202:205], v[170:173], v[52:55]
	v_mfma_f32_16x16x32_bf16 v[48:51], v[210:213], v[170:173], v[48:51]
	v_mfma_f32_16x16x32_bf16 v[36:39], v[202:205], v[178:181], v[36:39]
	v_mfma_f32_16x16x32_bf16 v[32:35], v[210:213], v[178:181], v[32:35]
	v_mfma_f32_16x16x32_bf16 v[20:23], v[202:205], v[186:189], v[20:23]
	v_mfma_f32_16x16x32_bf16 v[16:19], v[210:213], v[186:189], v[16:19]
	v_mfma_f32_16x16x32_bf16 v[4:7], v[202:205], v[194:197], v[4:7]
	v_mfma_f32_16x16x32_bf16 v[0:3], v[210:213], v[194:197], v[0:3]
	v_mfma_f32_16x16x32_bf16 v[52:55], v[206:209], v[174:177], v[52:55]
	v_mfma_f32_16x16x32_bf16 v[48:51], v[214:217], v[174:177], v[48:51]
	v_mfma_f32_16x16x32_bf16 v[36:39], v[206:209], v[182:185], v[36:39]
	v_mfma_f32_16x16x32_bf16 v[32:35], v[214:217], v[182:185], v[32:35]
	v_mfma_f32_16x16x32_bf16 v[20:23], v[206:209], v[190:193], v[20:23]
	v_mfma_f32_16x16x32_bf16 v[16:19], v[214:217], v[190:193], v[16:19]
	v_mfma_f32_16x16x32_bf16 v[4:7], v[206:209], v[198:201], v[4:7]
	v_mfma_f32_16x16x32_bf16 v[0:3], v[214:217], v[198:201], v[0:3]
	s_setprio 0
	s_barrier
	s_add_i32 s55, 0, 0x18000
	v_add_u32_e32 v157, s55, v152
	ds_read_b128 v[146:149], v157
	ds_read_b128 v[158:161], v157 offset:1024
	ds_read_b128 v[162:165], v157 offset:2048
	ds_read_b128 v[166:169], v157 offset:3072
	s_add_u32 s66, s66, 0x40000
	s_addc_u32 s67, s67, 0
	s_mov_b32 m0, s70
	v_lshl_add_u64 v[202:203], s[66:67], 0, v[130:131]
	ds_read_b128 v[170:173], v155 offset:32768
	ds_read_b128 v[174:177], v155 offset:33792
	ds_read_b128 v[178:181], v155 offset:34816
	ds_read_b128 v[182:185], v155 offset:35840
	ds_read_b128 v[186:189], v155 offset:36864
	ds_read_b128 v[190:193], v155 offset:37888
	ds_read_b128 v[194:197], v155 offset:38912
	ds_read_b128 v[198:201], v155 offset:39936
	global_load_lds_dwordx4 v[202:203], off
	v_lshl_add_u64 v[202:203], s[66:67], 0, v[134:135]
	s_mov_b32 m0, s71
	s_nop 0
	global_load_lds_dwordx4 v[202:203], off
	s_add_i32 s61, 0, 0x1c000
	v_add_u32_e32 v157, s61, v152
	ds_read_b128 v[202:205], v157
	ds_read_b128 v[206:209], v157 offset:1024
	ds_read_b128 v[210:213], v157 offset:2048
	ds_read_b128 v[214:217], v157 offset:3072
	s_waitcnt vmcnt(8) lgkmcnt(0)
	s_barrier
	s_setprio 1
	v_mfma_f32_16x16x32_bf16 v[124:127], v[146:149], v[170:173], v[124:127]
	v_mfma_f32_16x16x32_bf16 v[120:123], v[162:165], v[170:173], v[120:123]
	v_mfma_f32_16x16x32_bf16 v[108:111], v[146:149], v[178:181], v[108:111]
	v_mfma_f32_16x16x32_bf16 v[104:107], v[162:165], v[178:181], v[104:107]
	v_mfma_f32_16x16x32_bf16 v[92:95], v[146:149], v[186:189], v[92:95]
	v_mfma_f32_16x16x32_bf16 v[88:91], v[162:165], v[186:189], v[88:91]
	v_mfma_f32_16x16x32_bf16 v[76:79], v[146:149], v[194:197], v[76:79]
	v_mfma_f32_16x16x32_bf16 v[72:75], v[162:165], v[194:197], v[72:75]
	v_mfma_f32_16x16x32_bf16 v[124:127], v[158:161], v[174:177], v[124:127]
	v_mfma_f32_16x16x32_bf16 v[120:123], v[166:169], v[174:177], v[120:123]
	v_mfma_f32_16x16x32_bf16 v[108:111], v[158:161], v[182:185], v[108:111]
	v_mfma_f32_16x16x32_bf16 v[104:107], v[166:169], v[182:185], v[104:107]
	v_mfma_f32_16x16x32_bf16 v[92:95], v[158:161], v[190:193], v[92:95]
	v_mfma_f32_16x16x32_bf16 v[88:91], v[166:169], v[190:193], v[88:91]
	v_mfma_f32_16x16x32_bf16 v[76:79], v[158:161], v[198:201], v[76:79]
	v_mfma_f32_16x16x32_bf16 v[72:75], v[166:169], v[198:201], v[72:75]
	v_mfma_f32_16x16x32_bf16 v[116:119], v[202:205], v[170:173], v[116:119]
	v_mfma_f32_16x16x32_bf16 v[112:115], v[210:213], v[170:173], v[112:115]
	v_mfma_f32_16x16x32_bf16 v[100:103], v[202:205], v[178:181], v[100:103]
	v_mfma_f32_16x16x32_bf16 v[96:99], v[210:213], v[178:181], v[96:99]
	v_mfma_f32_16x16x32_bf16 v[84:87], v[202:205], v[186:189], v[84:87]
	v_mfma_f32_16x16x32_bf16 v[80:83], v[210:213], v[186:189], v[80:83]
	v_mfma_f32_16x16x32_bf16 v[68:71], v[202:205], v[194:197], v[68:71]
	v_mfma_f32_16x16x32_bf16 v[64:67], v[210:213], v[194:197], v[64:67]
	v_mfma_f32_16x16x32_bf16 v[116:119], v[206:209], v[174:177], v[116:119]
	v_mfma_f32_16x16x32_bf16 v[112:115], v[214:217], v[174:177], v[112:115]
	v_mfma_f32_16x16x32_bf16 v[100:103], v[206:209], v[182:185], v[100:103]
	v_mfma_f32_16x16x32_bf16 v[96:99], v[214:217], v[182:185], v[96:99]
	v_mfma_f32_16x16x32_bf16 v[84:87], v[206:209], v[190:193], v[84:87]
	v_mfma_f32_16x16x32_bf16 v[80:83], v[214:217], v[190:193], v[80:83]
	v_mfma_f32_16x16x32_bf16 v[68:71], v[206:209], v[198:201], v[68:71]
	v_mfma_f32_16x16x32_bf16 v[64:67], v[214:217], v[198:201], v[64:67]
	s_setprio 0
	s_barrier
; #define PG8_WAIT_V(n) asm volatile("s_waitcnt vmcnt(" #n ")" ::: "memory")
; #define PG8_WAIT_L(n) asm volatile("s_waitcnt lgkmcnt(" #n ")" ::: "memory")
;     __device__ __forceinline__ void operator()(const f32x4 (&acc)[2][2][4][2], const Unit& u, int wr, int wc, int fr, int fq) const {
;     ...
;         for (int ai = 0; ai < 2; ++ai)
; #pragma unroll
;             for (int m = 0; m < 4; ++m) { const int row = row0 + ai * HALF + m * 16; u16* rowp = O + (size_t)row * ldc + col0;
; #pragma unroll
;                 for (int bj = 0; bj < 2; ++bj) { f32x4 v0 = acc[ai][bj][m][0], v1 = acc[ai][bj][m][1];
; template <class Epi>
; __device__ __forceinline__ void gemm_phase(LAS unsigned char* lds, const Gemm g, const StaticOrder& S, const Epi& E) {
;     ...
;         for (int t = 0; t < nt; t += 2) {
;             const bool last = (t == nt - 2);
;             const char* a1 = cA + (size_t)(t + 1) * kstep;
;             const char* a2 = last ? nA : cA + (size_t)(t + 2) * kstep; const char* b2 = last ? nB : cB + (size_t)(t + 2) * kstep;
;             const char* a3 = a2 + kstep; const char* b3 = b2 + kstep;
;             PG8_LDB(B0, 0, 0); PG8_SCHED; PG8_LDA(At, 0, 0); PG8_STAGE(PG8_SA(1, 1), a1 + hstepA, voffA);
;             PG8_WAIT_L(8); PG8_BAR; PG8_WAIT_L(0); PG8_MMA(0, 0, At, B0); PG8_BAR; PG8_SCHED;
;             PG8_LDB(B1, 0, 1); PG8_STAGE(PG8_SB(0, 0), b2, voffB);
;             PG8_BAR; PG8_WAIT_L(0); PG8_MMA(0, 1, At, B1); PG8_BAR;
;             PG8_LDA(At, 0, 1); PG8_STAGE(PG8_SA(0, 0), a2, voffA);
;             PG8_BAR; PG8_WAIT_L(0); PG8_MMA(1, 0, At, B0); PG8_BAR; PG8_SCHED;
;             PG8_STAGE(PG8_SB(0, 1), b2 + hstepB, voffB);
;             PG8_WAIT_V(6); PG8_BAR; PG8_MMA(1, 1, At, B1); PG8_BAR;
;             PG8_LDB(B0, 1, 0); PG8_SCHED; PG8_LDA(At, 1, 0); PG8_STAGE(PG8_SA(0, 1), a2 + hstepA, voffA);
;             PG8_WAIT_L(8); PG8_BAR; PG8_WAIT_L(0); PG8_MMA(0, 0, At, B0); PG8_BAR; PG8_SCHED;
;             PG8_LDB(B1, 1, 1); PG8_STAGE(PG8_SB(1, 0), b3, voffB);
;             PG8_BAR; PG8_WAIT_L(0); PG8_MMA(0, 1, At, B1); PG8_BAR;
;             PG8_LDA(At, 1, 1); PG8_STAGE(PG8_SA(1, 0), a3, voffA);
;             PG8_BAR; PG8_WAIT_L(0); PG8_MMA(1, 0, At, B0); PG8_BAR; PG8_SCHED;
;             PG8_STAGE(PG8_SB(1, 1), b3 + hstepB, voffB);
;             PG8_WAIT_V(6); PG8_BAR; PG8_MMA(1, 1, At, B1); PG8_BAR;
;         }
	s_add_i32 s55, s55, s35
	v_lshl_add_u64 v[218:219], v[218:219], 0, s[28:29]
	s_mov_b32 m0, s55
	global_load_lds_dwordx4 v[218:219], off
	v_lshl_add_u64 v[218:219], v[220:221], 0, s[28:29]
	s_add_i32 m0, s55, 0x2000
	s_nop 0
	global_load_lds_dwordx4 v[218:219], off
	s_mov_b32 m0, s73
	v_lshl_add_u64 v[218:219], v[222:223], 0, s[28:29]
	ds_read_b128 v[170:173], v155 offset:49152
	ds_read_b128 v[174:177], v155 offset:50176
	ds_read_b128 v[178:181], v155 offset:51200
	ds_read_b128 v[182:185], v155 offset:52224
	ds_read_b128 v[186:189], v155 offset:53248
	ds_read_b128 v[190:193], v155 offset:54272
	ds_read_b128 v[194:197], v155 offset:55296
	ds_read_b128 v[198:201], v155 offset:56320
	global_load_lds_dwordx4 v[218:219], off
	v_lshl_add_u64 v[218:219], v[224:225], 0, s[28:29]
	s_mov_b32 m0, s74
	s_nop 0
	global_load_lds_dwordx4 v[218:219], off
	s_add_u32 s64, s64, 0x40080
	s_addc_u32 s65, s65, 0
	s_add_i32 s55, s61, s35
	v_lshl_add_u64 v[240:241], s[64:65], 0, v[132:133]
	s_mov_b32 m0, s55
	s_nop 0
	global_load_lds_dwordx4 v[240:241], off
	v_lshl_add_u64 v[240:241], s[64:65], 0, v[136:137]
	s_add_i32 m0, s55, 0x2000
	s_nop 0
	global_load_lds_dwordx4 v[240:241], off
	s_waitcnt vmcnt(8) lgkmcnt(0)
	s_barrier
	s_setprio 1
	v_mfma_f32_16x16x32_bf16 v[60:63], v[146:149], v[170:173], v[60:63]
	v_mfma_f32_16x16x32_bf16 v[56:59], v[162:165], v[170:173], v[56:59]
	v_mfma_f32_16x16x32_bf16 v[44:47], v[146:149], v[178:181], v[44:47]
	v_mfma_f32_16x16x32_bf16 v[40:43], v[162:165], v[178:181], v[40:43]
	v_mfma_f32_16x16x32_bf16 v[28:31], v[146:149], v[186:189], v[28:31]
	v_mfma_f32_16x16x32_bf16 v[24:27], v[162:165], v[186:189], v[24:27]
	v_mfma_f32_16x16x32_bf16 v[12:15], v[146:149], v[194:197], v[12:15]
	v_mfma_f32_16x16x32_bf16 v[8:11], v[162:165], v[194:197], v[8:11]
	v_mfma_f32_16x16x32_bf16 v[60:63], v[158:161], v[174:177], v[60:63]
	v_mfma_f32_16x16x32_bf16 v[56:59], v[166:169], v[174:177], v[56:59]
	v_mfma_f32_16x16x32_bf16 v[44:47], v[158:161], v[182:185], v[44:47]
	v_mfma_f32_16x16x32_bf16 v[40:43], v[166:169], v[182:185], v[40:43]
	v_mfma_f32_16x16x32_bf16 v[28:31], v[158:161], v[190:193], v[28:31]
	v_mfma_f32_16x16x32_bf16 v[24:27], v[166:169], v[190:193], v[24:27]
	v_mfma_f32_16x16x32_bf16 v[12:15], v[158:161], v[198:201], v[12:15]
	v_mfma_f32_16x16x32_bf16 v[8:11], v[166:169], v[198:201], v[8:11]
	v_mfma_f32_16x16x32_bf16 v[52:55], v[202:205], v[170:173], v[52:55]
	v_mfma_f32_16x16x32_bf16 v[48:51], v[210:213], v[170:173], v[48:51]
	v_mfma_f32_16x16x32_bf16 v[36:39], v[202:205], v[178:181], v[36:39]
	v_mfma_f32_16x16x32_bf16 v[32:35], v[210:213], v[178:181], v[32:35]
	v_mfma_f32_16x16x32_bf16 v[20:23], v[202:205], v[186:189], v[20:23]
	v_mfma_f32_16x16x32_bf16 v[16:19], v[210:213], v[186:189], v[16:19]
	v_mfma_f32_16x16x32_bf16 v[4:7], v[202:205], v[194:197], v[4:7]
	v_mfma_f32_16x16x32_bf16 v[0:3], v[210:213], v[194:197], v[0:3]
	v_mfma_f32_16x16x32_bf16 v[52:55], v[206:209], v[174:177], v[52:55]
	v_mfma_f32_16x16x32_bf16 v[48:51], v[214:217], v[174:177], v[48:51]
	v_mfma_f32_16x16x32_bf16 v[36:39], v[206:209], v[182:185], v[36:39]
	v_mfma_f32_16x16x32_bf16 v[32:35], v[214:217], v[182:185], v[32:35]
	v_mfma_f32_16x16x32_bf16 v[20:23], v[206:209], v[190:193], v[20:23]
	v_mfma_f32_16x16x32_bf16 v[16:19], v[214:217], v[190:193], v[16:19]
	v_mfma_f32_16x16x32_bf16 v[4:7], v[206:209], v[198:201], v[4:7]
	v_mfma_f32_16x16x32_bf16 v[0:3], v[214:217], v[198:201], v[0:3]
	s_setprio 0
	s_add_i32 s33, s33, 2
	s_add_u32 s62, s62, 0x100
	s_addc_u32 s63, s63, 0
	s_add_u32 s9, s9, 0x100
	s_addc_u32 s31, s31, 0
	s_cmp_gt_u32 s33, 13
	s_barrier
	s_cbranch_scc0 .LBB0_119
	v_lshl_or_b32 v146, s60, 8, v153
	v_cmp_lt_i32_e32 vcc, s80, v146
	s_and_saveexec_b64 s[60:61], vcc
	s_cbranch_execz .LBB0_122
	v_mul_f32_e32 v148, 0x3d372713, v125
	v_mul_f32_e32 v148, v125, v148
	v_fma_f32 v148, v125, v148, v125
	v_mul_f32_e32 v147, 0x3d372713, v124
	v_mul_f32_e32 v148, 0xbfcc422a, v148
	v_mul_f32_e32 v147, v124, v147
	v_mul_f32_e32 v148, 0x3fb8aa3b, v148
	v_fma_f32 v147, v124, v147, v124
	v_exp_f32_e32 v149, v148
	v_mul_f32_e32 v148, 0x3d372713, v126
	v_mul_f32_e32 v147, 0xbfcc422a, v147
	v_mul_f32_e32 v148, v126, v148
	v_mul_f32_e32 v147, 0x3fb8aa3b, v147
	v_fma_f32 v148, v126, v148, v126
	v_exp_f32_e32 v147, v147
	v_mul_f32_e32 v148, 0xbfcc422a, v148
	v_mul_f32_e32 v148, 0x3fb8aa3b, v148
	v_exp_f32_e32 v157, v148
	v_add_f32_e32 v147, 1.0, v147
	v_rcp_f32_e32 v148, v147
	v_add_f32_e32 v147, 1.0, v149
	v_rcp_f32_e32 v149, v147
	v_add_f32_e32 v147, 1.0, v157
	v_mul_f32_e32 v157, 0x3d372713, v127
	v_mul_f32_e32 v157, v127, v157
	v_mul_f32_e32 v158, 0x3d372713, v120
	v_fma_f32 v157, v127, v157, v127
	v_mul_f32_e32 v158, v120, v158
	v_mul_f32_e32 v157, 0xbfcc422a, v157
	v_fma_f32 v158, v120, v158, v120
	v_mul_f32_e32 v157, 0x3fb8aa3b, v157
	v_mul_f32_e32 v158, 0xbfcc422a, v158
	v_exp_f32_e32 v157, v157
	v_mul_f32_e32 v158, 0x3fb8aa3b, v158
	v_exp_f32_e32 v160, v158
	v_rcp_f32_e32 v158, v147
	v_add_f32_e32 v147, 1.0, v157
	v_rcp_f32_e32 v159, v147
	v_add_f32_e32 v147, 1.0, v160
	v_mul_f32_e32 v157, 0x3d372713, v122
	v_rcp_f32_e32 v160, v147
	v_mul_f32_e32 v147, 0x3d372713, v121
	v_mul_f32_e32 v157, v122, v157
	v_mul_f32_e32 v161, 0x3d372713, v123
	v_mul_f32_e32 v147, v121, v147
	v_fma_f32 v157, v122, v157, v122
	v_mul_f32_e32 v161, v123, v161
	v_fma_f32 v147, v121, v147, v121
	v_mul_f32_e32 v157, 0xbfcc422a, v157
	v_fma_f32 v161, v123, v161, v123
	v_mul_f32_e32 v147, 0xbfcc422a, v147
	v_mul_f32_e32 v157, 0x3fb8aa3b, v157
	v_mul_f32_e32 v161, 0xbfcc422a, v161
	v_mul_f32_e32 v147, 0x3fb8aa3b, v147
	v_exp_f32_e32 v157, v157
	v_mul_f32_e32 v161, 0x3fb8aa3b, v161
	v_exp_f32_e32 v147, v147
	v_exp_f32_e32 v161, v161
	v_add_f32_e32 v157, 1.0, v157
	v_rcp_f32_e32 v162, v157
	v_add_f32_e32 v147, 1.0, v147
	v_add_f32_e32 v157, 1.0, v161
	v_rcp_f32_e32 v163, v157
	v_rcp_f32_e32 v161, v147
	v_pk_mul_f32 v[126:127], v[126:127], v[158:159]
	v_pk_mul_f32 v[124:125], v[124:125], v[148:149]
	v_pk_mul_f32 v[122:123], v[122:123], v[162:163]
	v_pk_mul_f32 v[120:121], v[120:121], v[160:161]

; #define LAS __attribute__((address_space(3)))
; __device__ __forceinline__ float bf2f(unsigned b) { return __uint_as_float(b << 16); }
; __device__ __forceinline__ unsigned pk2(float lo, float hi) { unsigned r; asm("v_cvt_pk_bf16_f32 %0, %1, %2" : "=v"(r) : "v"(lo), "v"(hi)); return r; }
; __device__ __forceinline__ float sigmoidf_(float x) { return __builtin_amdgcn_rcpf(1.f + __expf(-x)); }
; __device__ __forceinline__ void gla_sample_item(int nh, const u16* PROJ, u16* MIXIN, const float* wgate, const float* bgate, const float* ggla, const float* state_in, float* state_out, LAS unsigned char* lds) {
;     ...
; #pragma unroll
;     for (int t = 0; t < 4; ++t) {
;         const float v = bf2f(PROJ[((size_t)TP + n * 4 + t) * NPROJ + C_V + h * 128 + e]);
;         float po = 0.f;
; #pragma unroll
;         for (int i4 = 0; i4 < 4; ++i4) {
;             const f32x4 a = *(const LAS f32x4*)(AKQ + (t * 3 + 0) * 64 + dq * 16 + 4 * i4), k = *(const LAS f32x4*)(AKQ + (t * 3 + 1) * 64 + dq * 16 + 4 * i4), q = *(const LAS f32x4*)(AKQ + (t * 3 + 2) * 64 + dq * 16 + 4 * i4);
;             S[4 * i4 + 0] = a.x * S[4 * i4 + 0] + k.x * v; po += q.x * S[4 * i4 + 0];
;             S[4 * i4 + 1] = a.y * S[4 * i4 + 1] + k.y * v; po += q.y * S[4 * i4 + 1];
;             S[4 * i4 + 2] = a.z * S[4 * i4 + 2] + k.z * v; po += q.z * S[4 * i4 + 2];
;             S[4 * i4 + 3] = a.w * S[4 * i4 + 3] + k.w * v; po += q.w * S[4 * i4 + 3];
;         }
;         PO[(t * 4 + dq) * 128 + e] = po;
;     }
;     ...
;     const size_t row = (size_t)TP + n * 4 + t2;
;     const float r = bf2f(PROJ[row * NPROJ + C_R + h * 128 + e2]);
;     MIXIN[row * D + h * 128 + e2] = (u16)(pk2(o * rs * ggla[e2] * r * sigmoidf_(r), 0.f) & 0xffffu);
.LBB0_228:
	s_or_b64 exec, exec, s[82:83]
	s_lshl_b32 s6, s55, 7
	v_or_b32_e32 v2, s6, v142
	s_mul_i32 s55, s85, 0xb00
	v_or_b32_e32 v0, s55, v2
	s_waitcnt lgkmcnt(0)
	s_barrier
	v_lshlrev_b32_e32 v52, 1, v0
	global_load_ushort v3, v52, s[4:5]
	v_lshl_add_u64 v[192:193], s[4:5], 0, v[52:53]
	v_add_co_u32_e32 v194, vcc, 0x1000, v192
	s_nop 1
	v_addc_co_u32_e32 v195, vcc, 0, v193, vcc
	global_load_ushort v196, v[194:195], off offset:1536
	v_add_co_u32_e32 v194, vcc, 0x2000, v192
	s_nop 1
	v_addc_co_u32_e32 v195, vcc, 0, v193, vcc
	global_load_ushort v197, v[194:195], off offset:3072
	v_add_co_u32_e32 v194, vcc, 0x4000, v192
	s_nop 1
	v_addc_co_u32_e32 v195, vcc, 0, v193, vcc
	global_load_ushort v198, v[194:195], off offset:512
	s_add_i32 s98, s84, s85
	s_addk_i32 s98, 0x4000
	s_mul_hi_i32 s99, s98, 0x1600
	s_mul_i32 s98, s98, 0x1600
	s_add_u32 s100, s4, s98
	s_addc_u32 s101, s5, s99
	s_lshl_b32 s98, s6, 1
	s_add_u32 s100, s100, s98
	s_addc_u32 s101, s101, 0
	s_lshl_b32 s98, s86, 6
	v_and_or_b32 v199, s98, 64, v128
	v_lshlrev_b32_e32 v200, 1, v199
	v_lshlrev_b32_e32 v202, 2, v199
	global_load_ushort v201, v200, s[100:101] offset:2048
	global_load_dword v203, v202, s[40:41]
	s_lshl_b32 s54, s54, 2
	s_add_i32 s54, s54, 0
	v_mov_b32_e32 v5, s54
	ds_read_b128 v[22:25], v5 offset:256
	ds_read_b128 v[26:29], v5 offset:512
	ds_read_b128 v[88:91], v5
	ds_read_b128 v[92:95], v5 offset:16
	ds_read_b128 v[96:99], v5 offset:32
	ds_read_b128 v[100:103], v5 offset:48
	v_lshl_add_u64 v[0:1], s[4:5], 0, v[52:53]
	v_lshl_add_u32 v4, s84, 9, v106
	s_movk_i32 s54, 0x2000
	s_or_b32 s35, s35, 3
	s_mulk_i32 s35, 0xb00
	s_lshl_b64 s[78:79], s[80:81], 7
	s_waitcnt vmcnt(0)
	v_lshlrev_b32_e32 v3, 16, v3
	s_waitcnt lgkmcnt(5)
	v_mul_f32_e32 v30, v22, v3
	v_mul_f32_e32 v31, v23, v3
	v_mul_f32_e32 v52, v24, v3
	v_mul_f32_e32 v79, v25, v3
	s_waitcnt lgkmcnt(3)
	v_fmac_f32_e32 v30, v21, v88
	v_fmac_f32_e32 v31, v20, v89
	v_fmac_f32_e32 v52, v19, v90
	v_fmac_f32_e32 v79, v18, v91
	ds_read_b128 v[18:21], v5 offset:272
	ds_read_b128 v[22:25], v5 offset:528
	v_fma_f32 v26, v26, v30, 0
	v_fmac_f32_e32 v26, v27, v31
	v_fmac_f32_e32 v26, v28, v52
	s_waitcnt lgkmcnt(1)
	v_mul_f32_e32 v81, v18, v3
	v_fmac_f32_e32 v26, v29, v79
	v_fmac_f32_e32 v81, v17, v92
	v_mul_f32_e32 v83, v19, v3
	s_waitcnt lgkmcnt(0)
	v_fmac_f32_e32 v26, v22, v81
	v_fmac_f32_e32 v83, v16, v93
	v_fmac_f32_e32 v26, v23, v83
	v_mul_f32_e32 v85, v20, v3
	v_mul_f32_e32 v87, v21, v3
	ds_read_b128 v[16:19], v5 offset:288
	ds_read_b128 v[20:23], v5 offset:544
	v_fmac_f32_e32 v85, v14, v94
	v_fmac_f32_e32 v87, v12, v95
	v_fmac_f32_e32 v26, v24, v85
	s_waitcnt lgkmcnt(1)
	v_mul_f32_e32 v88, v16, v3
	v_mul_f32_e32 v89, v17, v3
	v_mul_f32_e32 v90, v18, v3
	v_mul_f32_e32 v91, v19, v3
	v_fmac_f32_e32 v88, v15, v96
	v_fmac_f32_e32 v89, v13, v97
	v_fmac_f32_e32 v90, v11, v98
	v_fmac_f32_e32 v91, v10, v99
	ds_read_b128 v[10:13], v5 offset:304
	ds_read_b128 v[14:17], v5 offset:560
	v_fmac_f32_e32 v26, v25, v87
	s_waitcnt lgkmcnt(2)
	v_fmac_f32_e32 v26, v20, v88
	v_fmac_f32_e32 v26, v21, v89
	s_waitcnt lgkmcnt(1)
	v_mul_f32_e32 v92, v10, v3
	v_mul_f32_e32 v93, v11, v3
	v_mul_f32_e32 v94, v12, v3
	v_mul_f32_e32 v3, v13, v3
	v_fmac_f32_e32 v3, v6, v103
	v_add_co_u32_e32 v6, vcc, s3, v0
	v_fmac_f32_e32 v94, v7, v102
	s_nop 0
	v_addc_co_u32_e32 v7, vcc, 0, v1, vcc
	s_nop 0
	v_fmac_f32_e32 v26, v22, v90
	v_fmac_f32_e32 v26, v23, v91
	v_fmac_f32_e32 v92, v9, v100
	s_waitcnt lgkmcnt(0)
	v_fmac_f32_e32 v26, v14, v92
	v_fmac_f32_e32 v93, v8, v101
	v_fmac_f32_e32 v26, v15, v93
	v_fmac_f32_e32 v26, v16, v94
	v_fmac_f32_e32 v26, v17, v3
	ds_write_b32 v4, v26 offset:3072
	v_add_co_u32_e32 v0, vcc, s54, v0
	s_nop 0
	v_lshlrev_b32_e32 v95, 16, v196
	ds_read_b128 v[6:9], v5 offset:1024
	ds_read_b128 v[10:13], v5 offset:1280
	ds_read_b128 v[14:17], v5 offset:768
	ds_read_b128 v[18:21], v5 offset:784
	ds_read_b128 v[22:25], v5 offset:800
	ds_read_b128 v[26:29], v5 offset:816
	s_waitcnt lgkmcnt(5)
	v_mul_f32_e32 v96, v6, v95
	s_waitcnt lgkmcnt(3)
	v_fmac_f32_e32 v96, v30, v14
	v_mul_f32_e32 v30, v7, v95
	v_fma_f32 v14, v10, v96, 0
	v_fmac_f32_e32 v30, v31, v15
	v_mul_f32_e32 v31, v8, v95
	v_fmac_f32_e32 v14, v11, v30
	v_fmac_f32_e32 v31, v52, v16
	v_mul_f32_e32 v52, v9, v95
	v_fmac_f32_e32 v14, v12, v31
	v_fmac_f32_e32 v52, v79, v17
	v_fmac_f32_e32 v14, v13, v52
	ds_read_b128 v[6:9], v5 offset:1040
	ds_read_b128 v[10:13], v5 offset:1296
	v_addc_co_u32_e32 v1, vcc, 0, v1, vcc
	s_waitcnt lgkmcnt(1)
	v_mul_f32_e32 v79, v6, v95
	v_fmac_f32_e32 v79, v81, v18
	v_mul_f32_e32 v81, v7, v95
	s_waitcnt lgkmcnt(0)
	v_fmac_f32_e32 v14, v10, v79
	v_fmac_f32_e32 v81, v83, v19
	v_mul_f32_e32 v83, v8, v95
	v_fmac_f32_e32 v14, v11, v81
	v_fmac_f32_e32 v83, v85, v20
	v_mul_f32_e32 v85, v9, v95
	v_fmac_f32_e32 v14, v12, v83
	v_fmac_f32_e32 v85, v87, v21
	v_fmac_f32_e32 v14, v13, v85
	ds_read_b128 v[6:9], v5 offset:1056
	ds_read_b128 v[10:13], v5 offset:1312
	s_waitcnt lgkmcnt(1)
	v_mul_f32_e32 v87, v6, v95
	v_fmac_f32_e32 v87, v88, v22
	v_mul_f32_e32 v97, v7, v95
	s_waitcnt lgkmcnt(0)
	v_fmac_f32_e32 v14, v10, v87
	v_fmac_f32_e32 v97, v89, v23
	v_mul_f32_e32 v98, v8, v95
	v_fmac_f32_e32 v14, v11, v97
	v_fmac_f32_e32 v98, v90, v24
	v_mul_f32_e32 v99, v9, v95
	v_fmac_f32_e32 v14, v12, v98
	v_fmac_f32_e32 v99, v91, v25
	v_fmac_f32_e32 v14, v13, v99
	ds_read_b128 v[6:9], v5 offset:1072
	ds_read_b128 v[10:13], v5 offset:1328
	s_nop 0
	s_waitcnt lgkmcnt(1)
	v_mul_f32_e32 v100, v6, v95
	v_fmac_f32_e32 v100, v92, v26
	v_mul_f32_e32 v92, v7, v95
	s_waitcnt lgkmcnt(0)
; #define LAS __attribute__((address_space(3)))
; __device__ __forceinline__ float bf2f(unsigned b) { return __uint_as_float(b << 16); }
; __device__ __forceinline__ void gla_sample_item(int nh, const u16* PROJ, u16* MIXIN, const float* wgate, const float* bgate, const float* ggla, const float* state_in, float* state_out, LAS unsigned char* lds) {
;     ...
;     for (int t = 0; t < 4; ++t) {
;         const float v = bf2f(PROJ[((size_t)TP + n * 4 + t) * NPROJ + C_V + h * 128 + e]);
;         float po = 0.f;
; #pragma unroll
;         for (int i4 = 0; i4 < 4; ++i4) {
;             const f32x4 a = *(const LAS f32x4*)(AKQ + (t * 3 + 0) * 64 + dq * 16 + 4 * i4), k = *(const LAS f32x4*)(AKQ + (t * 3 + 1) * 64 + dq * 16 + 4 * i4), q = *(const LAS f32x4*)(AKQ + (t * 3 + 2) * 64 + dq * 16 + 4 * i4);
;             S[4 * i4 + 0] = a.x * S[4 * i4 + 0] + k.x * v; po += q.x * S[4 * i4 + 0];
;             S[4 * i4 + 1] = a.y * S[4 * i4 + 1] + k.y * v; po += q.y * S[4 * i4 + 1];
;             S[4 * i4 + 2] = a.z * S[4 * i4 + 2] + k.z * v; po += q.z * S[4 * i4 + 2];
;             S[4 * i4 + 3] = a.w * S[4 * i4 + 3] + k.w * v; po += q.w * S[4 * i4 + 3];
;         }
;         PO[(t * 4 + dq) * 128 + e] = po;
;     }
;     float* so = state_out + ((size_t)nh * 64 + dq * 16) * 128 + e;
; #pragma unroll
;     for (int i = 0; i < 16; ++i) so[i * 128] = S[i];
	v_fmac_f32_e32 v14, v10, v100
	v_fmac_f32_e32 v92, v93, v27
	v_mul_f32_e32 v93, v8, v95
	v_fmac_f32_e32 v14, v11, v92
	v_fmac_f32_e32 v93, v94, v28
	v_mul_f32_e32 v94, v9, v95
	v_fmac_f32_e32 v14, v12, v93
	v_fmac_f32_e32 v94, v3, v29
	v_fmac_f32_e32 v14, v13, v94
	ds_write_b32 v4, v14 offset:5120
	ds_read_b128 v[6:9], v5 offset:1792
	ds_read_b128 v[10:13], v5 offset:2048
	ds_read_b128 v[14:17], v5 offset:1536
	ds_read_b128 v[22:25], v5 offset:1552
	ds_read_b128 v[26:29], v5 offset:1568
	ds_read_b128 v[88:91], v5 offset:1584
	s_nop 0
	v_lshlrev_b32_e32 v0, 16, v197
	s_waitcnt lgkmcnt(5)
	v_mul_f32_e32 v18, v6, v0
	s_waitcnt lgkmcnt(3)
	v_fmac_f32_e32 v18, v96, v14
	v_mul_f32_e32 v19, v7, v0
	v_fma_f32 v1, v10, v18, 0
	v_fmac_f32_e32 v19, v30, v15
	v_mul_f32_e32 v20, v8, v0
	v_fmac_f32_e32 v1, v11, v19
	v_fmac_f32_e32 v20, v31, v16
	v_mul_f32_e32 v21, v9, v0
	v_fmac_f32_e32 v1, v12, v20
	v_fmac_f32_e32 v21, v52, v17
	v_fmac_f32_e32 v1, v13, v21
	ds_read_b128 v[6:9], v5 offset:1808
	ds_read_b128 v[10:13], v5 offset:2064
	v_add_u32_e32 v52, s35, v2
	s_lshl_b32 s35, s86, 6
	s_waitcnt lgkmcnt(1)
	v_mul_f32_e32 v17, v6, v0
	v_mul_f32_e32 v16, v7, v0
	v_mul_f32_e32 v15, v8, v0
	v_mul_f32_e32 v14, v9, v0
	v_fmac_f32_e32 v17, v79, v22
	v_fmac_f32_e32 v16, v81, v23
	v_fmac_f32_e32 v15, v83, v24
	v_fmac_f32_e32 v14, v85, v25
	ds_read_b128 v[6:9], v5 offset:1824
	ds_read_b128 v[22:25], v5 offset:2080
	s_waitcnt lgkmcnt(2)
	v_fmac_f32_e32 v1, v10, v17
	v_fmac_f32_e32 v1, v11, v16
	v_fmac_f32_e32 v1, v12, v15
	s_waitcnt lgkmcnt(1)
	v_mul_f32_e32 v10, v6, v0
	v_fmac_f32_e32 v1, v13, v14
	v_fmac_f32_e32 v10, v87, v26
	v_mul_f32_e32 v11, v7, v0
	s_waitcnt lgkmcnt(0)
	v_fmac_f32_e32 v1, v22, v10
	v_fmac_f32_e32 v11, v97, v27
	v_mul_f32_e32 v12, v8, v0
	v_fmac_f32_e32 v1, v23, v11
	v_fmac_f32_e32 v12, v98, v28
	v_mul_f32_e32 v13, v9, v0
	v_fmac_f32_e32 v1, v24, v12
	v_fmac_f32_e32 v13, v99, v29
	v_fmac_f32_e32 v1, v25, v13
	ds_read_b128 v[22:25], v5 offset:1840
	ds_read_b128 v[26:29], v5 offset:2096
	s_waitcnt lgkmcnt(1)
	v_mul_f32_e32 v9, v22, v0
	v_fmac_f32_e32 v9, v100, v88
	v_mul_f32_e32 v8, v23, v0
	s_waitcnt lgkmcnt(0)
	v_fmac_f32_e32 v1, v26, v9
	v_fmac_f32_e32 v8, v92, v89
	v_mul_f32_e32 v7, v24, v0
	v_fmac_f32_e32 v1, v27, v8
	v_fmac_f32_e32 v7, v93, v90
	v_mul_f32_e32 v6, v25, v0
	v_fmac_f32_e32 v1, v28, v7
	v_fmac_f32_e32 v6, v94, v91
	v_fmac_f32_e32 v1, v29, v6
	ds_write_b32 v4, v1 offset:7168
	v_lshl_add_u64 v[0:1], v[52:53], 1, s[4:5]
	s_nop 0
	s_nop 0
	v_lshlrev_b32_e32 v30, 16, v198
	ds_read_b128 v[22:25], v5 offset:2560
	ds_read_b128 v[26:29], v5 offset:2816
	ds_read_b128 v[88:91], v5 offset:2304
	ds_read_b128 v[92:95], v5 offset:2320
	ds_read_b128 v[96:99], v5 offset:2336
	ds_read_b128 v[0:3], v5 offset:2352
	s_waitcnt lgkmcnt(5)
	v_mul_f32_e32 v31, v22, v30
	s_waitcnt lgkmcnt(3)
	v_fmac_f32_e32 v31, v18, v88
	v_mul_f32_e32 v52, v23, v30
	v_fma_f32 v26, v26, v31, 0
	v_fmac_f32_e32 v52, v19, v89
	v_fmac_f32_e32 v26, v27, v52
	v_mul_f32_e32 v27, v24, v30
	v_fmac_f32_e32 v27, v20, v90
	v_fmac_f32_e32 v26, v28, v27
	v_mul_f32_e32 v28, v25, v30
	v_fmac_f32_e32 v28, v21, v91
	ds_read_b128 v[18:21], v5 offset:2576
	ds_read_b128 v[22:25], v5 offset:2832
	v_fmac_f32_e32 v26, v29, v28
	s_waitcnt lgkmcnt(1)
	v_mul_f32_e32 v29, v18, v30
	v_fmac_f32_e32 v29, v17, v92
	s_waitcnt lgkmcnt(0)
	v_fmac_f32_e32 v26, v22, v29
	v_mul_f32_e32 v22, v19, v30
	v_fmac_f32_e32 v22, v16, v93
	v_fmac_f32_e32 v26, v23, v22
	v_mul_f32_e32 v23, v20, v30
	v_fmac_f32_e32 v23, v15, v94
	v_fmac_f32_e32 v26, v24, v23
	v_mul_f32_e32 v24, v21, v30
	v_fmac_f32_e32 v24, v14, v95
	ds_read_b128 v[14:17], v5 offset:2592
	ds_read_b128 v[18:21], v5 offset:2848
	v_fmac_f32_e32 v26, v25, v24
	s_waitcnt lgkmcnt(1)
	v_mul_f32_e32 v25, v14, v30
	v_fmac_f32_e32 v25, v10, v96
	s_waitcnt lgkmcnt(0)
	v_fmac_f32_e32 v26, v18, v25
	v_mul_f32_e32 v18, v15, v30
	v_fmac_f32_e32 v18, v11, v97
	v_fmac_f32_e32 v26, v19, v18
	v_mul_f32_e32 v19, v16, v30
	v_fmac_f32_e32 v19, v12, v98
	v_fmac_f32_e32 v26, v20, v19
	v_mul_f32_e32 v20, v17, v30
	v_fmac_f32_e32 v20, v13, v99
	ds_read_b128 v[10:13], v5 offset:2608
	ds_read_b128 v[14:17], v5 offset:2864
	v_fmac_f32_e32 v26, v21, v20
	s_waitcnt lgkmcnt(1)
	v_mul_f32_e32 v5, v10, v30
	v_fmac_f32_e32 v5, v9, v0
	v_mul_f32_e32 v9, v11, v30
	s_waitcnt lgkmcnt(0)
	v_fmac_f32_e32 v26, v14, v5
	v_fmac_f32_e32 v9, v8, v1
	v_mul_f32_e32 v8, v12, v30
	v_fmac_f32_e32 v26, v15, v9
	v_fmac_f32_e32 v8, v7, v2
	v_mul_f32_e32 v2, v13, v30
	v_fmac_f32_e32 v26, v16, v8
	v_fmac_f32_e32 v2, v6, v3
	v_fmac_f32_e32 v26, v17, v2
	v_lshl_add_u64 v[0:1], s[78:79], 2, v[58:59]
	ds_write_b32 v4, v26 offset:9216
	global_store_dword v[0:1], v31, off
	global_store_dword v[0:1], v52, off offset:512
	global_store_dword v[0:1], v27, off offset:1024
	global_store_dword v[0:1], v28, off offset:1536
	global_store_dword v[0:1], v29, off offset:2048
	global_store_dword v[0:1], v22, off offset:2560
	global_store_dword v[0:1], v23, off offset:3072
	global_store_dword v[0:1], v24, off offset:3584
	v_add_co_u32_e32 v0, vcc, s3, v0
	s_nop 1
	v_addc_co_u32_e32 v1, vcc, 0, v1, vcc
	global_store_dword v[0:1], v25, off
	global_store_dword v[0:1], v18, off offset:512
	global_store_dword v[0:1], v19, off offset:1024
	global_store_dword v[0:1], v20, off offset:1536
	global_store_dword v[0:1], v5, off offset:2048
	global_store_dword v[0:1], v9, off offset:2560
	global_store_dword v[0:1], v8, off offset:3072
	global_store_dword v[0:1], v2, off offset:3584
	v_and_or_b32 v0, s35, 64, v128
	s_lshl_b32 s35, s84, 11
	s_add_i32 s35, s35, 0
	s_waitcnt lgkmcnt(0)
	s_barrier
; __device__ __forceinline__ float bf2f(unsigned b) { return __uint_as_float(b << 16); }
; __device__ __forceinline__ unsigned pk2(float lo, float hi) { unsigned r; asm("v_cvt_pk_bf16_f32 %0, %1, %2" : "=v"(r) : "v"(lo), "v"(hi)); return r; }
; __device__ __forceinline__ float sigmoidf_(float x) { return __builtin_amdgcn_rcpf(1.f + __expf(-x)); }
; #define LBAR() do { asm volatile("s_waitcnt lgkmcnt(0)" ::: "memory"); __builtin_amdgcn_s_barrier(); asm volatile("" ::: "memory"); } while (0)
; __device__ __forceinline__ void gla_sample_item(int nh, const u16* PROJ, u16* MIXIN, const float* wgate, const float* bgate, const float* ggla, const float* state_in, float* state_out, LAS unsigned char* lds) {
;     ...
;     LBAR();
;     const int t2 = w >> 1, e2 = (w & 1) * 64 + lane;
;     const float o = (PO[(t2 * 4 + 0) * 128 + e2] + PO[(t2 * 4 + 1) * 128 + e2]) + (PO[(t2 * 4 + 2) * 128 + e2] + PO[(t2 * 4 + 3) * 128 + e2]);
;     const float part = wave_sum(o * o);
;     if (lane == 0) SS[w] = part;
;     LBAR();
;     const float rs = rsqrtf((SS[2 * t2] + SS[2 * t2 + 1]) * (1.f / 128.f) + EPS);
;     const size_t row = (size_t)TP + n * 4 + t2;
;     const float r = bf2f(PROJ[row * NPROJ + C_R + h * 128 + e2]);
;     MIXIN[row * D + h * 128 + e2] = (u16)(pk2(o * rs * ggla[e2] * r * sigmoidf_(r), 0.f) & 0xffffu);
;     LBAR();
	v_lshl_add_u32 v1, v0, 2, s35
	ds_read2st64_b32 v[2:3], v1 offset0:12 offset1:14
	s_waitcnt lgkmcnt(0)
	v_add_f32_e32 v4, v2, v3
	ds_read2st64_b32 v[2:3], v1 offset0:16 offset1:18
	s_waitcnt lgkmcnt(0)
	v_add_f32_e32 v1, v2, v3
	v_and_b32_e32 v3, 64, v153
	v_add_f32_e32 v1, v4, v1
	v_add_u32_e32 v3, 64, v3
	v_xor_b32_e32 v4, 1, v153
	v_cmp_lt_i32_e32 vcc, v4, v3
	v_mul_f32_e32 v2, v1, v1
	s_nop 0
	v_cndmask_b32_e32 v4, v153, v4, vcc
	v_lshlrev_b32_e32 v4, 2, v4
	ds_bpermute_b32 v2, v4, v2
	v_xor_b32_e32 v4, 2, v153
	v_cmp_lt_i32_e32 vcc, v4, v3
	s_waitcnt lgkmcnt(0)
	v_fmac_f32_e32 v2, v1, v1
	v_cndmask_b32_e32 v4, v153, v4, vcc
	v_lshlrev_b32_e32 v4, 2, v4
	ds_bpermute_b32 v4, v4, v2
	s_waitcnt lgkmcnt(0)
	v_add_f32_e32 v2, v2, v4
	v_xor_b32_e32 v4, 4, v153
	v_cmp_lt_i32_e32 vcc, v4, v3
	s_nop 1
	v_cndmask_b32_e32 v4, v153, v4, vcc
	v_lshlrev_b32_e32 v4, 2, v4
	ds_bpermute_b32 v4, v4, v2
	s_waitcnt lgkmcnt(0)
	v_add_f32_e32 v2, v2, v4
	v_xor_b32_e32 v4, 8, v153
	v_cmp_lt_i32_e32 vcc, v4, v3
	s_nop 1
	v_cndmask_b32_e32 v4, v153, v4, vcc
	v_lshlrev_b32_e32 v4, 2, v4
	ds_bpermute_b32 v4, v4, v2
	s_waitcnt lgkmcnt(0)
	v_add_f32_e32 v2, v2, v4
	v_xor_b32_e32 v4, 16, v153
	v_cmp_lt_i32_e32 vcc, v4, v3
	s_nop 1
	v_cndmask_b32_e32 v4, v153, v4, vcc
	v_lshlrev_b32_e32 v4, 2, v4
	ds_bpermute_b32 v4, v4, v2
	s_waitcnt lgkmcnt(0)
	v_add_f32_e32 v2, v2, v4
	v_xor_b32_e32 v4, 32, v153
	v_cmp_lt_i32_e32 vcc, v4, v3
	s_nop 1
	v_cndmask_b32_e32 v3, v153, v4, vcc
	v_lshlrev_b32_e32 v3, 2, v3
	ds_bpermute_b32 v3, v3, v2
	s_mov_b64 s[78:79], exec
	v_readlane_b32 s54, v237, 18
	v_readlane_b32 s55, v237, 19
	s_and_b64 s[54:55], s[78:79], s[54:55]
	s_mov_b64 exec, s[54:55]
	s_cbranch_execz .LBB0_230
	s_lshl_b32 s35, s86, 2
	s_add_i32 s35, s35, 0
	s_waitcnt lgkmcnt(0)
	v_add_f32_e32 v2, v2, v3
	v_mov_b32_e32 v3, s35
	ds_write_b32 v3, v2 offset:11264
.LBB0_230:
	s_or_b64 exec, exec, s[78:79]
	s_and_b32 s35, s86, 0x3ffffffe
	s_lshl_b32 s35, s35, 2
	s_add_i32 s35, s35, 0
	v_mov_b32_e32 v2, s35
	s_lshl_b32 s35, s86, 2
	s_or_b32 s35, s35, 4
	s_add_i32 s35, s35, 0
	s_waitcnt lgkmcnt(0)
	s_barrier
	s_waitcnt lgkmcnt(0)
	v_mov_b32_e32 v3, s35
	ds_read_b32 v2, v2 offset:11264
	ds_read_b32 v3, v3 offset:11264
	s_bitset1_b32 s85, 14
	s_ashr_i32 s35, s84, 31
	s_add_u32 s54, s84, s85
	s_addc_u32 s55, s35, 0
	s_waitcnt lgkmcnt(0)
	v_add_f32_e32 v2, v2, v3
	v_fmamk_f32 v2, v2, 0x3c000000, v144
	v_cmp_gt_f32_e32 vcc, s21, v2
	v_mul_f32_e32 v3, 0x4b800000, v2
	s_mul_i32 s56, s54, 0x1600
	v_cndmask_b32_e32 v2, v2, v3, vcc
	v_rsq_f32_e32 v2, v2
	s_mul_hi_i32 s35, s54, 0x1600
	s_add_u32 s56, s4, s56
	s_addc_u32 s35, s5, s35
	s_lshl_b32 s6, s6, 1
	v_mul_f32_e32 v3, 0x45800000, v2
	s_add_u32 s56, s56, s6
	v_cndmask_b32_e32 v2, v2, v3, vcc
	s_addc_u32 s57, s35, 0
	v_lshlrev_b32_e32 v3, 1, v0
	s_nop 0
	v_lshlrev_b32_e32 v0, 2, v0
	s_nop 0
	v_mul_f32_e32 v1, v1, v2
	s_lshl_b64 s[54:55], s[54:55], 11
	s_add_u32 s35, s52, s54
	s_addc_u32 s55, s53, s55
	s_add_u32 s54, s35, s6
	s_addc_u32 s55, s55, 0
	s_mov_b64 s[78:79], 0
	s_nop 0
	v_lshlrev_b32_e32 v4, 16, v201
	s_nop 0
	v_mul_f32_e32 v0, v203, v1
	v_mul_f32_e32 v1, 0xbfb8aa3b, v4
	v_exp_f32_e32 v1, v1
	v_mul_f32_e32 v0, v0, v4
	v_add_f32_e32 v1, 1.0, v1
	v_rcp_f32_e32 v1, v1
	s_nop 0
	v_mul_f32_e32 v0, v1, v0
	v_cvt_pk_bf16_f32 v0, v0, v53
	global_store_short v3, v0, s[54:55]
	s_waitcnt lgkmcnt(0)
	s_barrier

; #define PG8_STAGE(bufoff, gbase, voff) do { _Pragma("unroll") for (int _i = 0; _i < 2; ++_i) \
;         __builtin_amdgcn_global_load_lds((const unsigned*)((const char*)(gbase) + (voff)[_i]), (LAS unsigned*)(lds + (bufoff) + ldsw + _i * 8192), 16, 0, 0); } while (0)
; #define PG8_LDA(dst, b, h) do { _Pragma("unroll") for (int m = 0; m < 4; ++m) _Pragma("unroll") for (int k = 0; k < 2; ++k) dst[m][k] = *(const LAS bf16x8*)(lds + PG8_SA(b, h) + aoff + m * 2048 + k * 1024); } while (0)
; #define PG8_LDB(dst, b, h) do { _Pragma("unroll") for (int n = 0; n < 2; ++n) _Pragma("unroll") for (int k = 0; k < 2; ++k) dst[n][k] = *(const LAS bf16x8*)(lds + PG8_SB(b, h) + boff + n * 2048 + k * 1024); } while (0)
; #define PG8_MMA(ai, bj, At, Bt) do { __builtin_amdgcn_s_setprio(1); _Pragma("unroll") for (int m = 0; m < 4; ++m) _Pragma("unroll") for (int n = 0; n < 2; ++n) _Pragma("unroll") for (int k = 0; k < 2; ++k) \
;         acc[ai][bj][m][n] = __builtin_amdgcn_mfma_f32_16x16x32_bf16(Bt[n][k], At[m][k], acc[ai][bj][m][n], 0, 0, 0); __builtin_amdgcn_s_setprio(0); } while (0)
; #define PG8_WAIT_V(n) asm volatile("s_waitcnt vmcnt(" #n ")" ::: "memory")
; #define PG8_WAIT_L(n) asm volatile("s_waitcnt lgkmcnt(" #n ")" ::: "memory")
; template <class Epi>
; __device__ __forceinline__ void gemm_phase(LAS unsigned char* lds, const Gemm g, const StaticOrder& S, const Epi& E) {
;     ...
;         for (int t = 0; t < nt; t += 2) {
;             const bool last = (t == nt - 2);
;             const char* a1 = cA + (size_t)(t + 1) * kstep;
;             const char* a2 = last ? nA : cA + (size_t)(t + 2) * kstep; const char* b2 = last ? nB : cB + (size_t)(t + 2) * kstep;
;             const char* a3 = a2 + kstep; const char* b3 = b2 + kstep;
;             PG8_LDB(B0, 0, 0); PG8_SCHED; PG8_LDA(At, 0, 0); PG8_STAGE(PG8_SA(1, 1), a1 + hstepA, voffA);
;             PG8_WAIT_L(8); PG8_BAR; PG8_WAIT_L(0); PG8_MMA(0, 0, At, B0); PG8_BAR; PG8_SCHED;
;             PG8_LDB(B1, 0, 1); PG8_STAGE(PG8_SB(0, 0), b2, voffB);
;             PG8_BAR; PG8_WAIT_L(0); PG8_MMA(0, 1, At, B1); PG8_BAR;
;             PG8_LDA(At, 0, 1); PG8_STAGE(PG8_SA(0, 0), a2, voffA);
;             PG8_BAR; PG8_WAIT_L(0); PG8_MMA(1, 0, At, B0); PG8_BAR; PG8_SCHED;
;             PG8_STAGE(PG8_SB(0, 1), b2 + hstepB, voffB);
;             PG8_WAIT_V(6); PG8_BAR; PG8_MMA(1, 1, At, B1); PG8_BAR;
.LBB0_456:
	ds_read_b128 v[144:147], v158
	ds_read_b128 v[148:151], v158 offset:1024
	ds_read_b128 v[162:165], v158 offset:2048
	ds_read_b128 v[166:169], v158 offset:3072
	s_add_i32 s85, s59, 2
	s_add_u32 s66, s64, 0xfffc0080
	s_addc_u32 s67, s65, -1
	s_cmp_eq_u32 s21, s59
	s_cselect_b32 s69, s63, s67
	s_cselect_b32 s68, s62, s66
	s_cselect_b32 s67, s1, s57
	s_cselect_b32 s66, s0, s31
	v_lshl_add_u64 v[152:153], s[64:65], 0, v[138:139]
	s_add_i32 m0, s35, 0xc000
	ds_read_b128 v[170:173], v159
	ds_read_b128 v[174:177], v159 offset:1024
	ds_read_b128 v[178:181], v159 offset:2048
	ds_read_b128 v[182:185], v159 offset:3072
	ds_read_b128 v[186:189], v159 offset:4096
	ds_read_b128 v[190:193], v159 offset:5120
	ds_read_b128 v[194:197], v159 offset:6144
	ds_read_b128 v[198:201], v159 offset:7168
	global_load_lds_dwordx4 v[152:153], off
	v_lshl_add_u64 v[152:153], s[64:65], 0, v[140:141]
	s_add_i32 m0, s35, 0xe000
	s_nop 0
	global_load_lds_dwordx4 v[152:153], off
	ds_read_b128 v[202:205], v160
	ds_read_b128 v[206:209], v160 offset:1024
	ds_read_b128 v[210:213], v160 offset:2048
	ds_read_b128 v[214:217], v160 offset:3072
	s_waitcnt vmcnt(8) lgkmcnt(0)
	s_barrier
	s_setprio 1
	v_mfma_f32_16x16x32_bf16 v[124:127], v[144:147], v[170:173], v[124:127]
	v_mfma_f32_16x16x32_bf16 v[120:123], v[162:165], v[170:173], v[120:123]
	v_mfma_f32_16x16x32_bf16 v[116:119], v[144:147], v[178:181], v[116:119]
	v_mfma_f32_16x16x32_bf16 v[108:111], v[162:165], v[178:181], v[108:111]
	v_mfma_f32_16x16x32_bf16 v[100:103], v[144:147], v[186:189], v[100:103]
	v_mfma_f32_16x16x32_bf16 v[92:95], v[162:165], v[186:189], v[92:95]
	v_mfma_f32_16x16x32_bf16 v[84:87], v[144:147], v[194:197], v[84:87]
	v_mfma_f32_16x16x32_bf16 v[76:79], v[162:165], v[194:197], v[76:79]
	v_mfma_f32_16x16x32_bf16 v[124:127], v[148:151], v[174:177], v[124:127]
	v_mfma_f32_16x16x32_bf16 v[120:123], v[166:169], v[174:177], v[120:123]
	v_mfma_f32_16x16x32_bf16 v[116:119], v[148:151], v[182:185], v[116:119]
	v_mfma_f32_16x16x32_bf16 v[108:111], v[166:169], v[182:185], v[108:111]
	v_mfma_f32_16x16x32_bf16 v[100:103], v[148:151], v[190:193], v[100:103]
	v_mfma_f32_16x16x32_bf16 v[92:95], v[166:169], v[190:193], v[92:95]
	v_mfma_f32_16x16x32_bf16 v[84:87], v[148:151], v[198:201], v[84:87]
	v_mfma_f32_16x16x32_bf16 v[76:79], v[166:169], v[198:201], v[76:79]
	v_mfma_f32_16x16x32_bf16 v[112:115], v[202:205], v[170:173], v[112:115]
	v_mfma_f32_16x16x32_bf16 v[104:107], v[210:213], v[170:173], v[104:107]
	v_mfma_f32_16x16x32_bf16 v[96:99], v[202:205], v[178:181], v[96:99]
	v_mfma_f32_16x16x32_bf16 v[88:91], v[210:213], v[178:181], v[88:91]
	v_mfma_f32_16x16x32_bf16 v[80:83], v[202:205], v[186:189], v[80:83]
	v_mfma_f32_16x16x32_bf16 v[72:75], v[210:213], v[186:189], v[72:75]
	v_mfma_f32_16x16x32_bf16 v[68:71], v[202:205], v[194:197], v[68:71]
	v_mfma_f32_16x16x32_bf16 v[64:67], v[210:213], v[194:197], v[64:67]
	v_mfma_f32_16x16x32_bf16 v[112:115], v[206:209], v[174:177], v[112:115]
	v_mfma_f32_16x16x32_bf16 v[104:107], v[214:217], v[174:177], v[104:107]
	v_mfma_f32_16x16x32_bf16 v[96:99], v[206:209], v[182:185], v[96:99]
	v_mfma_f32_16x16x32_bf16 v[88:91], v[214:217], v[182:185], v[88:91]
	v_mfma_f32_16x16x32_bf16 v[80:83], v[206:209], v[190:193], v[80:83]
	v_mfma_f32_16x16x32_bf16 v[72:75], v[214:217], v[190:193], v[72:75]
	v_mfma_f32_16x16x32_bf16 v[68:71], v[206:209], v[198:201], v[68:71]
	v_mfma_f32_16x16x32_bf16 v[64:67], v[214:217], v[198:201], v[64:67]
	s_setprio 0
	s_barrier
	s_add_i32 s59, s78, s33
	v_lshl_add_u64 v[152:153], s[66:67], 0, v[132:133]
	s_mov_b32 m0, s59
	global_load_lds_dwordx4 v[152:153], off
	v_lshl_add_u64 v[218:219], s[66:67], 0, v[136:137]
	s_add_i32 m0, s59, 0x2000
	s_nop 0
	global_load_lds_dwordx4 v[218:219], off
	s_mov_b32 m0, s35
	v_lshl_add_u64 v[220:221], s[68:69], 0, v[130:131]
	ds_read_b128 v[170:173], v159 offset:16384
	ds_read_b128 v[174:177], v159 offset:17408
	ds_read_b128 v[178:181], v159 offset:18432
	ds_read_b128 v[182:185], v159 offset:19456
	ds_read_b128 v[186:189], v159 offset:20480
	ds_read_b128 v[190:193], v159 offset:21504
	ds_read_b128 v[194:197], v159 offset:22528
	ds_read_b128 v[198:201], v159 offset:23552
	global_load_lds_dwordx4 v[220:221], off
	v_lshl_add_u64 v[222:223], s[68:69], 0, v[134:135]
	s_mov_b32 m0, s70
	s_nop 0
	global_load_lds_dwordx4 v[222:223], off
	s_add_u32 s86, s66, 0x40000
	s_addc_u32 s87, s67, 0
	s_add_i32 s59, s79, s33
	v_lshl_add_u64 v[240:241], s[86:87], 0, v[132:133]
	s_mov_b32 m0, s59
	s_nop 0
	global_load_lds_dwordx4 v[240:241], off
	v_lshl_add_u64 v[240:241], s[86:87], 0, v[136:137]
	s_add_i32 m0, s59, 0x2000
	s_nop 0
	global_load_lds_dwordx4 v[240:241], off
	s_waitcnt vmcnt(8) lgkmcnt(0)
	s_barrier
; #define PG8_STAGE(bufoff, gbase, voff) do { _Pragma("unroll") for (int _i = 0; _i < 2; ++_i) \
;         __builtin_amdgcn_global_load_lds((const unsigned*)((const char*)(gbase) + (voff)[_i]), (LAS unsigned*)(lds + (bufoff) + ldsw + _i * 8192), 16, 0, 0); } while (0)
; #define PG8_LDA(dst, b, h) do { _Pragma("unroll") for (int m = 0; m < 4; ++m) _Pragma("unroll") for (int k = 0; k < 2; ++k) dst[m][k] = *(const LAS bf16x8*)(lds + PG8_SA(b, h) + aoff + m * 2048 + k * 1024); } while (0)
; #define PG8_LDB(dst, b, h) do { _Pragma("unroll") for (int n = 0; n < 2; ++n) _Pragma("unroll") for (int k = 0; k < 2; ++k) dst[n][k] = *(const LAS bf16x8*)(lds + PG8_SB(b, h) + boff + n * 2048 + k * 1024); } while (0)
; #define PG8_MMA(ai, bj, At, Bt) do { __builtin_amdgcn_s_setprio(1); _Pragma("unroll") for (int m = 0; m < 4; ++m) _Pragma("unroll") for (int n = 0; n < 2; ++n) _Pragma("unroll") for (int k = 0; k < 2; ++k) \
;         acc[ai][bj][m][n] = __builtin_amdgcn_mfma_f32_16x16x32_bf16(Bt[n][k], At[m][k], acc[ai][bj][m][n], 0, 0, 0); __builtin_amdgcn_s_setprio(0); } while (0)
; #define PG8_WAIT_V(n) asm volatile("s_waitcnt vmcnt(" #n ")" ::: "memory")
; #define PG8_WAIT_L(n) asm volatile("s_waitcnt lgkmcnt(" #n ")" ::: "memory")
; #define PG8_BAR __builtin_amdgcn_s_barrier()
; #define PG8_SCHED __builtin_amdgcn_sched_barrier(0)
; template <class Epi>
; __device__ __forceinline__ void gemm_phase(LAS unsigned char* lds, const Gemm g, const StaticOrder& S, const Epi& E) {
;     ...
;             PG8_LDA(At, 0, 1); PG8_STAGE(PG8_SA(0, 0), a2, voffA);
;             PG8_BAR; PG8_WAIT_L(0); PG8_MMA(1, 0, At, B0); PG8_BAR; PG8_SCHED;
;             PG8_STAGE(PG8_SB(0, 1), b2 + hstepB, voffB);
;             PG8_WAIT_V(6); PG8_BAR; PG8_MMA(1, 1, At, B1); PG8_BAR;
;             PG8_LDB(B0, 1, 0); PG8_SCHED; PG8_LDA(At, 1, 0); PG8_STAGE(PG8_SA(0, 1), a2 + hstepA, voffA);
;             PG8_WAIT_L(8); PG8_BAR; PG8_WAIT_L(0); PG8_MMA(0, 0, At, B0); PG8_BAR; PG8_SCHED;
;             PG8_LDB(B1, 1, 1); PG8_STAGE(PG8_SB(1, 0), b3, voffB);
;             PG8_BAR; PG8_WAIT_L(0); PG8_MMA(0, 1, At, B1); PG8_BAR;
	s_setprio 1
	v_mfma_f32_16x16x32_bf16 v[60:63], v[144:147], v[170:173], v[60:63]
	v_mfma_f32_16x16x32_bf16 v[56:59], v[162:165], v[170:173], v[56:59]
	v_mfma_f32_16x16x32_bf16 v[52:55], v[144:147], v[178:181], v[52:55]
	v_mfma_f32_16x16x32_bf16 v[44:47], v[162:165], v[178:181], v[44:47]
	v_mfma_f32_16x16x32_bf16 v[36:39], v[144:147], v[186:189], v[36:39]
	v_mfma_f32_16x16x32_bf16 v[28:31], v[162:165], v[186:189], v[28:31]
	v_mfma_f32_16x16x32_bf16 v[20:23], v[144:147], v[194:197], v[20:23]
	v_mfma_f32_16x16x32_bf16 v[12:15], v[162:165], v[194:197], v[12:15]
	v_mfma_f32_16x16x32_bf16 v[60:63], v[148:151], v[174:177], v[60:63]
	v_mfma_f32_16x16x32_bf16 v[56:59], v[166:169], v[174:177], v[56:59]
	v_mfma_f32_16x16x32_bf16 v[52:55], v[148:151], v[182:185], v[52:55]
	v_mfma_f32_16x16x32_bf16 v[44:47], v[166:169], v[182:185], v[44:47]
	v_mfma_f32_16x16x32_bf16 v[36:39], v[148:151], v[190:193], v[36:39]
	v_mfma_f32_16x16x32_bf16 v[28:31], v[166:169], v[190:193], v[28:31]
	v_mfma_f32_16x16x32_bf16 v[20:23], v[148:151], v[198:201], v[20:23]
	v_mfma_f32_16x16x32_bf16 v[12:15], v[166:169], v[198:201], v[12:15]
	v_mfma_f32_16x16x32_bf16 v[48:51], v[202:205], v[170:173], v[48:51]
	v_mfma_f32_16x16x32_bf16 v[40:43], v[210:213], v[170:173], v[40:43]
	v_mfma_f32_16x16x32_bf16 v[32:35], v[202:205], v[178:181], v[32:35]
	v_mfma_f32_16x16x32_bf16 v[24:27], v[210:213], v[178:181], v[24:27]
	v_mfma_f32_16x16x32_bf16 v[16:19], v[202:205], v[186:189], v[16:19]
	v_mfma_f32_16x16x32_bf16 v[8:11], v[210:213], v[186:189], v[8:11]
	v_mfma_f32_16x16x32_bf16 v[4:7], v[202:205], v[194:197], v[4:7]
	v_mfma_f32_16x16x32_bf16 v[0:3], v[210:213], v[194:197], v[0:3]
	v_mfma_f32_16x16x32_bf16 v[48:51], v[206:209], v[174:177], v[48:51]
	v_mfma_f32_16x16x32_bf16 v[40:43], v[214:217], v[174:177], v[40:43]
	v_mfma_f32_16x16x32_bf16 v[32:35], v[206:209], v[182:185], v[32:35]
	v_mfma_f32_16x16x32_bf16 v[24:27], v[214:217], v[182:185], v[24:27]
	v_mfma_f32_16x16x32_bf16 v[16:19], v[206:209], v[190:193], v[16:19]
	v_mfma_f32_16x16x32_bf16 v[8:11], v[214:217], v[190:193], v[8:11]
	v_mfma_f32_16x16x32_bf16 v[4:7], v[206:209], v[198:201], v[4:7]
	v_mfma_f32_16x16x32_bf16 v[0:3], v[214:217], v[198:201], v[0:3]
	s_setprio 0
	s_barrier
	s_add_i32 s59, 0, 0x18000
	v_add_u32_e32 v161, s59, v156
	ds_read_b128 v[144:147], v161
	ds_read_b128 v[148:151], v161 offset:1024
	ds_read_b128 v[162:165], v161 offset:2048
	ds_read_b128 v[166:169], v161 offset:3072
	s_add_u32 s68, s68, 0x40000
	s_addc_u32 s69, s69, 0
	s_mov_b32 m0, s71
	v_lshl_add_u64 v[202:203], s[68:69], 0, v[130:131]
	ds_read_b128 v[170:173], v159 offset:32768
	ds_read_b128 v[174:177], v159 offset:33792
	ds_read_b128 v[178:181], v159 offset:34816
	ds_read_b128 v[182:185], v159 offset:35840
	ds_read_b128 v[186:189], v159 offset:36864
	ds_read_b128 v[190:193], v159 offset:37888
	ds_read_b128 v[194:197], v159 offset:38912
	ds_read_b128 v[198:201], v159 offset:39936
	global_load_lds_dwordx4 v[202:203], off
	v_lshl_add_u64 v[202:203], s[68:69], 0, v[134:135]
	s_mov_b32 m0, s72
	s_nop 0
	global_load_lds_dwordx4 v[202:203], off
	s_add_i32 s68, 0, 0x1c000
	v_add_u32_e32 v161, s68, v156
	ds_read_b128 v[202:205], v161
	ds_read_b128 v[206:209], v161 offset:1024
	ds_read_b128 v[210:213], v161 offset:2048
	ds_read_b128 v[214:217], v161 offset:3072
	s_waitcnt vmcnt(8) lgkmcnt(0)
	s_barrier
	s_setprio 1
	v_mfma_f32_16x16x32_bf16 v[124:127], v[144:147], v[170:173], v[124:127]
	v_mfma_f32_16x16x32_bf16 v[120:123], v[162:165], v[170:173], v[120:123]
	v_mfma_f32_16x16x32_bf16 v[116:119], v[144:147], v[178:181], v[116:119]
	v_mfma_f32_16x16x32_bf16 v[108:111], v[162:165], v[178:181], v[108:111]
	v_mfma_f32_16x16x32_bf16 v[100:103], v[144:147], v[186:189], v[100:103]
	v_mfma_f32_16x16x32_bf16 v[92:95], v[162:165], v[186:189], v[92:95]
	v_mfma_f32_16x16x32_bf16 v[84:87], v[144:147], v[194:197], v[84:87]
	v_mfma_f32_16x16x32_bf16 v[76:79], v[162:165], v[194:197], v[76:79]
	v_mfma_f32_16x16x32_bf16 v[124:127], v[148:151], v[174:177], v[124:127]
	v_mfma_f32_16x16x32_bf16 v[120:123], v[166:169], v[174:177], v[120:123]
	v_mfma_f32_16x16x32_bf16 v[116:119], v[148:151], v[182:185], v[116:119]
	v_mfma_f32_16x16x32_bf16 v[108:111], v[166:169], v[182:185], v[108:111]
	v_mfma_f32_16x16x32_bf16 v[100:103], v[148:151], v[190:193], v[100:103]
	v_mfma_f32_16x16x32_bf16 v[92:95], v[166:169], v[190:193], v[92:95]
	v_mfma_f32_16x16x32_bf16 v[84:87], v[148:151], v[198:201], v[84:87]
	v_mfma_f32_16x16x32_bf16 v[76:79], v[166:169], v[198:201], v[76:79]
	v_mfma_f32_16x16x32_bf16 v[112:115], v[202:205], v[170:173], v[112:115]
	v_mfma_f32_16x16x32_bf16 v[104:107], v[210:213], v[170:173], v[104:107]
	v_mfma_f32_16x16x32_bf16 v[96:99], v[202:205], v[178:181], v[96:99]
	v_mfma_f32_16x16x32_bf16 v[88:91], v[210:213], v[178:181], v[88:91]
	v_mfma_f32_16x16x32_bf16 v[80:83], v[202:205], v[186:189], v[80:83]
	v_mfma_f32_16x16x32_bf16 v[72:75], v[210:213], v[186:189], v[72:75]
	v_mfma_f32_16x16x32_bf16 v[68:71], v[202:205], v[194:197], v[68:71]
	v_mfma_f32_16x16x32_bf16 v[64:67], v[210:213], v[194:197], v[64:67]
	v_mfma_f32_16x16x32_bf16 v[112:115], v[206:209], v[174:177], v[112:115]
	v_mfma_f32_16x16x32_bf16 v[104:107], v[214:217], v[174:177], v[104:107]
	v_mfma_f32_16x16x32_bf16 v[96:99], v[206:209], v[182:185], v[96:99]
	v_mfma_f32_16x16x32_bf16 v[88:91], v[214:217], v[182:185], v[88:91]
	v_mfma_f32_16x16x32_bf16 v[80:83], v[206:209], v[190:193], v[80:83]
	v_mfma_f32_16x16x32_bf16 v[72:75], v[214:217], v[190:193], v[72:75]
	v_mfma_f32_16x16x32_bf16 v[68:71], v[206:209], v[198:201], v[68:71]
	v_mfma_f32_16x16x32_bf16 v[64:67], v[214:217], v[198:201], v[64:67]
	s_setprio 0
	s_barrier
; #define PG8_STAGE(bufoff, gbase, voff) do { _Pragma("unroll") for (int _i = 0; _i < 2; ++_i) \
;         __builtin_amdgcn_global_load_lds((const unsigned*)((const char*)(gbase) + (voff)[_i]), (LAS unsigned*)(lds + (bufoff) + ldsw + _i * 8192), 16, 0, 0); } while (0)
; #define PG8_LDA(dst, b, h) do { _Pragma("unroll") for (int m = 0; m < 4; ++m) _Pragma("unroll") for (int k = 0; k < 2; ++k) dst[m][k] = *(const LAS bf16x8*)(lds + PG8_SA(b, h) + aoff + m * 2048 + k * 1024); } while (0)
; #define PG8_LDB(dst, b, h) do { _Pragma("unroll") for (int n = 0; n < 2; ++n) _Pragma("unroll") for (int k = 0; k < 2; ++k) dst[n][k] = *(const LAS bf16x8*)(lds + PG8_SB(b, h) + boff + n * 2048 + k * 1024); } while (0)
; #define PG8_MMA(ai, bj, At, Bt) do { __builtin_amdgcn_s_setprio(1); _Pragma("unroll") for (int m = 0; m < 4; ++m) _Pragma("unroll") for (int n = 0; n < 2; ++n) _Pragma("unroll") for (int k = 0; k < 2; ++k) \
;         acc[ai][bj][m][n] = __builtin_amdgcn_mfma_f32_16x16x32_bf16(Bt[n][k], At[m][k], acc[ai][bj][m][n], 0, 0, 0); __builtin_amdgcn_s_setprio(0); } while (0)
; #define PG8_WAIT_V(n) asm volatile("s_waitcnt vmcnt(" #n ")" ::: "memory")
; #define PG8_WAIT_L(n) asm volatile("s_waitcnt lgkmcnt(" #n ")" ::: "memory")
; #define PG8_BAR __builtin_amdgcn_s_barrier()
; #define PG8_SCHED __builtin_amdgcn_sched_barrier(0)
; template <class Epi>
; __device__ __forceinline__ void gemm_phase(LAS unsigned char* lds, const Gemm g, const StaticOrder& S, const Epi& E) {
;     ...
;             PG8_LDB(B1, 1, 1); PG8_STAGE(PG8_SB(1, 0), b3, voffB);
;             PG8_BAR; PG8_WAIT_L(0); PG8_MMA(0, 1, At, B1); PG8_BAR;
;             PG8_LDA(At, 1, 1); PG8_STAGE(PG8_SA(1, 0), a3, voffA);
;             PG8_BAR; PG8_WAIT_L(0); PG8_MMA(1, 0, At, B0); PG8_BAR; PG8_SCHED;
;             PG8_STAGE(PG8_SB(1, 1), b3 + hstepB, voffB);
;             PG8_WAIT_V(6); PG8_BAR; PG8_MMA(1, 1, At, B1); PG8_BAR;
;         }
	s_add_i32 s59, s59, s33
	v_lshl_add_u64 v[152:153], v[152:153], 0, s[12:13]
	s_mov_b32 m0, s59
	global_load_lds_dwordx4 v[152:153], off
	v_lshl_add_u64 v[152:153], v[218:219], 0, s[12:13]
	s_add_i32 m0, s59, 0x2000
	s_nop 0
	global_load_lds_dwordx4 v[152:153], off
	s_mov_b32 m0, s73
	v_lshl_add_u64 v[152:153], v[220:221], 0, s[12:13]
	ds_read_b128 v[170:173], v159 offset:49152
	ds_read_b128 v[174:177], v159 offset:50176
	ds_read_b128 v[178:181], v159 offset:51200
	ds_read_b128 v[182:185], v159 offset:52224
	ds_read_b128 v[186:189], v159 offset:53248
	ds_read_b128 v[190:193], v159 offset:54272
	ds_read_b128 v[194:197], v159 offset:55296
	ds_read_b128 v[198:201], v159 offset:56320
	global_load_lds_dwordx4 v[152:153], off
	v_lshl_add_u64 v[152:153], v[222:223], 0, s[12:13]
	s_mov_b32 m0, s74
	s_nop 0
	global_load_lds_dwordx4 v[152:153], off
	s_add_u32 s66, s66, 0x40080
	s_addc_u32 s67, s67, 0
	s_add_i32 s59, s68, s33
	v_lshl_add_u64 v[240:241], s[66:67], 0, v[132:133]
	s_mov_b32 m0, s59
	s_nop 0
	global_load_lds_dwordx4 v[240:241], off
	v_lshl_add_u64 v[240:241], s[66:67], 0, v[136:137]
	s_add_i32 m0, s59, 0x2000
	s_nop 0
	global_load_lds_dwordx4 v[240:241], off
	s_waitcnt vmcnt(8) lgkmcnt(0)
	s_barrier
	s_setprio 1
	v_mfma_f32_16x16x32_bf16 v[60:63], v[144:147], v[170:173], v[60:63]
	v_mfma_f32_16x16x32_bf16 v[56:59], v[162:165], v[170:173], v[56:59]
	v_mfma_f32_16x16x32_bf16 v[52:55], v[144:147], v[178:181], v[52:55]
	v_mfma_f32_16x16x32_bf16 v[44:47], v[162:165], v[178:181], v[44:47]
	v_mfma_f32_16x16x32_bf16 v[36:39], v[144:147], v[186:189], v[36:39]
	v_mfma_f32_16x16x32_bf16 v[28:31], v[162:165], v[186:189], v[28:31]
	v_mfma_f32_16x16x32_bf16 v[20:23], v[144:147], v[194:197], v[20:23]
	v_mfma_f32_16x16x32_bf16 v[12:15], v[162:165], v[194:197], v[12:15]
	v_mfma_f32_16x16x32_bf16 v[60:63], v[148:151], v[174:177], v[60:63]
	v_mfma_f32_16x16x32_bf16 v[56:59], v[166:169], v[174:177], v[56:59]
	v_mfma_f32_16x16x32_bf16 v[52:55], v[148:151], v[182:185], v[52:55]
	v_mfma_f32_16x16x32_bf16 v[44:47], v[166:169], v[182:185], v[44:47]
	v_mfma_f32_16x16x32_bf16 v[36:39], v[148:151], v[190:193], v[36:39]
	v_mfma_f32_16x16x32_bf16 v[28:31], v[166:169], v[190:193], v[28:31]
	v_mfma_f32_16x16x32_bf16 v[20:23], v[148:151], v[198:201], v[20:23]
	v_mfma_f32_16x16x32_bf16 v[12:15], v[166:169], v[198:201], v[12:15]
	v_mfma_f32_16x16x32_bf16 v[48:51], v[202:205], v[170:173], v[48:51]
	v_mfma_f32_16x16x32_bf16 v[40:43], v[210:213], v[170:173], v[40:43]
	v_mfma_f32_16x16x32_bf16 v[32:35], v[202:205], v[178:181], v[32:35]
	v_mfma_f32_16x16x32_bf16 v[24:27], v[210:213], v[178:181], v[24:27]
	v_mfma_f32_16x16x32_bf16 v[16:19], v[202:205], v[186:189], v[16:19]
	v_mfma_f32_16x16x32_bf16 v[8:11], v[210:213], v[186:189], v[8:11]
	v_mfma_f32_16x16x32_bf16 v[4:7], v[202:205], v[194:197], v[4:7]
	v_mfma_f32_16x16x32_bf16 v[0:3], v[210:213], v[194:197], v[0:3]
	v_mfma_f32_16x16x32_bf16 v[48:51], v[206:209], v[174:177], v[48:51]
	v_mfma_f32_16x16x32_bf16 v[40:43], v[214:217], v[174:177], v[40:43]
	v_mfma_f32_16x16x32_bf16 v[32:35], v[206:209], v[182:185], v[32:35]
	v_mfma_f32_16x16x32_bf16 v[24:27], v[214:217], v[182:185], v[24:27]
	v_mfma_f32_16x16x32_bf16 v[16:19], v[206:209], v[190:193], v[16:19]
	v_mfma_f32_16x16x32_bf16 v[8:11], v[214:217], v[190:193], v[8:11]
	v_mfma_f32_16x16x32_bf16 v[4:7], v[206:209], v[198:201], v[4:7]
	v_mfma_f32_16x16x32_bf16 v[0:3], v[214:217], v[198:201], v[0:3]
	s_setprio 0
	s_add_u32 s64, s64, 0x100
	s_addc_u32 s65, s65, 0
	s_add_u32 s31, s31, 0x100
	s_addc_u32 s57, s57, 0
	s_cmp_ge_i32 s85, s84
	s_mov_b32 s59, s85
	s_barrier
	s_cbranch_scc0 .LBB0_456
;     __device__ __forceinline__ void operator()(const f32x4 (&acc)[2][2][4][2], const Unit& u, int wr, int wc, int fr, int fq) const {
;     ...
;         if (u.part) {
;             float* base = tailacc + (size_t)(u.part - 1) * slab - (size_t)tail_row0 * tail_ld;
; #pragma unroll
;             for (int ai = 0; ai < 2; ++ai)
; #pragma unroll
;                 for (int m = 0; m < 4; ++m) { float* rowp = base + (size_t)(row0 + ai * HALF + m * 16) * tail_ld + col0;
; #pragma unroll
;                     for (int bj = 0; bj < 2; ++bj)
; #pragma unroll
;                         for (int n = 0; n < 2; ++n) *(f32x4*)(rowp + bj * HALF + 4 * n) = acc[ai][bj][m][n]; }
;             return;
	v_lshl_add_u32 v152, s8, 8, v155
	v_lshl_or_b32 v144, s30, 8, v157
	v_or_b32_e32 v150, 16, v152
	v_or_b32_e32 v148, 32, v152
	v_or_b32_e32 v146, 48, v152
	s_cmp_lg_u32 s81, 0
	v_ashrrev_i32_e32 v145, 31, v144
	v_ashrrev_i32_e32 v153, 31, v152
	v_ashrrev_i32_e32 v151, 31, v150
	v_ashrrev_i32_e32 v149, 31, v148
	v_ashrrev_i32_e32 v147, 31, v146
	s_cbranch_scc0 .LBB0_459
	s_add_i32 s8, s81, -1
	s_lshl_b64 s[30:31], s[8:9], 21
	s_add_u32 s30, s4, s30
	s_addc_u32 s31, s5, s31
	v_lshl_add_u64 v[162:163], v[144:145], 2, s[30:31]
	s_brev_b32 s30, 63
	s_mov_b32 s31, -1
	v_lshl_add_u64 v[162:163], v[162:163], 0, s[30:31]
	v_lshlrev_b64 v[164:165], 12, v[152:153]
	v_lshlrev_b64 v[166:167], 12, v[150:151]
	v_lshl_add_u64 v[164:165], v[162:163], 0, v[164:165]
	v_lshl_add_u64 v[166:167], v[162:163], 0, v[166:167]
	global_store_dwordx4 v[164:165], v[124:127], off
	global_store_dwordx4 v[164:165], v[120:123], off offset:16
	global_store_dwordx4 v[164:165], v[112:115], off offset:512
	global_store_dwordx4 v[164:165], v[104:107], off offset:528
	global_store_dwordx4 v[166:167], v[116:119], off
	global_store_dwordx4 v[166:167], v[108:111], off offset:16
	global_store_dwordx4 v[166:167], v[96:99], off offset:512
	global_store_dwordx4 v[166:167], v[88:91], off offset:528
	v_lshlrev_b64 v[166:167], 12, v[148:149]
	v_lshl_add_u64 v[166:167], v[162:163], 0, v[166:167]
	global_store_dwordx4 v[166:167], v[100:103], off
	global_store_dwordx4 v[166:167], v[92:95], off offset:16
	global_store_dwordx4 v[166:167], v[80:83], off offset:512
	global_store_dwordx4 v[166:167], v[72:75], off offset:528
	v_lshlrev_b64 v[166:167], 12, v[146:147]
	s_mov_b32 s8, 0x80000
	v_lshl_add_u64 v[162:163], v[162:163], 0, v[166:167]
	v_add_co_u32_e32 v166, vcc, s8, v164
	s_mov_b64 s[30:31], 0x80000
	s_nop 0
	v_addc_co_u32_e32 v167, vcc, 0, v165, vcc
	s_mov_b32 s8, 0x90000
	global_store_dwordx4 v[162:163], v[84:87], off
	global_store_dwordx4 v[162:163], v[76:79], off offset:16
	global_store_dwordx4 v[162:163], v[68:71], off offset:512
	global_store_dwordx4 v[162:163], v[64:67], off offset:528
	v_lshl_add_u64 v[162:163], v[164:165], 0, s[30:31]
	global_store_dwordx4 v[166:167], v[60:63], off
	global_store_dwordx4 v[162:163], v[56:59], off offset:16
	global_store_dwordx4 v[162:163], v[48:51], off offset:512
	global_store_dwordx4 v[162:163], v[40:43], off offset:528
	v_add_co_u32_e32 v166, vcc, s8, v164
	s_mov_b64 s[30:31], 0x90000
	s_nop 0
	v_addc_co_u32_e32 v167, vcc, 0, v165, vcc
	s_mov_b32 s8, 0xa0000
	v_lshl_add_u64 v[162:163], v[164:165], 0, s[30:31]
	global_store_dwordx4 v[166:167], v[52:55], off
	global_store_dwordx4 v[162:163], v[44:47], off offset:16
	global_store_dwordx4 v[162:163], v[32:35], off offset:512
	global_store_dwordx4 v[162:163], v[24:27], off offset:528
	s_mov_b64 s[30:31], 0xa0000
	v_add_co_u32_e32 v166, vcc, s8, v164
	v_lshl_add_u64 v[162:163], v[164:165], 0, s[30:31]
	s_nop 0
	v_addc_co_u32_e32 v167, vcc, 0, v165, vcc
	s_mov_b64 s[30:31], 0xb0000
	global_store_dwordx4 v[166:167], v[36:39], off
	global_store_dwordx4 v[162:163], v[28:31], off offset:16
	global_store_dwordx4 v[162:163], v[16:19], off offset:512
	global_store_dwordx4 v[162:163], v[8:11], off offset:528
	v_lshl_add_u64 v[162:163], v[164:165], 0, s[30:31]
	v_add_co_u32_e32 v164, vcc, 0xb0000, v164
	s_nop 1
	v_addc_co_u32_e32 v165, vcc, 0, v165, vcc
	global_store_dwordx4 v[164:165], v[20:23], off
	global_store_dwordx4 v[162:163], v[12:15], off offset:16
	global_store_dwordx4 v[162:163], v[4:7], off offset:512
	global_store_dwordx4 v[162:163], v[0:3], off offset:528
	s_cbranch_execnz .LBB0_441
	s_branch .LBB0_440

; #define PG8_STAGE(bufoff, gbase, voff) do { _Pragma("unroll") for (int _i = 0; _i < 2; ++_i) \
;         __builtin_amdgcn_global_load_lds((const unsigned*)((const char*)(gbase) + (voff)[_i]), (LAS unsigned*)(lds + (bufoff) + ldsw + _i * 8192), 16, 0, 0); } while (0)
; #define PG8_LDA(dst, b, h) do { _Pragma("unroll") for (int m = 0; m < 4; ++m) _Pragma("unroll") for (int k = 0; k < 2; ++k) dst[m][k] = *(const LAS bf16x8*)(lds + PG8_SA(b, h) + aoff + m * 2048 + k * 1024); } while (0)
; #define PG8_LDB(dst, b, h) do { _Pragma("unroll") for (int n = 0; n < 2; ++n) _Pragma("unroll") for (int k = 0; k < 2; ++k) dst[n][k] = *(const LAS bf16x8*)(lds + PG8_SB(b, h) + boff + n * 2048 + k * 1024); } while (0)
; #define PG8_MMA(ai, bj, At, Bt) do { __builtin_amdgcn_s_setprio(1); _Pragma("unroll") for (int m = 0; m < 4; ++m) _Pragma("unroll") for (int n = 0; n < 2; ++n) _Pragma("unroll") for (int k = 0; k < 2; ++k) \
;         acc[ai][bj][m][n] = __builtin_amdgcn_mfma_f32_16x16x32_bf16(Bt[n][k], At[m][k], acc[ai][bj][m][n], 0, 0, 0); __builtin_amdgcn_s_setprio(0); } while (0)
; #define PG8_WAIT_V(n) asm volatile("s_waitcnt vmcnt(" #n ")" ::: "memory")
; #define PG8_WAIT_L(n) asm volatile("s_waitcnt lgkmcnt(" #n ")" ::: "memory")
; template <class Epi>
; __device__ __forceinline__ void gemm_phase(LAS unsigned char* lds, const Gemm g, const StaticOrder& S, const Epi& E) {
;     ...
;         for (int t = 0; t < nt; t += 2) {
;             const bool last = (t == nt - 2);
;             const char* a1 = cA + (size_t)(t + 1) * kstep;
;             const char* a2 = last ? nA : cA + (size_t)(t + 2) * kstep; const char* b2 = last ? nB : cB + (size_t)(t + 2) * kstep;
;             const char* a3 = a2 + kstep; const char* b3 = b2 + kstep;
;             PG8_LDB(B0, 0, 0); PG8_SCHED; PG8_LDA(At, 0, 0); PG8_STAGE(PG8_SA(1, 1), a1 + hstepA, voffA);
;             PG8_WAIT_L(8); PG8_BAR; PG8_WAIT_L(0); PG8_MMA(0, 0, At, B0); PG8_BAR; PG8_SCHED;
;             PG8_LDB(B1, 0, 1); PG8_STAGE(PG8_SB(0, 0), b2, voffB);
;             PG8_BAR; PG8_WAIT_L(0); PG8_MMA(0, 1, At, B1); PG8_BAR;
;             PG8_LDA(At, 0, 1); PG8_STAGE(PG8_SA(0, 0), a2, voffA);
;             PG8_BAR; PG8_WAIT_L(0); PG8_MMA(1, 0, At, B0); PG8_BAR; PG8_SCHED;
;             PG8_STAGE(PG8_SB(0, 1), b2 + hstepB, voffB);
;             PG8_WAIT_V(6); PG8_BAR; PG8_MMA(1, 1, At, B1); PG8_BAR;
.LBB0_682:
	ds_read_b128 v[152:155], v159
	ds_read_b128 v[162:165], v159 offset:1024
	ds_read_b128 v[166:169], v159 offset:2048
	ds_read_b128 v[170:173], v159 offset:3072
	s_add_u32 s62, s60, 0xfffc0080
	s_addc_u32 s63, s61, -1
	s_cmp_eq_u32 s78, 12
	s_cselect_b32 s65, s41, s63
	s_cselect_b32 s64, s40, s62
	s_cselect_b32 s63, s57, s39
	s_cselect_b32 s62, s56, s37
	v_lshl_add_u64 v[206:207], s[60:61], 0, v[144:145]
	s_add_i32 m0, s35, 0xc000
	ds_read_b128 v[174:177], v160
	ds_read_b128 v[178:181], v160 offset:1024
	ds_read_b128 v[182:185], v160 offset:2048
	ds_read_b128 v[186:189], v160 offset:3072
	ds_read_b128 v[190:193], v160 offset:4096
	ds_read_b128 v[194:197], v160 offset:5120
	ds_read_b128 v[198:201], v160 offset:6144
	ds_read_b128 v[202:205], v160 offset:7168
	global_load_lds_dwordx4 v[206:207], off
	v_lshl_add_u64 v[206:207], s[60:61], 0, v[146:147]
	s_add_i32 m0, s35, 0xe000
	s_nop 0
	global_load_lds_dwordx4 v[206:207], off
	ds_read_b128 v[206:209], v161
	ds_read_b128 v[210:213], v161 offset:1024
	ds_read_b128 v[214:217], v161 offset:2048
	ds_read_b128 v[218:221], v161 offset:3072
	s_waitcnt vmcnt(8) lgkmcnt(0)
	s_barrier
	s_setprio 1
	v_mfma_f32_16x16x32_bf16 v[124:127], v[152:155], v[174:177], v[124:127]
	v_mfma_f32_16x16x32_bf16 v[120:123], v[166:169], v[174:177], v[120:123]
	v_mfma_f32_16x16x32_bf16 v[116:119], v[152:155], v[182:185], v[116:119]
	v_mfma_f32_16x16x32_bf16 v[108:111], v[166:169], v[182:185], v[108:111]
	v_mfma_f32_16x16x32_bf16 v[100:103], v[152:155], v[190:193], v[100:103]
	v_mfma_f32_16x16x32_bf16 v[92:95], v[166:169], v[190:193], v[92:95]
	v_mfma_f32_16x16x32_bf16 v[84:87], v[152:155], v[198:201], v[84:87]
	v_mfma_f32_16x16x32_bf16 v[76:79], v[166:169], v[198:201], v[76:79]
	v_mfma_f32_16x16x32_bf16 v[124:127], v[162:165], v[178:181], v[124:127]
	v_mfma_f32_16x16x32_bf16 v[120:123], v[170:173], v[178:181], v[120:123]
	v_mfma_f32_16x16x32_bf16 v[116:119], v[162:165], v[186:189], v[116:119]
	v_mfma_f32_16x16x32_bf16 v[108:111], v[170:173], v[186:189], v[108:111]
	v_mfma_f32_16x16x32_bf16 v[100:103], v[162:165], v[194:197], v[100:103]
	v_mfma_f32_16x16x32_bf16 v[92:95], v[170:173], v[194:197], v[92:95]
	v_mfma_f32_16x16x32_bf16 v[84:87], v[162:165], v[202:205], v[84:87]
	v_mfma_f32_16x16x32_bf16 v[76:79], v[170:173], v[202:205], v[76:79]
	v_mfma_f32_16x16x32_bf16 v[112:115], v[206:209], v[174:177], v[112:115]
	v_mfma_f32_16x16x32_bf16 v[104:107], v[214:217], v[174:177], v[104:107]
	v_mfma_f32_16x16x32_bf16 v[96:99], v[206:209], v[182:185], v[96:99]
	v_mfma_f32_16x16x32_bf16 v[88:91], v[214:217], v[182:185], v[88:91]
	v_mfma_f32_16x16x32_bf16 v[80:83], v[206:209], v[190:193], v[80:83]
	v_mfma_f32_16x16x32_bf16 v[72:75], v[214:217], v[190:193], v[72:75]
	v_mfma_f32_16x16x32_bf16 v[68:71], v[206:209], v[198:201], v[68:71]
	v_mfma_f32_16x16x32_bf16 v[64:67], v[214:217], v[198:201], v[64:67]
	v_mfma_f32_16x16x32_bf16 v[112:115], v[210:213], v[178:181], v[112:115]
	v_mfma_f32_16x16x32_bf16 v[104:107], v[218:221], v[178:181], v[104:107]
	v_mfma_f32_16x16x32_bf16 v[96:99], v[210:213], v[186:189], v[96:99]
	v_mfma_f32_16x16x32_bf16 v[88:91], v[218:221], v[186:189], v[88:91]
	v_mfma_f32_16x16x32_bf16 v[80:83], v[210:213], v[194:197], v[80:83]
	v_mfma_f32_16x16x32_bf16 v[72:75], v[218:221], v[194:197], v[72:75]
	v_mfma_f32_16x16x32_bf16 v[68:71], v[210:213], v[202:205], v[68:71]
	v_mfma_f32_16x16x32_bf16 v[64:67], v[218:221], v[202:205], v[64:67]
	s_setprio 0
	s_barrier
	s_add_i32 s79, s75, s33
	v_lshl_add_u64 v[222:223], s[62:63], 0, v[138:139]
	s_mov_b32 m0, s79
	global_load_lds_dwordx4 v[222:223], off
	v_lshl_add_u64 v[224:225], s[62:63], 0, v[142:143]
	s_add_i32 m0, s79, 0x2000
	s_nop 0
	global_load_lds_dwordx4 v[224:225], off
	s_mov_b32 m0, s35
	v_lshl_add_u64 v[226:227], s[64:65], 0, v[136:137]
	ds_read_b128 v[174:177], v160 offset:16384
	ds_read_b128 v[178:181], v160 offset:17408
	ds_read_b128 v[182:185], v160 offset:18432
	ds_read_b128 v[186:189], v160 offset:19456
	ds_read_b128 v[190:193], v160 offset:20480
	ds_read_b128 v[194:197], v160 offset:21504
	ds_read_b128 v[198:201], v160 offset:22528
	ds_read_b128 v[202:205], v160 offset:23552
	global_load_lds_dwordx4 v[226:227], off
	v_lshl_add_u64 v[228:229], s[64:65], 0, v[140:141]
	s_mov_b32 m0, s66
	s_nop 0
	global_load_lds_dwordx4 v[228:229], off
	s_add_u32 s80, s62, 0x40000
	s_addc_u32 s81, s63, 0
	s_add_i32 s79, s76, s33
	v_lshl_add_u64 v[240:241], s[80:81], 0, v[138:139]
	s_mov_b32 m0, s79
	s_nop 0
	global_load_lds_dwordx4 v[240:241], off
	v_lshl_add_u64 v[240:241], s[80:81], 0, v[142:143]
	s_add_i32 m0, s79, 0x2000
	s_nop 0
	global_load_lds_dwordx4 v[240:241], off
	s_waitcnt vmcnt(8) lgkmcnt(0)
	s_barrier
; #define PG8_STAGE(bufoff, gbase, voff) do { _Pragma("unroll") for (int _i = 0; _i < 2; ++_i) \
;         __builtin_amdgcn_global_load_lds((const unsigned*)((const char*)(gbase) + (voff)[_i]), (LAS unsigned*)(lds + (bufoff) + ldsw + _i * 8192), 16, 0, 0); } while (0)
; #define PG8_LDA(dst, b, h) do { _Pragma("unroll") for (int m = 0; m < 4; ++m) _Pragma("unroll") for (int k = 0; k < 2; ++k) dst[m][k] = *(const LAS bf16x8*)(lds + PG8_SA(b, h) + aoff + m * 2048 + k * 1024); } while (0)
; #define PG8_LDB(dst, b, h) do { _Pragma("unroll") for (int n = 0; n < 2; ++n) _Pragma("unroll") for (int k = 0; k < 2; ++k) dst[n][k] = *(const LAS bf16x8*)(lds + PG8_SB(b, h) + boff + n * 2048 + k * 1024); } while (0)
; #define PG8_MMA(ai, bj, At, Bt) do { __builtin_amdgcn_s_setprio(1); _Pragma("unroll") for (int m = 0; m < 4; ++m) _Pragma("unroll") for (int n = 0; n < 2; ++n) _Pragma("unroll") for (int k = 0; k < 2; ++k) \
;         acc[ai][bj][m][n] = __builtin_amdgcn_mfma_f32_16x16x32_bf16(Bt[n][k], At[m][k], acc[ai][bj][m][n], 0, 0, 0); __builtin_amdgcn_s_setprio(0); } while (0)
; #define PG8_WAIT_V(n) asm volatile("s_waitcnt vmcnt(" #n ")" ::: "memory")
; #define PG8_WAIT_L(n) asm volatile("s_waitcnt lgkmcnt(" #n ")" ::: "memory")
; #define PG8_BAR __builtin_amdgcn_s_barrier()
; #define PG8_SCHED __builtin_amdgcn_sched_barrier(0)
; template <class Epi>
; __device__ __forceinline__ void gemm_phase(LAS unsigned char* lds, const Gemm g, const StaticOrder& S, const Epi& E) {
;     ...
;             PG8_LDA(At, 0, 1); PG8_STAGE(PG8_SA(0, 0), a2, voffA);
;             PG8_BAR; PG8_WAIT_L(0); PG8_MMA(1, 0, At, B0); PG8_BAR; PG8_SCHED;
;             PG8_STAGE(PG8_SB(0, 1), b2 + hstepB, voffB);
;             PG8_WAIT_V(6); PG8_BAR; PG8_MMA(1, 1, At, B1); PG8_BAR;
;             PG8_LDB(B0, 1, 0); PG8_SCHED; PG8_LDA(At, 1, 0); PG8_STAGE(PG8_SA(0, 1), a2 + hstepA, voffA);
;             PG8_WAIT_L(8); PG8_BAR; PG8_WAIT_L(0); PG8_MMA(0, 0, At, B0); PG8_BAR; PG8_SCHED;
;             PG8_LDB(B1, 1, 1); PG8_STAGE(PG8_SB(1, 0), b3, voffB);
;             PG8_BAR; PG8_WAIT_L(0); PG8_MMA(0, 1, At, B1); PG8_BAR;
	s_setprio 1
	v_mfma_f32_16x16x32_bf16 v[60:63], v[152:155], v[174:177], v[60:63]
	v_mfma_f32_16x16x32_bf16 v[56:59], v[166:169], v[174:177], v[56:59]
	v_mfma_f32_16x16x32_bf16 v[52:55], v[152:155], v[182:185], v[52:55]
	v_mfma_f32_16x16x32_bf16 v[44:47], v[166:169], v[182:185], v[44:47]
	v_mfma_f32_16x16x32_bf16 v[36:39], v[152:155], v[190:193], v[36:39]
	v_mfma_f32_16x16x32_bf16 v[28:31], v[166:169], v[190:193], v[28:31]
	v_mfma_f32_16x16x32_bf16 v[20:23], v[152:155], v[198:201], v[20:23]
	v_mfma_f32_16x16x32_bf16 v[12:15], v[166:169], v[198:201], v[12:15]
	v_mfma_f32_16x16x32_bf16 v[60:63], v[162:165], v[178:181], v[60:63]
	v_mfma_f32_16x16x32_bf16 v[56:59], v[170:173], v[178:181], v[56:59]
	v_mfma_f32_16x16x32_bf16 v[52:55], v[162:165], v[186:189], v[52:55]
	v_mfma_f32_16x16x32_bf16 v[44:47], v[170:173], v[186:189], v[44:47]
	v_mfma_f32_16x16x32_bf16 v[36:39], v[162:165], v[194:197], v[36:39]
	v_mfma_f32_16x16x32_bf16 v[28:31], v[170:173], v[194:197], v[28:31]
	v_mfma_f32_16x16x32_bf16 v[20:23], v[162:165], v[202:205], v[20:23]
	v_mfma_f32_16x16x32_bf16 v[12:15], v[170:173], v[202:205], v[12:15]
	v_mfma_f32_16x16x32_bf16 v[48:51], v[206:209], v[174:177], v[48:51]
	v_mfma_f32_16x16x32_bf16 v[40:43], v[214:217], v[174:177], v[40:43]
	v_mfma_f32_16x16x32_bf16 v[32:35], v[206:209], v[182:185], v[32:35]
	v_mfma_f32_16x16x32_bf16 v[24:27], v[214:217], v[182:185], v[24:27]
	v_mfma_f32_16x16x32_bf16 v[16:19], v[206:209], v[190:193], v[16:19]
	v_mfma_f32_16x16x32_bf16 v[8:11], v[214:217], v[190:193], v[8:11]
	v_mfma_f32_16x16x32_bf16 v[4:7], v[206:209], v[198:201], v[4:7]
	v_mfma_f32_16x16x32_bf16 v[0:3], v[214:217], v[198:201], v[0:3]
	v_mfma_f32_16x16x32_bf16 v[48:51], v[210:213], v[178:181], v[48:51]
	v_mfma_f32_16x16x32_bf16 v[40:43], v[218:221], v[178:181], v[40:43]
	v_mfma_f32_16x16x32_bf16 v[32:35], v[210:213], v[186:189], v[32:35]
	v_mfma_f32_16x16x32_bf16 v[24:27], v[218:221], v[186:189], v[24:27]
	v_mfma_f32_16x16x32_bf16 v[16:19], v[210:213], v[194:197], v[16:19]
	v_mfma_f32_16x16x32_bf16 v[8:11], v[218:221], v[194:197], v[8:11]
	v_mfma_f32_16x16x32_bf16 v[4:7], v[210:213], v[202:205], v[4:7]
	v_mfma_f32_16x16x32_bf16 v[0:3], v[218:221], v[202:205], v[0:3]
	s_setprio 0
	s_barrier
	s_add_i32 s79, 0, 0x18000
	v_add_u32_e32 v170, s79, v156
	ds_read_b128 v[152:155], v170
	ds_read_b128 v[162:165], v170 offset:1024
	ds_read_b128 v[166:169], v170 offset:2048
	ds_read_b128 v[170:173], v170 offset:3072
	s_add_u32 s64, s64, 0x40000
	s_addc_u32 s65, s65, 0
	s_mov_b32 m0, s67
	v_lshl_add_u64 v[206:207], s[64:65], 0, v[136:137]
	ds_read_b128 v[174:177], v160 offset:32768
	ds_read_b128 v[178:181], v160 offset:33792
	ds_read_b128 v[182:185], v160 offset:34816
	ds_read_b128 v[186:189], v160 offset:35840
	ds_read_b128 v[190:193], v160 offset:36864
	ds_read_b128 v[194:197], v160 offset:37888
	ds_read_b128 v[198:201], v160 offset:38912
	ds_read_b128 v[202:205], v160 offset:39936
	global_load_lds_dwordx4 v[206:207], off
	v_lshl_add_u64 v[206:207], s[64:65], 0, v[140:141]
	s_mov_b32 m0, s68
	s_nop 0
	global_load_lds_dwordx4 v[206:207], off
	s_add_i32 s64, 0, 0x1c000
	v_add_u32_e32 v218, s64, v156
	ds_read_b128 v[206:209], v218
	ds_read_b128 v[210:213], v218 offset:1024
	ds_read_b128 v[214:217], v218 offset:2048
	ds_read_b128 v[218:221], v218 offset:3072
	s_waitcnt vmcnt(8) lgkmcnt(0)
	s_barrier
	s_setprio 1
	v_mfma_f32_16x16x32_bf16 v[124:127], v[152:155], v[174:177], v[124:127]
	v_mfma_f32_16x16x32_bf16 v[120:123], v[166:169], v[174:177], v[120:123]
	v_mfma_f32_16x16x32_bf16 v[116:119], v[152:155], v[182:185], v[116:119]
	v_mfma_f32_16x16x32_bf16 v[108:111], v[166:169], v[182:185], v[108:111]
	v_mfma_f32_16x16x32_bf16 v[100:103], v[152:155], v[190:193], v[100:103]
	v_mfma_f32_16x16x32_bf16 v[92:95], v[166:169], v[190:193], v[92:95]
	v_mfma_f32_16x16x32_bf16 v[84:87], v[152:155], v[198:201], v[84:87]
	v_mfma_f32_16x16x32_bf16 v[76:79], v[166:169], v[198:201], v[76:79]
	v_mfma_f32_16x16x32_bf16 v[124:127], v[162:165], v[178:181], v[124:127]
	v_mfma_f32_16x16x32_bf16 v[120:123], v[170:173], v[178:181], v[120:123]
	v_mfma_f32_16x16x32_bf16 v[116:119], v[162:165], v[186:189], v[116:119]
	v_mfma_f32_16x16x32_bf16 v[108:111], v[170:173], v[186:189], v[108:111]
	v_mfma_f32_16x16x32_bf16 v[100:103], v[162:165], v[194:197], v[100:103]
	v_mfma_f32_16x16x32_bf16 v[92:95], v[170:173], v[194:197], v[92:95]
	v_mfma_f32_16x16x32_bf16 v[84:87], v[162:165], v[202:205], v[84:87]
	v_mfma_f32_16x16x32_bf16 v[76:79], v[170:173], v[202:205], v[76:79]
	v_mfma_f32_16x16x32_bf16 v[112:115], v[206:209], v[174:177], v[112:115]
	v_mfma_f32_16x16x32_bf16 v[104:107], v[214:217], v[174:177], v[104:107]
	v_mfma_f32_16x16x32_bf16 v[96:99], v[206:209], v[182:185], v[96:99]
	v_mfma_f32_16x16x32_bf16 v[88:91], v[214:217], v[182:185], v[88:91]
	v_mfma_f32_16x16x32_bf16 v[80:83], v[206:209], v[190:193], v[80:83]
	v_mfma_f32_16x16x32_bf16 v[72:75], v[214:217], v[190:193], v[72:75]
	v_mfma_f32_16x16x32_bf16 v[68:71], v[206:209], v[198:201], v[68:71]
	v_mfma_f32_16x16x32_bf16 v[64:67], v[214:217], v[198:201], v[64:67]
	v_mfma_f32_16x16x32_bf16 v[112:115], v[210:213], v[178:181], v[112:115]
	v_mfma_f32_16x16x32_bf16 v[104:107], v[218:221], v[178:181], v[104:107]
	v_mfma_f32_16x16x32_bf16 v[96:99], v[210:213], v[186:189], v[96:99]
	v_mfma_f32_16x16x32_bf16 v[88:91], v[218:221], v[186:189], v[88:91]
	v_mfma_f32_16x16x32_bf16 v[80:83], v[210:213], v[194:197], v[80:83]
	v_mfma_f32_16x16x32_bf16 v[72:75], v[218:221], v[194:197], v[72:75]
	v_mfma_f32_16x16x32_bf16 v[68:71], v[210:213], v[202:205], v[68:71]
	v_mfma_f32_16x16x32_bf16 v[64:67], v[218:221], v[202:205], v[64:67]
	s_setprio 0
	s_barrier
; __device__ __forceinline__ unsigned pk2(float lo, float hi) { unsigned r; asm("v_cvt_pk_bf16_f32 %0, %1, %2" : "=v"(r) : "v"(lo), "v"(hi)); return r; }
; __device__ __forceinline__ float gelu_t(float x) { return x * __builtin_amdgcn_rcpf(1.f + __expf(-1.5957691216057308f * (x + 0.044715f * x * x * x))); }
; #define PG8_STAGE(bufoff, gbase, voff) do { _Pragma("unroll") for (int _i = 0; _i < 2; ++_i) \
;         __builtin_amdgcn_global_load_lds((const unsigned*)((const char*)(gbase) + (voff)[_i]), (LAS unsigned*)(lds + (bufoff) + ldsw + _i * 8192), 16, 0, 0); } while (0)
; #define PG8_LDA(dst, b, h) do { _Pragma("unroll") for (int m = 0; m < 4; ++m) _Pragma("unroll") for (int k = 0; k < 2; ++k) dst[m][k] = *(const LAS bf16x8*)(lds + PG8_SA(b, h) + aoff + m * 2048 + k * 1024); } while (0)
;     __device__ __forceinline__ void operator()(const f32x4 (&acc)[2][2][4][2], const Unit& u, int wr, int wc, int fr, int fq) const {
;     ...
; #pragma unroll
;         for (int ai = 0; ai < 2; ++ai)
; #pragma unroll
;             for (int m = 0; m < 4; ++m) { const int row = row0 + ai * HALF + m * 16; u16* rowp = O + (size_t)row * ldc + col0;
; #pragma unroll
;                 for (int bj = 0; bj < 2; ++bj) { f32x4 v0 = acc[ai][bj][m][0], v1 = acc[ai][bj][m][1];
;                     if (col0 + bj * HALF >= gelu_from) { v0 = (f32x4){gelu_t(v0.x), gelu_t(v0.y), gelu_t(v0.z), gelu_t(v0.w)}; v1 = (f32x4){gelu_t(v1.x), gelu_t(v1.y), gelu_t(v1.z), gelu_t(v1.w)}; }
;                     u32x4 w; w.x = pk2(v0[0], v0[1]); w.y = pk2(v0[2], v0[3]); w.z = pk2(v1[0], v1[1]); w.w = pk2(v1[2], v1[3]);
;                     *(u32x4*)(rowp + bj * HALF) = w;
;                     if (halo != nullptr && m == 3 && fr >= 14) *(u32x4*)(halo + (size_t)((row >> 6) * 2 + (fr - 14)) * ldc + col0 + bj * HALF) = w; } }
; template <class Epi>
; __device__ __forceinline__ void gemm_phase(LAS unsigned char* lds, const Gemm g, const StaticOrder& S, const Epi& E) {
;     ...
;             PG8_LDB(B1, 1, 1); PG8_STAGE(PG8_SB(1, 0), b3, voffB);
;             PG8_BAR; PG8_WAIT_L(0); PG8_MMA(0, 1, At, B1); PG8_BAR;
;             PG8_LDA(At, 1, 1); PG8_STAGE(PG8_SA(1, 0), a3, voffA);
;             PG8_BAR; PG8_WAIT_L(0); PG8_MMA(1, 0, At, B0); PG8_BAR; PG8_SCHED;
;             PG8_STAGE(PG8_SB(1, 1), b3 + hstepB, voffB);
;             PG8_WAIT_V(6); PG8_BAR; PG8_MMA(1, 1, At, B1); PG8_BAR;
;         }
	s_add_i32 s65, s79, s33
	v_lshl_add_u64 v[222:223], v[222:223], 0, s[28:29]
	s_mov_b32 m0, s65
	global_load_lds_dwordx4 v[222:223], off
	v_lshl_add_u64 v[222:223], v[224:225], 0, s[28:29]
	s_add_i32 m0, s65, 0x2000
	s_nop 0
	global_load_lds_dwordx4 v[222:223], off
	s_mov_b32 m0, s71
	v_lshl_add_u64 v[222:223], v[226:227], 0, s[28:29]
	ds_read_b128 v[174:177], v160 offset:49152
	ds_read_b128 v[178:181], v160 offset:50176
	ds_read_b128 v[182:185], v160 offset:51200
	ds_read_b128 v[186:189], v160 offset:52224
	ds_read_b128 v[190:193], v160 offset:53248
	ds_read_b128 v[194:197], v160 offset:54272
	ds_read_b128 v[198:201], v160 offset:55296
	ds_read_b128 v[202:205], v160 offset:56320
	global_load_lds_dwordx4 v[222:223], off
	v_lshl_add_u64 v[222:223], v[228:229], 0, s[28:29]
	s_mov_b32 m0, s72
	s_nop 0
	global_load_lds_dwordx4 v[222:223], off
	s_add_u32 s62, s62, 0x40080
	s_addc_u32 s63, s63, 0
	s_add_i32 s64, s64, s33
	v_lshl_add_u64 v[240:241], s[62:63], 0, v[138:139]
	s_mov_b32 m0, s64
	s_nop 0
	global_load_lds_dwordx4 v[240:241], off
	v_lshl_add_u64 v[240:241], s[62:63], 0, v[142:143]
	s_add_i32 m0, s64, 0x2000
	s_nop 0
	global_load_lds_dwordx4 v[240:241], off
	s_waitcnt vmcnt(8) lgkmcnt(0)
	s_barrier
	s_setprio 1
	v_mfma_f32_16x16x32_bf16 v[60:63], v[152:155], v[174:177], v[60:63]
	v_mfma_f32_16x16x32_bf16 v[56:59], v[166:169], v[174:177], v[56:59]
	v_mfma_f32_16x16x32_bf16 v[52:55], v[152:155], v[182:185], v[52:55]
	v_mfma_f32_16x16x32_bf16 v[44:47], v[166:169], v[182:185], v[44:47]
	v_mfma_f32_16x16x32_bf16 v[36:39], v[152:155], v[190:193], v[36:39]
	v_mfma_f32_16x16x32_bf16 v[28:31], v[166:169], v[190:193], v[28:31]
	v_mfma_f32_16x16x32_bf16 v[20:23], v[152:155], v[198:201], v[20:23]
	v_mfma_f32_16x16x32_bf16 v[12:15], v[166:169], v[198:201], v[12:15]
	v_mfma_f32_16x16x32_bf16 v[60:63], v[162:165], v[178:181], v[60:63]
	v_mfma_f32_16x16x32_bf16 v[56:59], v[170:173], v[178:181], v[56:59]
	v_mfma_f32_16x16x32_bf16 v[52:55], v[162:165], v[186:189], v[52:55]
	v_mfma_f32_16x16x32_bf16 v[44:47], v[170:173], v[186:189], v[44:47]
	v_mfma_f32_16x16x32_bf16 v[36:39], v[162:165], v[194:197], v[36:39]
	v_mfma_f32_16x16x32_bf16 v[28:31], v[170:173], v[194:197], v[28:31]
	v_mfma_f32_16x16x32_bf16 v[20:23], v[162:165], v[202:205], v[20:23]
	v_mfma_f32_16x16x32_bf16 v[12:15], v[170:173], v[202:205], v[12:15]
	v_mfma_f32_16x16x32_bf16 v[48:51], v[206:209], v[174:177], v[48:51]
	v_mfma_f32_16x16x32_bf16 v[40:43], v[214:217], v[174:177], v[40:43]
	v_mfma_f32_16x16x32_bf16 v[32:35], v[206:209], v[182:185], v[32:35]
	v_mfma_f32_16x16x32_bf16 v[24:27], v[214:217], v[182:185], v[24:27]
	v_mfma_f32_16x16x32_bf16 v[16:19], v[206:209], v[190:193], v[16:19]
	v_mfma_f32_16x16x32_bf16 v[8:11], v[214:217], v[190:193], v[8:11]
	v_mfma_f32_16x16x32_bf16 v[4:7], v[206:209], v[198:201], v[4:7]
	v_mfma_f32_16x16x32_bf16 v[0:3], v[214:217], v[198:201], v[0:3]
	v_mfma_f32_16x16x32_bf16 v[48:51], v[210:213], v[178:181], v[48:51]
	v_mfma_f32_16x16x32_bf16 v[40:43], v[218:221], v[178:181], v[40:43]
	v_mfma_f32_16x16x32_bf16 v[32:35], v[210:213], v[186:189], v[32:35]
	v_mfma_f32_16x16x32_bf16 v[24:27], v[218:221], v[186:189], v[24:27]
	v_mfma_f32_16x16x32_bf16 v[16:19], v[210:213], v[194:197], v[16:19]
	v_mfma_f32_16x16x32_bf16 v[8:11], v[218:221], v[194:197], v[8:11]
	v_mfma_f32_16x16x32_bf16 v[4:7], v[210:213], v[202:205], v[4:7]
	v_mfma_f32_16x16x32_bf16 v[0:3], v[218:221], v[202:205], v[0:3]
	s_setprio 0
	s_add_i32 s78, s78, 2
	s_add_u32 s60, s60, 0x100
	s_addc_u32 s61, s61, 0
	s_add_u32 s37, s37, 0x100
	s_addc_u32 s39, s39, 0
	s_cmp_gt_u32 s78, 13
	s_barrier
	s_cbranch_scc0 .LBB0_682
	s_lshl_b32 s37, s58, 8
	s_add_i32 s37, s37, s70
	v_lshl_or_b32 v152, s59, 8, v158
	v_or_b32_e32 v162, s37, v135
	v_ashrrev_i32_e32 v153, 31, v152
	v_mov_b64_e32 v[164:165], s[4:5]
	v_mad_i64_i32 v[166:167], s[58:59], v162, s77, v[164:165]
	v_lshlrev_b64 v[154:155], 1, v[152:153]
	v_cvt_pk_bf16_f32 v112, v112, v113
	v_cvt_pk_bf16_f32 v113, v114, v115
	v_cvt_pk_bf16_f32 v114, v104, v105
	v_or_b32_e32 v104, 16, v162
	v_lshl_add_u64 v[166:167], v[166:167], 0, v[154:155]
	v_mad_i64_i32 v[104:105], s[58:59], v104, s77, v[164:165]
	v_cvt_pk_bf16_f32 v96, v96, v97
	v_cvt_pk_bf16_f32 v97, v98, v99
	v_cvt_pk_bf16_f32 v98, v88, v89
	v_or_b32_e32 v88, 32, v162
	v_cvt_pk_bf16_f32 v115, v106, v107
	global_store_dwordx4 v[166:167], v[112:115], off offset:256
	v_mad_i64_i32 v[88:89], s[58:59], v88, s77, v[164:165]
	s_nop 0
	v_lshl_add_u64 v[112:113], v[104:105], 0, v[154:155]
	v_cvt_pk_bf16_f32 v80, v80, v81
	v_cvt_pk_bf16_f32 v81, v82, v83
	v_cvt_pk_bf16_f32 v82, v72, v73
	v_or_b32_e32 v72, 48, v162
	s_ashr_i32 s37, s37, 5
	v_cvt_pk_bf16_f32 v99, v90, v91
	global_store_dwordx4 v[112:113], v[96:99], off offset:256
	v_mad_i64_i32 v[72:73], s[58:59], v72, s77, v[164:165]
	s_nop 0
	v_lshl_add_u64 v[96:97], v[88:89], 0, v[154:155]
	v_add_u32_e32 v163, s37, v157
	v_cvt_pk_bf16_f32 v83, v74, v75
	global_store_dwordx4 v[96:97], v[80:83], off offset:256
	v_cvt_pk_bf16_f32 v124, v124, v125
	v_cvt_pk_bf16_f32 v125, v126, v127
	v_cvt_pk_bf16_f32 v126, v120, v121
	v_cvt_pk_bf16_f32 v127, v122, v123
	global_store_dwordx4 v[166:167], v[124:127], off
	s_nop 0
	v_lshl_add_u64 v[80:81], v[72:73], 0, v[154:155]
	v_cvt_pk_bf16_f32 v104, v116, v117
	v_cvt_pk_bf16_f32 v105, v118, v119
	v_cvt_pk_bf16_f32 v106, v108, v109
	v_cvt_pk_bf16_f32 v107, v110, v111
	global_store_dwordx4 v[112:113], v[104:107], off
	v_cvt_pk_bf16_f32 v88, v100, v101
	v_cvt_pk_bf16_f32 v89, v102, v103
	v_cvt_pk_bf16_f32 v90, v92, v93
	v_cvt_pk_bf16_f32 v91, v94, v95
	global_store_dwordx4 v[96:97], v[88:91], off
	v_cvt_pk_bf16_f32 v72, v84, v85
	v_cvt_pk_bf16_f32 v73, v86, v87
	v_cvt_pk_bf16_f32 v74, v76, v77
	v_cvt_pk_bf16_f32 v75, v78, v79
	global_store_dwordx4 v[80:81], v[72:75], off
	s_and_saveexec_b64 s[58:59], s[0:1]
	s_cbranch_execz .LBB0_685
	v_mov_b64_e32 v[76:77], s[18:19]
	v_mad_i64_i32 v[76:77], s[60:61], v163, s77, v[76:77]
	v_lshl_add_u64 v[76:77], v[152:153], 1, v[76:77]
	global_store_dwordx4 v[76:77], v[72:75], off

; #define PG8_STAGE(bufoff, gbase, voff) do { _Pragma("unroll") for (int _i = 0; _i < 2; ++_i) \
;         __builtin_amdgcn_global_load_lds((const unsigned*)((const char*)(gbase) + (voff)[_i]), (LAS unsigned*)(lds + (bufoff) + ldsw + _i * 8192), 16, 0, 0); } while (0)
; #define PG8_LDA(dst, b, h) do { _Pragma("unroll") for (int m = 0; m < 4; ++m) _Pragma("unroll") for (int k = 0; k < 2; ++k) dst[m][k] = *(const LAS bf16x8*)(lds + PG8_SA(b, h) + aoff + m * 2048 + k * 1024); } while (0)
; #define PG8_LDB(dst, b, h) do { _Pragma("unroll") for (int n = 0; n < 2; ++n) _Pragma("unroll") for (int k = 0; k < 2; ++k) dst[n][k] = *(const LAS bf16x8*)(lds + PG8_SB(b, h) + boff + n * 2048 + k * 1024); } while (0)
; #define PG8_MMA(ai, bj, At, Bt) do { __builtin_amdgcn_s_setprio(1); _Pragma("unroll") for (int m = 0; m < 4; ++m) _Pragma("unroll") for (int n = 0; n < 2; ++n) _Pragma("unroll") for (int k = 0; k < 2; ++k) \
;         acc[ai][bj][m][n] = __builtin_amdgcn_mfma_f32_16x16x32_bf16(Bt[n][k], At[m][k], acc[ai][bj][m][n], 0, 0, 0); __builtin_amdgcn_s_setprio(0); } while (0)
; #define PG8_WAIT_V(n) asm volatile("s_waitcnt vmcnt(" #n ")" ::: "memory")
; #define PG8_WAIT_L(n) asm volatile("s_waitcnt lgkmcnt(" #n ")" ::: "memory")
; template <class Epi>
; __device__ __forceinline__ void gemm_phase(LAS unsigned char* lds, const Gemm g, const StaticOrder& S, const Epi& E) {
;     ...
;         for (int t = 0; t < nt; t += 2) {
;             const bool last = (t == nt - 2);
;             const char* a1 = cA + (size_t)(t + 1) * kstep;
;             const char* a2 = last ? nA : cA + (size_t)(t + 2) * kstep; const char* b2 = last ? nB : cB + (size_t)(t + 2) * kstep;
;             const char* a3 = a2 + kstep; const char* b3 = b2 + kstep;
;             PG8_LDB(B0, 0, 0); PG8_SCHED; PG8_LDA(At, 0, 0); PG8_STAGE(PG8_SA(1, 1), a1 + hstepA, voffA);
;             PG8_WAIT_L(8); PG8_BAR; PG8_WAIT_L(0); PG8_MMA(0, 0, At, B0); PG8_BAR; PG8_SCHED;
;             PG8_LDB(B1, 0, 1); PG8_STAGE(PG8_SB(0, 0), b2, voffB);
;             PG8_BAR; PG8_WAIT_L(0); PG8_MMA(0, 1, At, B1); PG8_BAR;
;             PG8_LDA(At, 0, 1); PG8_STAGE(PG8_SA(0, 0), a2, voffA);
;             PG8_BAR; PG8_WAIT_L(0); PG8_MMA(1, 0, At, B0); PG8_BAR; PG8_SCHED;
;             PG8_STAGE(PG8_SB(0, 1), b2 + hstepB, voffB);
;             PG8_WAIT_V(6); PG8_BAR; PG8_MMA(1, 1, At, B1); PG8_BAR;
.LBB0_910:
	ds_read_b128 v[150:153], v170
	ds_read_b128 v[154:157], v170 offset:1024
	ds_read_b128 v[174:177], v170 offset:2048
	ds_read_b128 v[178:181], v170 offset:3072
	s_add_i32 s83, s54, 2
	s_add_u32 s55, s46, 0xffea0080
	s_addc_u32 s56, s47, -1
	s_cmp_eq_u32 s18, s54
	s_cselect_b32 s54, s0, s41
	s_cselect_b32 s57, s45, s56
	s_cselect_b32 s56, s44, s55
	s_cselect_b32 s55, s1, s82
	v_lshl_add_u64 v[158:159], s[46:47], 0, v[144:145]
	s_add_i32 m0, s33, 0xc000
	ds_read_b128 v[182:185], v171
	ds_read_b128 v[186:189], v171 offset:1024
	ds_read_b128 v[190:193], v171 offset:2048
	ds_read_b128 v[194:197], v171 offset:3072
	ds_read_b128 v[198:201], v171 offset:4096
	ds_read_b128 v[202:205], v171 offset:5120
	ds_read_b128 v[206:209], v171 offset:6144
	ds_read_b128 v[210:213], v171 offset:7168
	global_load_lds_dwordx4 v[158:159], off
	v_lshl_add_u64 v[158:159], s[46:47], 0, v[146:147]
	s_add_i32 m0, s33, 0xe000
	s_nop 0
	global_load_lds_dwordx4 v[158:159], off
	ds_read_b128 v[214:217], v172
	ds_read_b128 v[218:221], v172 offset:1024
	ds_read_b128 v[222:225], v172 offset:2048
	ds_read_b128 v[226:229], v172 offset:3072
	s_waitcnt vmcnt(8) lgkmcnt(0)
	s_barrier
	s_setprio 1
	v_mfma_f32_16x16x32_bf16 v[124:127], v[150:153], v[182:185], v[124:127]
	v_mfma_f32_16x16x32_bf16 v[120:123], v[174:177], v[182:185], v[120:123]
	v_mfma_f32_16x16x32_bf16 v[116:119], v[150:153], v[190:193], v[116:119]
	v_mfma_f32_16x16x32_bf16 v[108:111], v[174:177], v[190:193], v[108:111]
	v_mfma_f32_16x16x32_bf16 v[100:103], v[150:153], v[198:201], v[100:103]
	v_mfma_f32_16x16x32_bf16 v[92:95], v[174:177], v[198:201], v[92:95]
	v_mfma_f32_16x16x32_bf16 v[84:87], v[150:153], v[206:209], v[84:87]
	v_mfma_f32_16x16x32_bf16 v[76:79], v[174:177], v[206:209], v[76:79]
	v_mfma_f32_16x16x32_bf16 v[124:127], v[154:157], v[186:189], v[124:127]
	v_mfma_f32_16x16x32_bf16 v[120:123], v[178:181], v[186:189], v[120:123]
	v_mfma_f32_16x16x32_bf16 v[116:119], v[154:157], v[194:197], v[116:119]
	v_mfma_f32_16x16x32_bf16 v[108:111], v[178:181], v[194:197], v[108:111]
	v_mfma_f32_16x16x32_bf16 v[100:103], v[154:157], v[202:205], v[100:103]
	v_mfma_f32_16x16x32_bf16 v[92:95], v[178:181], v[202:205], v[92:95]
	v_mfma_f32_16x16x32_bf16 v[84:87], v[154:157], v[210:213], v[84:87]
	v_mfma_f32_16x16x32_bf16 v[76:79], v[178:181], v[210:213], v[76:79]
	v_mfma_f32_16x16x32_bf16 v[112:115], v[214:217], v[182:185], v[112:115]
	v_mfma_f32_16x16x32_bf16 v[104:107], v[222:225], v[182:185], v[104:107]
	v_mfma_f32_16x16x32_bf16 v[96:99], v[214:217], v[190:193], v[96:99]
	v_mfma_f32_16x16x32_bf16 v[88:91], v[222:225], v[190:193], v[88:91]
	v_mfma_f32_16x16x32_bf16 v[80:83], v[214:217], v[198:201], v[80:83]
	v_mfma_f32_16x16x32_bf16 v[72:75], v[222:225], v[198:201], v[72:75]
	v_mfma_f32_16x16x32_bf16 v[68:71], v[214:217], v[206:209], v[68:71]
	v_mfma_f32_16x16x32_bf16 v[64:67], v[222:225], v[206:209], v[64:67]
	v_mfma_f32_16x16x32_bf16 v[112:115], v[218:221], v[186:189], v[112:115]
	v_mfma_f32_16x16x32_bf16 v[104:107], v[226:229], v[186:189], v[104:107]
	v_mfma_f32_16x16x32_bf16 v[96:99], v[218:221], v[194:197], v[96:99]
	v_mfma_f32_16x16x32_bf16 v[88:91], v[226:229], v[194:197], v[88:91]
	v_mfma_f32_16x16x32_bf16 v[80:83], v[218:221], v[202:205], v[80:83]
	v_mfma_f32_16x16x32_bf16 v[72:75], v[226:229], v[202:205], v[72:75]
	v_mfma_f32_16x16x32_bf16 v[68:71], v[218:221], v[210:213], v[68:71]
	v_mfma_f32_16x16x32_bf16 v[64:67], v[226:229], v[210:213], v[64:67]
	s_setprio 0
	s_barrier
	s_add_i32 s84, s65, s21
	v_lshl_add_u64 v[158:159], s[54:55], 0, v[138:139]
	s_mov_b32 m0, s84
	global_load_lds_dwordx4 v[158:159], off
	v_lshl_add_u64 v[230:231], s[54:55], 0, v[142:143]
	s_add_i32 m0, s84, 0x2000
	s_nop 0
	global_load_lds_dwordx4 v[230:231], off
	s_mov_b32 m0, s33
	v_lshl_add_u64 v[232:233], s[56:57], 0, v[136:137]
	ds_read_b128 v[182:185], v171 offset:16384
	ds_read_b128 v[186:189], v171 offset:17408
	ds_read_b128 v[190:193], v171 offset:18432
	ds_read_b128 v[194:197], v171 offset:19456
	ds_read_b128 v[198:201], v171 offset:20480
	ds_read_b128 v[202:205], v171 offset:21504
	ds_read_b128 v[206:209], v171 offset:22528
	ds_read_b128 v[210:213], v171 offset:23552
	global_load_lds_dwordx4 v[232:233], off
	v_lshl_add_u64 v[234:235], s[56:57], 0, v[140:141]
	s_mov_b32 m0, s35
	s_nop 0
	global_load_lds_dwordx4 v[234:235], off
	s_add_u32 s84, s54, 0xb0000
	s_addc_u32 s85, s55, 0
	s_add_i32 s86, s66, s21
	v_lshl_add_u64 v[240:241], s[84:85], 0, v[138:139]
	s_mov_b32 m0, s86
	s_nop 0
	global_load_lds_dwordx4 v[240:241], off
	v_lshl_add_u64 v[240:241], s[84:85], 0, v[142:143]
	s_add_i32 m0, s86, 0x2000
	s_nop 0
	global_load_lds_dwordx4 v[240:241], off
	s_waitcnt vmcnt(8) lgkmcnt(0)
	s_barrier
; #define PG8_STAGE(bufoff, gbase, voff) do { _Pragma("unroll") for (int _i = 0; _i < 2; ++_i) \
;         __builtin_amdgcn_global_load_lds((const unsigned*)((const char*)(gbase) + (voff)[_i]), (LAS unsigned*)(lds + (bufoff) + ldsw + _i * 8192), 16, 0, 0); } while (0)
; #define PG8_LDA(dst, b, h) do { _Pragma("unroll") for (int m = 0; m < 4; ++m) _Pragma("unroll") for (int k = 0; k < 2; ++k) dst[m][k] = *(const LAS bf16x8*)(lds + PG8_SA(b, h) + aoff + m * 2048 + k * 1024); } while (0)
; #define PG8_LDB(dst, b, h) do { _Pragma("unroll") for (int n = 0; n < 2; ++n) _Pragma("unroll") for (int k = 0; k < 2; ++k) dst[n][k] = *(const LAS bf16x8*)(lds + PG8_SB(b, h) + boff + n * 2048 + k * 1024); } while (0)
; #define PG8_MMA(ai, bj, At, Bt) do { __builtin_amdgcn_s_setprio(1); _Pragma("unroll") for (int m = 0; m < 4; ++m) _Pragma("unroll") for (int n = 0; n < 2; ++n) _Pragma("unroll") for (int k = 0; k < 2; ++k) \
;         acc[ai][bj][m][n] = __builtin_amdgcn_mfma_f32_16x16x32_bf16(Bt[n][k], At[m][k], acc[ai][bj][m][n], 0, 0, 0); __builtin_amdgcn_s_setprio(0); } while (0)
; #define PG8_WAIT_V(n) asm volatile("s_waitcnt vmcnt(" #n ")" ::: "memory")
; #define PG8_WAIT_L(n) asm volatile("s_waitcnt lgkmcnt(" #n ")" ::: "memory")
; #define PG8_BAR __builtin_amdgcn_s_barrier()
; #define PG8_SCHED __builtin_amdgcn_sched_barrier(0)
; template <class Epi>
; __device__ __forceinline__ void gemm_phase(LAS unsigned char* lds, const Gemm g, const StaticOrder& S, const Epi& E) {
;     ...
;             PG8_LDA(At, 0, 1); PG8_STAGE(PG8_SA(0, 0), a2, voffA);
;             PG8_BAR; PG8_WAIT_L(0); PG8_MMA(1, 0, At, B0); PG8_BAR; PG8_SCHED;
;             PG8_STAGE(PG8_SB(0, 1), b2 + hstepB, voffB);
;             PG8_WAIT_V(6); PG8_BAR; PG8_MMA(1, 1, At, B1); PG8_BAR;
;             PG8_LDB(B0, 1, 0); PG8_SCHED; PG8_LDA(At, 1, 0); PG8_STAGE(PG8_SA(0, 1), a2 + hstepA, voffA);
;             PG8_WAIT_L(8); PG8_BAR; PG8_WAIT_L(0); PG8_MMA(0, 0, At, B0); PG8_BAR; PG8_SCHED;
;             PG8_LDB(B1, 1, 1); PG8_STAGE(PG8_SB(1, 0), b3, voffB);
;             PG8_BAR; PG8_WAIT_L(0); PG8_MMA(0, 1, At, B1); PG8_BAR;
	s_setprio 1
	v_mfma_f32_16x16x32_bf16 v[60:63], v[150:153], v[182:185], v[60:63]
	v_mfma_f32_16x16x32_bf16 v[56:59], v[174:177], v[182:185], v[56:59]
	v_mfma_f32_16x16x32_bf16 v[52:55], v[150:153], v[190:193], v[52:55]
	v_mfma_f32_16x16x32_bf16 v[44:47], v[174:177], v[190:193], v[44:47]
	v_mfma_f32_16x16x32_bf16 v[36:39], v[150:153], v[198:201], v[36:39]
	v_mfma_f32_16x16x32_bf16 v[28:31], v[174:177], v[198:201], v[28:31]
	v_mfma_f32_16x16x32_bf16 v[20:23], v[150:153], v[206:209], v[20:23]
	v_mfma_f32_16x16x32_bf16 v[12:15], v[174:177], v[206:209], v[12:15]
	v_mfma_f32_16x16x32_bf16 v[60:63], v[154:157], v[186:189], v[60:63]
	v_mfma_f32_16x16x32_bf16 v[56:59], v[178:181], v[186:189], v[56:59]
	v_mfma_f32_16x16x32_bf16 v[52:55], v[154:157], v[194:197], v[52:55]
	v_mfma_f32_16x16x32_bf16 v[44:47], v[178:181], v[194:197], v[44:47]
	v_mfma_f32_16x16x32_bf16 v[36:39], v[154:157], v[202:205], v[36:39]
	v_mfma_f32_16x16x32_bf16 v[28:31], v[178:181], v[202:205], v[28:31]
	v_mfma_f32_16x16x32_bf16 v[20:23], v[154:157], v[210:213], v[20:23]
	v_mfma_f32_16x16x32_bf16 v[12:15], v[178:181], v[210:213], v[12:15]
	v_mfma_f32_16x16x32_bf16 v[48:51], v[214:217], v[182:185], v[48:51]
	v_mfma_f32_16x16x32_bf16 v[40:43], v[222:225], v[182:185], v[40:43]
	v_mfma_f32_16x16x32_bf16 v[32:35], v[214:217], v[190:193], v[32:35]
	v_mfma_f32_16x16x32_bf16 v[24:27], v[222:225], v[190:193], v[24:27]
	v_mfma_f32_16x16x32_bf16 v[16:19], v[214:217], v[198:201], v[16:19]
	v_mfma_f32_16x16x32_bf16 v[8:11], v[222:225], v[198:201], v[8:11]
	v_mfma_f32_16x16x32_bf16 v[4:7], v[214:217], v[206:209], v[4:7]
	v_mfma_f32_16x16x32_bf16 v[0:3], v[222:225], v[206:209], v[0:3]
	v_mfma_f32_16x16x32_bf16 v[48:51], v[218:221], v[186:189], v[48:51]
	v_mfma_f32_16x16x32_bf16 v[40:43], v[226:229], v[186:189], v[40:43]
	v_mfma_f32_16x16x32_bf16 v[32:35], v[218:221], v[194:197], v[32:35]
	v_mfma_f32_16x16x32_bf16 v[24:27], v[226:229], v[194:197], v[24:27]
	v_mfma_f32_16x16x32_bf16 v[16:19], v[218:221], v[202:205], v[16:19]
	v_mfma_f32_16x16x32_bf16 v[8:11], v[226:229], v[202:205], v[8:11]
	v_mfma_f32_16x16x32_bf16 v[4:7], v[218:221], v[210:213], v[4:7]
	v_mfma_f32_16x16x32_bf16 v[0:3], v[226:229], v[210:213], v[0:3]
	s_setprio 0
	s_barrier
	s_add_i32 s84, 0, 0x18000
	v_add_u32_e32 v173, s84, v168
	ds_read_b128 v[150:153], v173
	ds_read_b128 v[154:157], v173 offset:1024
	ds_read_b128 v[174:177], v173 offset:2048
	ds_read_b128 v[178:181], v173 offset:3072
	s_add_u32 s56, s56, 0x160000
	s_addc_u32 s57, s57, 0
	s_mov_b32 m0, s58
	v_lshl_add_u64 v[214:215], s[56:57], 0, v[136:137]
	ds_read_b128 v[182:185], v171 offset:32768
	ds_read_b128 v[186:189], v171 offset:33792
	ds_read_b128 v[190:193], v171 offset:34816
	ds_read_b128 v[194:197], v171 offset:35840
	ds_read_b128 v[198:201], v171 offset:36864
	ds_read_b128 v[202:205], v171 offset:37888
	ds_read_b128 v[206:209], v171 offset:38912
	ds_read_b128 v[210:213], v171 offset:39936
	global_load_lds_dwordx4 v[214:215], off
	v_lshl_add_u64 v[214:215], s[56:57], 0, v[140:141]
	s_mov_b32 m0, s59
	s_nop 0
	global_load_lds_dwordx4 v[214:215], off
	s_add_i32 s56, 0, 0x1c000
	v_add_u32_e32 v173, s56, v168
	ds_read_b128 v[214:217], v173
	ds_read_b128 v[218:221], v173 offset:1024
	ds_read_b128 v[222:225], v173 offset:2048
	ds_read_b128 v[226:229], v173 offset:3072
	s_waitcnt vmcnt(8) lgkmcnt(0)
	s_barrier
	s_setprio 1
	v_mfma_f32_16x16x32_bf16 v[124:127], v[150:153], v[182:185], v[124:127]
	v_mfma_f32_16x16x32_bf16 v[120:123], v[174:177], v[182:185], v[120:123]
	v_mfma_f32_16x16x32_bf16 v[116:119], v[150:153], v[190:193], v[116:119]
	v_mfma_f32_16x16x32_bf16 v[108:111], v[174:177], v[190:193], v[108:111]
	v_mfma_f32_16x16x32_bf16 v[100:103], v[150:153], v[198:201], v[100:103]
	v_mfma_f32_16x16x32_bf16 v[92:95], v[174:177], v[198:201], v[92:95]
	v_mfma_f32_16x16x32_bf16 v[84:87], v[150:153], v[206:209], v[84:87]
	v_mfma_f32_16x16x32_bf16 v[76:79], v[174:177], v[206:209], v[76:79]
	v_mfma_f32_16x16x32_bf16 v[124:127], v[154:157], v[186:189], v[124:127]
	v_mfma_f32_16x16x32_bf16 v[120:123], v[178:181], v[186:189], v[120:123]
	v_mfma_f32_16x16x32_bf16 v[116:119], v[154:157], v[194:197], v[116:119]
	v_mfma_f32_16x16x32_bf16 v[108:111], v[178:181], v[194:197], v[108:111]
	v_mfma_f32_16x16x32_bf16 v[100:103], v[154:157], v[202:205], v[100:103]
	v_mfma_f32_16x16x32_bf16 v[92:95], v[178:181], v[202:205], v[92:95]
	v_mfma_f32_16x16x32_bf16 v[84:87], v[154:157], v[210:213], v[84:87]
	v_mfma_f32_16x16x32_bf16 v[76:79], v[178:181], v[210:213], v[76:79]
	v_mfma_f32_16x16x32_bf16 v[112:115], v[214:217], v[182:185], v[112:115]
	v_mfma_f32_16x16x32_bf16 v[104:107], v[222:225], v[182:185], v[104:107]
	v_mfma_f32_16x16x32_bf16 v[96:99], v[214:217], v[190:193], v[96:99]
	v_mfma_f32_16x16x32_bf16 v[88:91], v[222:225], v[190:193], v[88:91]
	v_mfma_f32_16x16x32_bf16 v[80:83], v[214:217], v[198:201], v[80:83]
	v_mfma_f32_16x16x32_bf16 v[72:75], v[222:225], v[198:201], v[72:75]
	v_mfma_f32_16x16x32_bf16 v[68:71], v[214:217], v[206:209], v[68:71]
	v_mfma_f32_16x16x32_bf16 v[64:67], v[222:225], v[206:209], v[64:67]
	v_mfma_f32_16x16x32_bf16 v[112:115], v[218:221], v[186:189], v[112:115]
	v_mfma_f32_16x16x32_bf16 v[104:107], v[226:229], v[186:189], v[104:107]
	v_mfma_f32_16x16x32_bf16 v[96:99], v[218:221], v[194:197], v[96:99]
	v_mfma_f32_16x16x32_bf16 v[88:91], v[226:229], v[194:197], v[88:91]
	v_mfma_f32_16x16x32_bf16 v[80:83], v[218:221], v[202:205], v[80:83]
	v_mfma_f32_16x16x32_bf16 v[72:75], v[226:229], v[202:205], v[72:75]
	v_mfma_f32_16x16x32_bf16 v[68:71], v[218:221], v[210:213], v[68:71]
	v_mfma_f32_16x16x32_bf16 v[64:67], v[226:229], v[210:213], v[64:67]
	s_setprio 0
	s_barrier
; #define PG8_STAGE(bufoff, gbase, voff) do { _Pragma("unroll") for (int _i = 0; _i < 2; ++_i) \
;         __builtin_amdgcn_global_load_lds((const unsigned*)((const char*)(gbase) + (voff)[_i]), (LAS unsigned*)(lds + (bufoff) + ldsw + _i * 8192), 16, 0, 0); } while (0)
; #define PG8_LDA(dst, b, h) do { _Pragma("unroll") for (int m = 0; m < 4; ++m) _Pragma("unroll") for (int k = 0; k < 2; ++k) dst[m][k] = *(const LAS bf16x8*)(lds + PG8_SA(b, h) + aoff + m * 2048 + k * 1024); } while (0)
; #define PG8_LDB(dst, b, h) do { _Pragma("unroll") for (int n = 0; n < 2; ++n) _Pragma("unroll") for (int k = 0; k < 2; ++k) dst[n][k] = *(const LAS bf16x8*)(lds + PG8_SB(b, h) + boff + n * 2048 + k * 1024); } while (0)
; #define PG8_MMA(ai, bj, At, Bt) do { __builtin_amdgcn_s_setprio(1); _Pragma("unroll") for (int m = 0; m < 4; ++m) _Pragma("unroll") for (int n = 0; n < 2; ++n) _Pragma("unroll") for (int k = 0; k < 2; ++k) \
;         acc[ai][bj][m][n] = __builtin_amdgcn_mfma_f32_16x16x32_bf16(Bt[n][k], At[m][k], acc[ai][bj][m][n], 0, 0, 0); __builtin_amdgcn_s_setprio(0); } while (0)
; #define PG8_WAIT_V(n) asm volatile("s_waitcnt vmcnt(" #n ")" ::: "memory")
; #define PG8_WAIT_L(n) asm volatile("s_waitcnt lgkmcnt(" #n ")" ::: "memory")
; #define PG8_BAR __builtin_amdgcn_s_barrier()
; #define PG8_SCHED __builtin_amdgcn_sched_barrier(0)
; template <class Epi>
; __device__ __forceinline__ void gemm_phase(LAS unsigned char* lds, const Gemm g, const StaticOrder& S, const Epi& E) {
;     ...
;             PG8_LDB(B1, 1, 1); PG8_STAGE(PG8_SB(1, 0), b3, voffB);
;             PG8_BAR; PG8_WAIT_L(0); PG8_MMA(0, 1, At, B1); PG8_BAR;
;             PG8_LDA(At, 1, 1); PG8_STAGE(PG8_SA(1, 0), a3, voffA);
;             PG8_BAR; PG8_WAIT_L(0); PG8_MMA(1, 0, At, B0); PG8_BAR; PG8_SCHED;
;             PG8_STAGE(PG8_SB(1, 1), b3 + hstepB, voffB);
;             PG8_WAIT_V(6); PG8_BAR; PG8_MMA(1, 1, At, B1); PG8_BAR;
;         }
	s_add_i32 s57, s84, s21
	v_lshl_add_u64 v[158:159], v[158:159], 0, s[22:23]
	s_mov_b32 m0, s57
	global_load_lds_dwordx4 v[158:159], off
	v_lshl_add_u64 v[158:159], v[230:231], 0, s[22:23]
	s_add_i32 m0, s57, 0x2000
	s_nop 0
	global_load_lds_dwordx4 v[158:159], off
	s_mov_b32 m0, s60
	v_lshl_add_u64 v[158:159], v[232:233], 0, s[22:23]
	ds_read_b128 v[182:185], v171 offset:49152
	ds_read_b128 v[186:189], v171 offset:50176
	ds_read_b128 v[190:193], v171 offset:51200
	ds_read_b128 v[194:197], v171 offset:52224
	ds_read_b128 v[198:201], v171 offset:53248
	ds_read_b128 v[202:205], v171 offset:54272
	ds_read_b128 v[206:209], v171 offset:55296
	ds_read_b128 v[210:213], v171 offset:56320
	global_load_lds_dwordx4 v[158:159], off
	v_lshl_add_u64 v[158:159], v[234:235], 0, s[22:23]
	s_mov_b32 m0, s61
	s_nop 0
	global_load_lds_dwordx4 v[158:159], off
	s_add_u32 s54, s54, 0xb0080
	s_addc_u32 s55, s55, 0
	s_add_i32 s56, s56, s21
	v_lshl_add_u64 v[240:241], s[54:55], 0, v[138:139]
	s_mov_b32 m0, s56
	s_nop 0
	global_load_lds_dwordx4 v[240:241], off
	v_lshl_add_u64 v[240:241], s[54:55], 0, v[142:143]
	s_add_i32 m0, s56, 0x2000
	s_nop 0
	global_load_lds_dwordx4 v[240:241], off
	s_waitcnt vmcnt(8) lgkmcnt(0)
	s_barrier
	s_setprio 1
	v_mfma_f32_16x16x32_bf16 v[60:63], v[150:153], v[182:185], v[60:63]
	v_mfma_f32_16x16x32_bf16 v[56:59], v[174:177], v[182:185], v[56:59]
	v_mfma_f32_16x16x32_bf16 v[52:55], v[150:153], v[190:193], v[52:55]
	v_mfma_f32_16x16x32_bf16 v[44:47], v[174:177], v[190:193], v[44:47]
	v_mfma_f32_16x16x32_bf16 v[36:39], v[150:153], v[198:201], v[36:39]
	v_mfma_f32_16x16x32_bf16 v[28:31], v[174:177], v[198:201], v[28:31]
	v_mfma_f32_16x16x32_bf16 v[20:23], v[150:153], v[206:209], v[20:23]
	v_mfma_f32_16x16x32_bf16 v[12:15], v[174:177], v[206:209], v[12:15]
	v_mfma_f32_16x16x32_bf16 v[60:63], v[154:157], v[186:189], v[60:63]
	v_mfma_f32_16x16x32_bf16 v[56:59], v[178:181], v[186:189], v[56:59]
	v_mfma_f32_16x16x32_bf16 v[52:55], v[154:157], v[194:197], v[52:55]
	v_mfma_f32_16x16x32_bf16 v[44:47], v[178:181], v[194:197], v[44:47]
	v_mfma_f32_16x16x32_bf16 v[36:39], v[154:157], v[202:205], v[36:39]
	v_mfma_f32_16x16x32_bf16 v[28:31], v[178:181], v[202:205], v[28:31]
	v_mfma_f32_16x16x32_bf16 v[20:23], v[154:157], v[210:213], v[20:23]
	v_mfma_f32_16x16x32_bf16 v[12:15], v[178:181], v[210:213], v[12:15]
	v_mfma_f32_16x16x32_bf16 v[48:51], v[214:217], v[182:185], v[48:51]
	v_mfma_f32_16x16x32_bf16 v[40:43], v[222:225], v[182:185], v[40:43]
	v_mfma_f32_16x16x32_bf16 v[32:35], v[214:217], v[190:193], v[32:35]
	v_mfma_f32_16x16x32_bf16 v[24:27], v[222:225], v[190:193], v[24:27]
	v_mfma_f32_16x16x32_bf16 v[16:19], v[214:217], v[198:201], v[16:19]
	v_mfma_f32_16x16x32_bf16 v[8:11], v[222:225], v[198:201], v[8:11]
	v_mfma_f32_16x16x32_bf16 v[4:7], v[214:217], v[206:209], v[4:7]
	v_mfma_f32_16x16x32_bf16 v[0:3], v[222:225], v[206:209], v[0:3]
	v_mfma_f32_16x16x32_bf16 v[48:51], v[218:221], v[186:189], v[48:51]
	v_mfma_f32_16x16x32_bf16 v[40:43], v[226:229], v[186:189], v[40:43]
	v_mfma_f32_16x16x32_bf16 v[32:35], v[218:221], v[194:197], v[32:35]
	v_mfma_f32_16x16x32_bf16 v[24:27], v[226:229], v[194:197], v[24:27]
	v_mfma_f32_16x16x32_bf16 v[16:19], v[218:221], v[202:205], v[16:19]
	v_mfma_f32_16x16x32_bf16 v[8:11], v[226:229], v[202:205], v[8:11]
	v_mfma_f32_16x16x32_bf16 v[4:7], v[218:221], v[210:213], v[4:7]
	v_mfma_f32_16x16x32_bf16 v[0:3], v[226:229], v[210:213], v[0:3]
	s_setprio 0
	s_add_u32 s46, s46, 0x100
	s_addc_u32 s47, s47, 0
	s_add_u32 s41, s41, 0x100
	s_addc_u32 s82, s82, 0
	s_cmp_ge_i32 s83, s81
	s_mov_b32 s54, s83
	s_barrier
;     __device__ __forceinline__ void operator()(const f32x4 (&acc)[2][2][4][2], const Unit& u, int wr, int wc, int fr, int fq) const {
;     ...
;         if (u.part) {
;             float* base = tailacc + (size_t)(u.part - 1) * slab - (size_t)tail_row0 * tail_ld;
; #pragma unroll
;             for (int ai = 0; ai < 2; ++ai)
; #pragma unroll
;                 for (int m = 0; m < 4; ++m) { float* rowp = base + (size_t)(row0 + ai * HALF + m * 16) * tail_ld + col0;
; #pragma unroll
;                     for (int bj = 0; bj < 2; ++bj)
; #pragma unroll
;                         for (int n = 0; n < 2; ++n) *(f32x4*)(rowp + bj * HALF + 4 * n) = acc[ai][bj][m][n]; }
;             return;
	s_cbranch_scc0 .LBB0_910
	v_lshl_add_u32 v158, s78, 8, v167
	v_lshl_or_b32 v150, s79, 8, v169
	v_or_b32_e32 v156, 16, v158
	v_or_b32_e32 v154, 32, v158
	v_or_b32_e32 v152, 48, v158
	s_cmp_lg_u32 s80, 0
	v_ashrrev_i32_e32 v151, 31, v150
	v_ashrrev_i32_e32 v159, 31, v158
	v_ashrrev_i32_e32 v157, 31, v156
	v_ashrrev_i32_e32 v155, 31, v154
	v_ashrrev_i32_e32 v153, 31, v152
	s_cbranch_scc0 .LBB0_913
	s_add_i32 s18, s80, -1
	s_lshl_b64 s[46:47], s[18:19], 21
	s_add_u32 s46, s92, s46
	s_addc_u32 s47, s93, s47
	v_lshl_add_u64 v[174:175], v[150:151], 2, s[46:47]
	s_brev_b32 s46, 63
	s_mov_b32 s47, -1
	v_lshl_add_u64 v[174:175], v[174:175], 0, s[46:47]
	v_lshlrev_b64 v[176:177], 12, v[158:159]
	v_lshlrev_b64 v[178:179], 12, v[156:157]
	v_lshl_add_u64 v[176:177], v[174:175], 0, v[176:177]
	v_lshl_add_u64 v[178:179], v[174:175], 0, v[178:179]
	global_store_dwordx4 v[176:177], v[124:127], off
	global_store_dwordx4 v[176:177], v[120:123], off offset:16
	global_store_dwordx4 v[176:177], v[112:115], off offset:512
	global_store_dwordx4 v[176:177], v[104:107], off offset:528
	global_store_dwordx4 v[178:179], v[116:119], off
	global_store_dwordx4 v[178:179], v[108:111], off offset:16
	global_store_dwordx4 v[178:179], v[96:99], off offset:512
	global_store_dwordx4 v[178:179], v[88:91], off offset:528
	v_lshlrev_b64 v[178:179], 12, v[154:155]
	v_lshl_add_u64 v[178:179], v[174:175], 0, v[178:179]
	global_store_dwordx4 v[178:179], v[100:103], off
	global_store_dwordx4 v[178:179], v[92:95], off offset:16
	global_store_dwordx4 v[178:179], v[80:83], off offset:512
	global_store_dwordx4 v[178:179], v[72:75], off offset:528
	v_lshlrev_b64 v[178:179], 12, v[152:153]
	s_mov_b32 s18, 0x80000
	v_lshl_add_u64 v[174:175], v[174:175], 0, v[178:179]
	v_add_co_u32_e32 v178, vcc, s18, v176
	s_mov_b64 s[46:47], 0x80000
	s_nop 0
	v_addc_co_u32_e32 v179, vcc, 0, v177, vcc
	global_store_dwordx4 v[174:175], v[84:87], off
	global_store_dwordx4 v[174:175], v[76:79], off offset:16
	global_store_dwordx4 v[174:175], v[68:71], off offset:512
	global_store_dwordx4 v[174:175], v[64:67], off offset:528
	v_lshl_add_u64 v[174:175], v[176:177], 0, s[46:47]
	global_store_dwordx4 v[178:179], v[60:63], off
	global_store_dwordx4 v[174:175], v[56:59], off offset:16
	global_store_dwordx4 v[174:175], v[48:51], off offset:512
	global_store_dwordx4 v[174:175], v[40:43], off offset:528
	v_add_co_u32_e32 v178, vcc, s67, v176
	s_mov_b64 s[46:47], 0x90000
	s_nop 0
	v_addc_co_u32_e32 v179, vcc, 0, v177, vcc
	v_lshl_add_u64 v[174:175], v[176:177], 0, s[46:47]
	global_store_dwordx4 v[178:179], v[52:55], off
	global_store_dwordx4 v[174:175], v[44:47], off offset:16
	global_store_dwordx4 v[174:175], v[32:35], off offset:512
	global_store_dwordx4 v[174:175], v[24:27], off offset:528
	v_add_co_u32_e32 v178, vcc, s68, v176
	v_lshl_add_u64 v[174:175], v[176:177], 0, s[24:25]
	s_nop 0
	v_addc_co_u32_e32 v179, vcc, 0, v177, vcc
	s_mov_b64 s[46:47], 0xb0000
	global_store_dwordx4 v[178:179], v[36:39], off
	global_store_dwordx4 v[174:175], v[28:31], off offset:16
	global_store_dwordx4 v[174:175], v[16:19], off offset:512
	global_store_dwordx4 v[174:175], v[8:11], off offset:528
	v_lshl_add_u64 v[174:175], v[176:177], 0, s[46:47]
	v_add_co_u32_e32 v176, vcc, 0xb0000, v176
	s_nop 1
	v_addc_co_u32_e32 v177, vcc, 0, v177, vcc
	global_store_dwordx4 v[176:177], v[20:23], off
	global_store_dwordx4 v[174:175], v[12:15], off offset:16
	global_store_dwordx4 v[174:175], v[4:7], off offset:512
	global_store_dwordx4 v[174:175], v[0:3], off offset:528
	s_cbranch_execnz .LBB0_895
	s_branch .LBB0_894

; #define PG8_STAGE(bufoff, gbase, voff) do { _Pragma("unroll") for (int _i = 0; _i < 2; ++_i) \
;         __builtin_amdgcn_global_load_lds((const unsigned*)((const char*)(gbase) + (voff)[_i]), (LAS unsigned*)(lds + (bufoff) + ldsw + _i * 8192), 16, 0, 0); } while (0)
; #define PG8_LDA(dst, b, h) do { _Pragma("unroll") for (int m = 0; m < 4; ++m) _Pragma("unroll") for (int k = 0; k < 2; ++k) dst[m][k] = *(const LAS bf16x8*)(lds + PG8_SA(b, h) + aoff + m * 2048 + k * 1024); } while (0)
; #define PG8_LDB(dst, b, h) do { _Pragma("unroll") for (int n = 0; n < 2; ++n) _Pragma("unroll") for (int k = 0; k < 2; ++k) dst[n][k] = *(const LAS bf16x8*)(lds + PG8_SB(b, h) + boff + n * 2048 + k * 1024); } while (0)
; #define PG8_MMA(ai, bj, At, Bt) do { __builtin_amdgcn_s_setprio(1); _Pragma("unroll") for (int m = 0; m < 4; ++m) _Pragma("unroll") for (int n = 0; n < 2; ++n) _Pragma("unroll") for (int k = 0; k < 2; ++k) \
;         acc[ai][bj][m][n] = __builtin_amdgcn_mfma_f32_16x16x32_bf16(Bt[n][k], At[m][k], acc[ai][bj][m][n], 0, 0, 0); __builtin_amdgcn_s_setprio(0); } while (0)
; #define PG8_WAIT_V(n) asm volatile("s_waitcnt vmcnt(" #n ")" ::: "memory")
; #define PG8_WAIT_L(n) asm volatile("s_waitcnt lgkmcnt(" #n ")" ::: "memory")
; template <class Epi>
; __device__ __forceinline__ void gemm_phase(LAS unsigned char* lds, const Gemm g, const StaticOrder& S, const Epi& E) {
;     ...
;         for (int t = 0; t < nt; t += 2) {
;             const bool last = (t == nt - 2);
;             const char* a1 = cA + (size_t)(t + 1) * kstep;
;             const char* a2 = last ? nA : cA + (size_t)(t + 2) * kstep; const char* b2 = last ? nB : cB + (size_t)(t + 2) * kstep;
;             const char* a3 = a2 + kstep; const char* b3 = b2 + kstep;
;             PG8_LDB(B0, 0, 0); PG8_SCHED; PG8_LDA(At, 0, 0); PG8_STAGE(PG8_SA(1, 1), a1 + hstepA, voffA);
;             PG8_WAIT_L(8); PG8_BAR; PG8_WAIT_L(0); PG8_MMA(0, 0, At, B0); PG8_BAR; PG8_SCHED;
;             PG8_LDB(B1, 0, 1); PG8_STAGE(PG8_SB(0, 0), b2, voffB);
;             PG8_BAR; PG8_WAIT_L(0); PG8_MMA(0, 1, At, B1); PG8_BAR;
;             PG8_LDA(At, 0, 1); PG8_STAGE(PG8_SA(0, 0), a2, voffA);
;             PG8_BAR; PG8_WAIT_L(0); PG8_MMA(1, 0, At, B0); PG8_BAR; PG8_SCHED;
;             PG8_STAGE(PG8_SB(0, 1), b2 + hstepB, voffB);
;             PG8_WAIT_V(6); PG8_BAR; PG8_MMA(1, 1, At, B1); PG8_BAR;
.LBB0_1146:
	ds_read_b128 v[150:153], v129
	ds_read_b128 v[154:157], v129 offset:1024
	ds_read_b128 v[158:161], v129 offset:2048
	ds_read_b128 v[166:169], v129 offset:3072
	s_add_i32 s77, s45, 2
	s_add_u32 s54, s50, 0xfffc0080
	s_addc_u32 s55, s51, -1
	s_cmp_eq_u32 s39, s45
	s_cselect_b32 s57, s49, s55
	s_cselect_b32 s56, s48, s54
	s_cselect_b32 s55, s1, s43
	s_cselect_b32 s54, s0, s41
	v_lshl_add_u64 v[202:203], s[50:51], 0, v[144:145]
	s_add_i32 m0, s33, 0xc000
	ds_read_b128 v[170:173], v163
	ds_read_b128 v[174:177], v163 offset:1024
	ds_read_b128 v[178:181], v163 offset:2048
	ds_read_b128 v[182:185], v163 offset:3072
	ds_read_b128 v[186:189], v163 offset:4096
	ds_read_b128 v[190:193], v163 offset:5120
	ds_read_b128 v[194:197], v163 offset:6144
	ds_read_b128 v[198:201], v163 offset:7168
	global_load_lds_dwordx4 v[202:203], off
	v_lshl_add_u64 v[202:203], s[50:51], 0, v[146:147]
	s_add_i32 m0, s33, 0xe000
	s_nop 0
	global_load_lds_dwordx4 v[202:203], off
	ds_read_b128 v[202:205], v164
	ds_read_b128 v[206:209], v164 offset:1024
	ds_read_b128 v[210:213], v164 offset:2048
	ds_read_b128 v[214:217], v164 offset:3072
	s_waitcnt vmcnt(8) lgkmcnt(0)
	s_barrier
	s_setprio 1
	v_mfma_f32_16x16x32_bf16 v[124:127], v[150:153], v[170:173], v[124:127]
	v_mfma_f32_16x16x32_bf16 v[120:123], v[158:161], v[170:173], v[120:123]
	v_mfma_f32_16x16x32_bf16 v[116:119], v[150:153], v[178:181], v[116:119]
	v_mfma_f32_16x16x32_bf16 v[108:111], v[158:161], v[178:181], v[108:111]
	v_mfma_f32_16x16x32_bf16 v[100:103], v[150:153], v[186:189], v[100:103]
	v_mfma_f32_16x16x32_bf16 v[92:95], v[158:161], v[186:189], v[92:95]
	v_mfma_f32_16x16x32_bf16 v[84:87], v[150:153], v[194:197], v[84:87]
	v_mfma_f32_16x16x32_bf16 v[76:79], v[158:161], v[194:197], v[76:79]
	v_mfma_f32_16x16x32_bf16 v[124:127], v[154:157], v[174:177], v[124:127]
	v_mfma_f32_16x16x32_bf16 v[120:123], v[166:169], v[174:177], v[120:123]
	v_mfma_f32_16x16x32_bf16 v[116:119], v[154:157], v[182:185], v[116:119]
	v_mfma_f32_16x16x32_bf16 v[108:111], v[166:169], v[182:185], v[108:111]
	v_mfma_f32_16x16x32_bf16 v[100:103], v[154:157], v[190:193], v[100:103]
	v_mfma_f32_16x16x32_bf16 v[92:95], v[166:169], v[190:193], v[92:95]
	v_mfma_f32_16x16x32_bf16 v[84:87], v[154:157], v[198:201], v[84:87]
	v_mfma_f32_16x16x32_bf16 v[76:79], v[166:169], v[198:201], v[76:79]
	v_mfma_f32_16x16x32_bf16 v[112:115], v[202:205], v[170:173], v[112:115]
	v_mfma_f32_16x16x32_bf16 v[104:107], v[210:213], v[170:173], v[104:107]
	v_mfma_f32_16x16x32_bf16 v[96:99], v[202:205], v[178:181], v[96:99]
	v_mfma_f32_16x16x32_bf16 v[88:91], v[210:213], v[178:181], v[88:91]
	v_mfma_f32_16x16x32_bf16 v[80:83], v[202:205], v[186:189], v[80:83]
	v_mfma_f32_16x16x32_bf16 v[72:75], v[210:213], v[186:189], v[72:75]
	v_mfma_f32_16x16x32_bf16 v[68:71], v[202:205], v[194:197], v[68:71]
	v_mfma_f32_16x16x32_bf16 v[64:67], v[210:213], v[194:197], v[64:67]
	v_mfma_f32_16x16x32_bf16 v[112:115], v[206:209], v[174:177], v[112:115]
	v_mfma_f32_16x16x32_bf16 v[104:107], v[214:217], v[174:177], v[104:107]
	v_mfma_f32_16x16x32_bf16 v[96:99], v[206:209], v[182:185], v[96:99]
	v_mfma_f32_16x16x32_bf16 v[88:91], v[214:217], v[182:185], v[88:91]
	v_mfma_f32_16x16x32_bf16 v[80:83], v[206:209], v[190:193], v[80:83]
	v_mfma_f32_16x16x32_bf16 v[72:75], v[214:217], v[190:193], v[72:75]
	v_mfma_f32_16x16x32_bf16 v[68:71], v[206:209], v[198:201], v[68:71]
	v_mfma_f32_16x16x32_bf16 v[64:67], v[214:217], v[198:201], v[64:67]
	s_setprio 0
	s_barrier
	s_add_i32 s45, s66, s21
	v_lshl_add_u64 v[218:219], s[54:55], 0, v[138:139]
	s_mov_b32 m0, s45
	global_load_lds_dwordx4 v[218:219], off
	v_lshl_add_u64 v[220:221], s[54:55], 0, v[142:143]
	s_add_i32 m0, s45, 0x2000
	s_nop 0
	global_load_lds_dwordx4 v[220:221], off
	s_mov_b32 m0, s33
	v_lshl_add_u64 v[222:223], s[56:57], 0, v[136:137]
	ds_read_b128 v[170:173], v163 offset:16384
	ds_read_b128 v[174:177], v163 offset:17408
	ds_read_b128 v[178:181], v163 offset:18432
	ds_read_b128 v[182:185], v163 offset:19456
	ds_read_b128 v[186:189], v163 offset:20480
	ds_read_b128 v[190:193], v163 offset:21504
	ds_read_b128 v[194:197], v163 offset:22528
	ds_read_b128 v[198:201], v163 offset:23552
	global_load_lds_dwordx4 v[222:223], off
	v_lshl_add_u64 v[224:225], s[56:57], 0, v[140:141]
	s_mov_b32 m0, s35
	s_nop 0
	global_load_lds_dwordx4 v[224:225], off
	s_add_u32 s78, s54, 0x40000
	s_addc_u32 s79, s55, 0
	s_add_i32 s45, s67, s21
	v_lshl_add_u64 v[240:241], s[78:79], 0, v[138:139]
	s_mov_b32 m0, s45
	s_nop 0
	global_load_lds_dwordx4 v[240:241], off
	v_lshl_add_u64 v[240:241], s[78:79], 0, v[142:143]
	s_add_i32 m0, s45, 0x2000
	s_nop 0
	global_load_lds_dwordx4 v[240:241], off
	s_waitcnt vmcnt(8) lgkmcnt(0)
	s_barrier
; #define PG8_STAGE(bufoff, gbase, voff) do { _Pragma("unroll") for (int _i = 0; _i < 2; ++_i) \
;         __builtin_amdgcn_global_load_lds((const unsigned*)((const char*)(gbase) + (voff)[_i]), (LAS unsigned*)(lds + (bufoff) + ldsw + _i * 8192), 16, 0, 0); } while (0)
; #define PG8_LDA(dst, b, h) do { _Pragma("unroll") for (int m = 0; m < 4; ++m) _Pragma("unroll") for (int k = 0; k < 2; ++k) dst[m][k] = *(const LAS bf16x8*)(lds + PG8_SA(b, h) + aoff + m * 2048 + k * 1024); } while (0)
; #define PG8_LDB(dst, b, h) do { _Pragma("unroll") for (int n = 0; n < 2; ++n) _Pragma("unroll") for (int k = 0; k < 2; ++k) dst[n][k] = *(const LAS bf16x8*)(lds + PG8_SB(b, h) + boff + n * 2048 + k * 1024); } while (0)
; #define PG8_MMA(ai, bj, At, Bt) do { __builtin_amdgcn_s_setprio(1); _Pragma("unroll") for (int m = 0; m < 4; ++m) _Pragma("unroll") for (int n = 0; n < 2; ++n) _Pragma("unroll") for (int k = 0; k < 2; ++k) \
;         acc[ai][bj][m][n] = __builtin_amdgcn_mfma_f32_16x16x32_bf16(Bt[n][k], At[m][k], acc[ai][bj][m][n], 0, 0, 0); __builtin_amdgcn_s_setprio(0); } while (0)
; #define PG8_WAIT_V(n) asm volatile("s_waitcnt vmcnt(" #n ")" ::: "memory")
; #define PG8_WAIT_L(n) asm volatile("s_waitcnt lgkmcnt(" #n ")" ::: "memory")
; #define PG8_BAR __builtin_amdgcn_s_barrier()
; #define PG8_SCHED __builtin_amdgcn_sched_barrier(0)
; template <class Epi>
; __device__ __forceinline__ void gemm_phase(LAS unsigned char* lds, const Gemm g, const StaticOrder& S, const Epi& E) {
;     ...
;             PG8_LDA(At, 0, 1); PG8_STAGE(PG8_SA(0, 0), a2, voffA);
;             PG8_BAR; PG8_WAIT_L(0); PG8_MMA(1, 0, At, B0); PG8_BAR; PG8_SCHED;
;             PG8_STAGE(PG8_SB(0, 1), b2 + hstepB, voffB);
;             PG8_WAIT_V(6); PG8_BAR; PG8_MMA(1, 1, At, B1); PG8_BAR;
;             PG8_LDB(B0, 1, 0); PG8_SCHED; PG8_LDA(At, 1, 0); PG8_STAGE(PG8_SA(0, 1), a2 + hstepA, voffA);
;             PG8_WAIT_L(8); PG8_BAR; PG8_WAIT_L(0); PG8_MMA(0, 0, At, B0); PG8_BAR; PG8_SCHED;
;             PG8_LDB(B1, 1, 1); PG8_STAGE(PG8_SB(1, 0), b3, voffB);
;             PG8_BAR; PG8_WAIT_L(0); PG8_MMA(0, 1, At, B1); PG8_BAR;
	s_setprio 1
	v_mfma_f32_16x16x32_bf16 v[60:63], v[150:153], v[170:173], v[60:63]
	v_mfma_f32_16x16x32_bf16 v[56:59], v[158:161], v[170:173], v[56:59]
	v_mfma_f32_16x16x32_bf16 v[52:55], v[150:153], v[178:181], v[52:55]
	v_mfma_f32_16x16x32_bf16 v[44:47], v[158:161], v[178:181], v[44:47]
	v_mfma_f32_16x16x32_bf16 v[36:39], v[150:153], v[186:189], v[36:39]
	v_mfma_f32_16x16x32_bf16 v[28:31], v[158:161], v[186:189], v[28:31]
	v_mfma_f32_16x16x32_bf16 v[20:23], v[150:153], v[194:197], v[20:23]
	v_mfma_f32_16x16x32_bf16 v[12:15], v[158:161], v[194:197], v[12:15]
	v_mfma_f32_16x16x32_bf16 v[60:63], v[154:157], v[174:177], v[60:63]
	v_mfma_f32_16x16x32_bf16 v[56:59], v[166:169], v[174:177], v[56:59]
	v_mfma_f32_16x16x32_bf16 v[52:55], v[154:157], v[182:185], v[52:55]
	v_mfma_f32_16x16x32_bf16 v[44:47], v[166:169], v[182:185], v[44:47]
	v_mfma_f32_16x16x32_bf16 v[36:39], v[154:157], v[190:193], v[36:39]
	v_mfma_f32_16x16x32_bf16 v[28:31], v[166:169], v[190:193], v[28:31]
	v_mfma_f32_16x16x32_bf16 v[20:23], v[154:157], v[198:201], v[20:23]
	v_mfma_f32_16x16x32_bf16 v[12:15], v[166:169], v[198:201], v[12:15]
	v_mfma_f32_16x16x32_bf16 v[48:51], v[202:205], v[170:173], v[48:51]
	v_mfma_f32_16x16x32_bf16 v[40:43], v[210:213], v[170:173], v[40:43]
	v_mfma_f32_16x16x32_bf16 v[32:35], v[202:205], v[178:181], v[32:35]
	v_mfma_f32_16x16x32_bf16 v[24:27], v[210:213], v[178:181], v[24:27]
	v_mfma_f32_16x16x32_bf16 v[16:19], v[202:205], v[186:189], v[16:19]
	v_mfma_f32_16x16x32_bf16 v[8:11], v[210:213], v[186:189], v[8:11]
	v_mfma_f32_16x16x32_bf16 v[4:7], v[202:205], v[194:197], v[4:7]
	v_mfma_f32_16x16x32_bf16 v[0:3], v[210:213], v[194:197], v[0:3]
	v_mfma_f32_16x16x32_bf16 v[48:51], v[206:209], v[174:177], v[48:51]
	v_mfma_f32_16x16x32_bf16 v[40:43], v[214:217], v[174:177], v[40:43]
	v_mfma_f32_16x16x32_bf16 v[32:35], v[206:209], v[182:185], v[32:35]
	v_mfma_f32_16x16x32_bf16 v[24:27], v[214:217], v[182:185], v[24:27]
	v_mfma_f32_16x16x32_bf16 v[16:19], v[206:209], v[190:193], v[16:19]
	v_mfma_f32_16x16x32_bf16 v[8:11], v[214:217], v[190:193], v[8:11]
	v_mfma_f32_16x16x32_bf16 v[4:7], v[206:209], v[198:201], v[4:7]
	v_mfma_f32_16x16x32_bf16 v[0:3], v[214:217], v[198:201], v[0:3]
	s_setprio 0
	s_barrier
	s_add_i32 s45, 0, 0x18000
	v_add_u32_e32 v165, s45, v135
	ds_read_b128 v[150:153], v165
	ds_read_b128 v[154:157], v165 offset:1024
	ds_read_b128 v[158:161], v165 offset:2048
	ds_read_b128 v[166:169], v165 offset:3072
	s_add_u32 s56, s56, 0x40000
	s_addc_u32 s57, s57, 0
	s_mov_b32 m0, s58
	v_lshl_add_u64 v[202:203], s[56:57], 0, v[136:137]
	ds_read_b128 v[170:173], v163 offset:32768
	ds_read_b128 v[174:177], v163 offset:33792
	ds_read_b128 v[178:181], v163 offset:34816
	ds_read_b128 v[182:185], v163 offset:35840
	ds_read_b128 v[186:189], v163 offset:36864
	ds_read_b128 v[190:193], v163 offset:37888
	ds_read_b128 v[194:197], v163 offset:38912
	ds_read_b128 v[198:201], v163 offset:39936
	global_load_lds_dwordx4 v[202:203], off
	v_lshl_add_u64 v[202:203], s[56:57], 0, v[140:141]
	s_mov_b32 m0, s59
	s_nop 0
	global_load_lds_dwordx4 v[202:203], off
	s_add_i32 s56, 0, 0x1c000
	v_add_u32_e32 v165, s56, v135
	ds_read_b128 v[202:205], v165
	ds_read_b128 v[206:209], v165 offset:1024
	ds_read_b128 v[210:213], v165 offset:2048
	ds_read_b128 v[214:217], v165 offset:3072
	s_waitcnt vmcnt(8) lgkmcnt(0)
	s_barrier
	s_setprio 1
	v_mfma_f32_16x16x32_bf16 v[124:127], v[150:153], v[170:173], v[124:127]
	v_mfma_f32_16x16x32_bf16 v[120:123], v[158:161], v[170:173], v[120:123]
	v_mfma_f32_16x16x32_bf16 v[116:119], v[150:153], v[178:181], v[116:119]
	v_mfma_f32_16x16x32_bf16 v[108:111], v[158:161], v[178:181], v[108:111]
	v_mfma_f32_16x16x32_bf16 v[100:103], v[150:153], v[186:189], v[100:103]
	v_mfma_f32_16x16x32_bf16 v[92:95], v[158:161], v[186:189], v[92:95]
	v_mfma_f32_16x16x32_bf16 v[84:87], v[150:153], v[194:197], v[84:87]
	v_mfma_f32_16x16x32_bf16 v[76:79], v[158:161], v[194:197], v[76:79]
	v_mfma_f32_16x16x32_bf16 v[124:127], v[154:157], v[174:177], v[124:127]
	v_mfma_f32_16x16x32_bf16 v[120:123], v[166:169], v[174:177], v[120:123]
	v_mfma_f32_16x16x32_bf16 v[116:119], v[154:157], v[182:185], v[116:119]
	v_mfma_f32_16x16x32_bf16 v[108:111], v[166:169], v[182:185], v[108:111]
	v_mfma_f32_16x16x32_bf16 v[100:103], v[154:157], v[190:193], v[100:103]
	v_mfma_f32_16x16x32_bf16 v[92:95], v[166:169], v[190:193], v[92:95]
	v_mfma_f32_16x16x32_bf16 v[84:87], v[154:157], v[198:201], v[84:87]
	v_mfma_f32_16x16x32_bf16 v[76:79], v[166:169], v[198:201], v[76:79]
	v_mfma_f32_16x16x32_bf16 v[112:115], v[202:205], v[170:173], v[112:115]
	v_mfma_f32_16x16x32_bf16 v[104:107], v[210:213], v[170:173], v[104:107]
	v_mfma_f32_16x16x32_bf16 v[96:99], v[202:205], v[178:181], v[96:99]
	v_mfma_f32_16x16x32_bf16 v[88:91], v[210:213], v[178:181], v[88:91]
	v_mfma_f32_16x16x32_bf16 v[80:83], v[202:205], v[186:189], v[80:83]
	v_mfma_f32_16x16x32_bf16 v[72:75], v[210:213], v[186:189], v[72:75]
	v_mfma_f32_16x16x32_bf16 v[68:71], v[202:205], v[194:197], v[68:71]
	v_mfma_f32_16x16x32_bf16 v[64:67], v[210:213], v[194:197], v[64:67]
	v_mfma_f32_16x16x32_bf16 v[112:115], v[206:209], v[174:177], v[112:115]
	v_mfma_f32_16x16x32_bf16 v[104:107], v[214:217], v[174:177], v[104:107]
	v_mfma_f32_16x16x32_bf16 v[96:99], v[206:209], v[182:185], v[96:99]
	v_mfma_f32_16x16x32_bf16 v[88:91], v[214:217], v[182:185], v[88:91]
	v_mfma_f32_16x16x32_bf16 v[80:83], v[206:209], v[190:193], v[80:83]
	v_mfma_f32_16x16x32_bf16 v[72:75], v[214:217], v[190:193], v[72:75]
	v_mfma_f32_16x16x32_bf16 v[68:71], v[206:209], v[198:201], v[68:71]
	v_mfma_f32_16x16x32_bf16 v[64:67], v[214:217], v[198:201], v[64:67]
	s_setprio 0
	s_barrier
; #define PG8_STAGE(bufoff, gbase, voff) do { _Pragma("unroll") for (int _i = 0; _i < 2; ++_i) \
;         __builtin_amdgcn_global_load_lds((const unsigned*)((const char*)(gbase) + (voff)[_i]), (LAS unsigned*)(lds + (bufoff) + ldsw + _i * 8192), 16, 0, 0); } while (0)
; #define PG8_LDA(dst, b, h) do { _Pragma("unroll") for (int m = 0; m < 4; ++m) _Pragma("unroll") for (int k = 0; k < 2; ++k) dst[m][k] = *(const LAS bf16x8*)(lds + PG8_SA(b, h) + aoff + m * 2048 + k * 1024); } while (0)
; #define PG8_LDB(dst, b, h) do { _Pragma("unroll") for (int n = 0; n < 2; ++n) _Pragma("unroll") for (int k = 0; k < 2; ++k) dst[n][k] = *(const LAS bf16x8*)(lds + PG8_SB(b, h) + boff + n * 2048 + k * 1024); } while (0)
; #define PG8_MMA(ai, bj, At, Bt) do { __builtin_amdgcn_s_setprio(1); _Pragma("unroll") for (int m = 0; m < 4; ++m) _Pragma("unroll") for (int n = 0; n < 2; ++n) _Pragma("unroll") for (int k = 0; k < 2; ++k) \
;         acc[ai][bj][m][n] = __builtin_amdgcn_mfma_f32_16x16x32_bf16(Bt[n][k], At[m][k], acc[ai][bj][m][n], 0, 0, 0); __builtin_amdgcn_s_setprio(0); } while (0)
; #define PG8_BAR __builtin_amdgcn_s_barrier()
;     __device__ __forceinline__ void operator()(const f32x4 (&acc)[2][2][4][2], const Unit& u, int wr, int wc, int fr, int fq) const {
;     ...
;         if (u.part) {
;             float* base = tailacc + (size_t)(u.part - 1) * slab - (size_t)tail_row0 * tail_ld;
; #pragma unroll
;             for (int ai = 0; ai < 2; ++ai)
; #pragma unroll
;                 for (int m = 0; m < 4; ++m) { float* rowp = base + (size_t)(row0 + ai * HALF + m * 16) * tail_ld + col0;
; #pragma unroll
;                     for (int bj = 0; bj < 2; ++bj)
; #pragma unroll
;                         for (int n = 0; n < 2; ++n) *(f32x4*)(rowp + bj * HALF + 4 * n) = acc[ai][bj][m][n]; }
;             return;
; template <class Epi>
; __device__ __forceinline__ void gemm_phase(LAS unsigned char* lds, const Gemm g, const StaticOrder& S, const Epi& E) {
;     ...
;             PG8_LDB(B1, 1, 1); PG8_STAGE(PG8_SB(1, 0), b3, voffB);
;             PG8_BAR; PG8_WAIT_L(0); PG8_MMA(0, 1, At, B1); PG8_BAR;
;             PG8_LDA(At, 1, 1); PG8_STAGE(PG8_SA(1, 0), a3, voffA);
;             PG8_BAR; PG8_WAIT_L(0); PG8_MMA(1, 0, At, B0); PG8_BAR; PG8_SCHED;
;             PG8_STAGE(PG8_SB(1, 1), b3 + hstepB, voffB);
;             PG8_WAIT_V(6); PG8_BAR; PG8_MMA(1, 1, At, B1); PG8_BAR;
;         }
	s_add_i32 s45, s45, s21
	v_lshl_add_u64 v[218:219], v[218:219], 0, s[12:13]
	s_mov_b32 m0, s45
	global_load_lds_dwordx4 v[218:219], off
	v_lshl_add_u64 v[218:219], v[220:221], 0, s[12:13]
	s_add_i32 m0, s45, 0x2000
	s_nop 0
	global_load_lds_dwordx4 v[218:219], off
	s_mov_b32 m0, s60
	v_lshl_add_u64 v[218:219], v[222:223], 0, s[12:13]
	ds_read_b128 v[170:173], v163 offset:49152
	ds_read_b128 v[174:177], v163 offset:50176
	ds_read_b128 v[178:181], v163 offset:51200
	ds_read_b128 v[182:185], v163 offset:52224
	ds_read_b128 v[186:189], v163 offset:53248
	ds_read_b128 v[190:193], v163 offset:54272
	ds_read_b128 v[194:197], v163 offset:55296
	ds_read_b128 v[198:201], v163 offset:56320
	global_load_lds_dwordx4 v[218:219], off
	v_lshl_add_u64 v[218:219], v[224:225], 0, s[12:13]
	s_mov_b32 m0, s61
	s_nop 0
	global_load_lds_dwordx4 v[218:219], off
	s_add_u32 s54, s54, 0x40080
	s_addc_u32 s55, s55, 0
	s_add_i32 s45, s56, s21
	v_lshl_add_u64 v[240:241], s[54:55], 0, v[138:139]
	s_mov_b32 m0, s45
	s_nop 0
	global_load_lds_dwordx4 v[240:241], off
	v_lshl_add_u64 v[240:241], s[54:55], 0, v[142:143]
	s_add_i32 m0, s45, 0x2000
	s_nop 0
	global_load_lds_dwordx4 v[240:241], off
	s_waitcnt vmcnt(8) lgkmcnt(0)
	s_barrier
	s_setprio 1
	v_mfma_f32_16x16x32_bf16 v[60:63], v[150:153], v[170:173], v[60:63]
	v_mfma_f32_16x16x32_bf16 v[56:59], v[158:161], v[170:173], v[56:59]
	v_mfma_f32_16x16x32_bf16 v[52:55], v[150:153], v[178:181], v[52:55]
	v_mfma_f32_16x16x32_bf16 v[44:47], v[158:161], v[178:181], v[44:47]
	v_mfma_f32_16x16x32_bf16 v[36:39], v[150:153], v[186:189], v[36:39]
	v_mfma_f32_16x16x32_bf16 v[28:31], v[158:161], v[186:189], v[28:31]
	v_mfma_f32_16x16x32_bf16 v[20:23], v[150:153], v[194:197], v[20:23]
	v_mfma_f32_16x16x32_bf16 v[12:15], v[158:161], v[194:197], v[12:15]
	v_mfma_f32_16x16x32_bf16 v[60:63], v[154:157], v[174:177], v[60:63]
	v_mfma_f32_16x16x32_bf16 v[56:59], v[166:169], v[174:177], v[56:59]
	v_mfma_f32_16x16x32_bf16 v[52:55], v[154:157], v[182:185], v[52:55]
	v_mfma_f32_16x16x32_bf16 v[44:47], v[166:169], v[182:185], v[44:47]
	v_mfma_f32_16x16x32_bf16 v[36:39], v[154:157], v[190:193], v[36:39]
	v_mfma_f32_16x16x32_bf16 v[28:31], v[166:169], v[190:193], v[28:31]
	v_mfma_f32_16x16x32_bf16 v[20:23], v[154:157], v[198:201], v[20:23]
	v_mfma_f32_16x16x32_bf16 v[12:15], v[166:169], v[198:201], v[12:15]
	v_mfma_f32_16x16x32_bf16 v[48:51], v[202:205], v[170:173], v[48:51]
	v_mfma_f32_16x16x32_bf16 v[40:43], v[210:213], v[170:173], v[40:43]
	v_mfma_f32_16x16x32_bf16 v[32:35], v[202:205], v[178:181], v[32:35]
	v_mfma_f32_16x16x32_bf16 v[24:27], v[210:213], v[178:181], v[24:27]
	v_mfma_f32_16x16x32_bf16 v[16:19], v[202:205], v[186:189], v[16:19]
	v_mfma_f32_16x16x32_bf16 v[8:11], v[210:213], v[186:189], v[8:11]
	v_mfma_f32_16x16x32_bf16 v[4:7], v[202:205], v[194:197], v[4:7]
	v_mfma_f32_16x16x32_bf16 v[0:3], v[210:213], v[194:197], v[0:3]
	v_mfma_f32_16x16x32_bf16 v[48:51], v[206:209], v[174:177], v[48:51]
	v_mfma_f32_16x16x32_bf16 v[40:43], v[214:217], v[174:177], v[40:43]
	v_mfma_f32_16x16x32_bf16 v[32:35], v[206:209], v[182:185], v[32:35]
	v_mfma_f32_16x16x32_bf16 v[24:27], v[214:217], v[182:185], v[24:27]
	v_mfma_f32_16x16x32_bf16 v[16:19], v[206:209], v[190:193], v[16:19]
	v_mfma_f32_16x16x32_bf16 v[8:11], v[214:217], v[190:193], v[8:11]
	v_mfma_f32_16x16x32_bf16 v[4:7], v[206:209], v[198:201], v[4:7]
	v_mfma_f32_16x16x32_bf16 v[0:3], v[214:217], v[198:201], v[0:3]
	s_setprio 0
	s_add_u32 s50, s50, 0x100
	s_addc_u32 s51, s51, 0
	s_add_u32 s41, s41, 0x100
	s_addc_u32 s43, s43, 0
	s_cmp_ge_i32 s77, s76
	s_mov_b32 s45, s77
	s_barrier
	s_cbranch_scc0 .LBB0_1146
	v_lshl_add_u32 v150, s8, 8, v133
	v_lshl_or_b32 v154, s44, 8, v162
	s_cmp_lg_u32 s75, 0
	v_ashrrev_i32_e32 v155, 31, v154
	v_or_b32_e32 v160, 16, v150
	v_or_b32_e32 v158, 32, v150
	v_or_b32_e32 v156, 48, v150
	s_cbranch_scc0 .LBB0_1149
	s_add_i32 s8, s75, -1
	s_lshl_b64 s[44:45], s[8:9], 21
	s_add_u32 s44, s92, s44
	s_addc_u32 s45, s93, s45
	v_lshl_add_u64 v[152:153], v[154:155], 2, s[44:45]
	v_ashrrev_i32_e32 v151, 31, v150
	v_ashrrev_i32_e32 v161, 31, v160
	v_lshl_add_u64 v[152:153], v[152:153], 0, s[22:23]
	v_lshlrev_b64 v[166:167], 12, v[150:151]
	v_lshlrev_b64 v[168:169], 12, v[160:161]
	v_lshl_add_u64 v[166:167], v[152:153], 0, v[166:167]
	v_lshl_add_u64 v[168:169], v[152:153], 0, v[168:169]
	v_ashrrev_i32_e32 v159, 31, v158
	global_store_dwordx4 v[166:167], v[124:127], off
	global_store_dwordx4 v[166:167], v[120:123], off offset:16
	global_store_dwordx4 v[166:167], v[112:115], off offset:512
	global_store_dwordx4 v[166:167], v[104:107], off offset:528
	global_store_dwordx4 v[168:169], v[116:119], off
	global_store_dwordx4 v[168:169], v[108:111], off offset:16
	global_store_dwordx4 v[168:169], v[96:99], off offset:512
	global_store_dwordx4 v[168:169], v[88:91], off offset:528
	v_lshlrev_b64 v[168:169], 12, v[158:159]
	v_lshl_add_u64 v[168:169], v[152:153], 0, v[168:169]
	v_ashrrev_i32_e32 v157, 31, v156
	global_store_dwordx4 v[168:169], v[100:103], off
	global_store_dwordx4 v[168:169], v[92:95], off offset:16
	global_store_dwordx4 v[168:169], v[80:83], off offset:512
	global_store_dwordx4 v[168:169], v[72:75], off offset:528
	v_lshlrev_b64 v[168:169], 12, v[156:157]
	v_lshl_add_u64 v[152:153], v[152:153], 0, v[168:169]
	v_add_co_u32_e32 v168, vcc, s68, v166
	global_store_dwordx4 v[152:153], v[84:87], off
	global_store_dwordx4 v[152:153], v[76:79], off offset:16
	global_store_dwordx4 v[152:153], v[68:71], off offset:512
	global_store_dwordx4 v[152:153], v[64:67], off offset:528
	v_addc_co_u32_e32 v169, vcc, 0, v167, vcc
	v_lshl_add_u64 v[152:153], v[166:167], 0, s[24:25]
	global_store_dwordx4 v[168:169], v[60:63], off
	global_store_dwordx4 v[152:153], v[56:59], off offset:16
	global_store_dwordx4 v[152:153], v[48:51], off offset:512
	global_store_dwordx4 v[152:153], v[40:43], off offset:528
	v_add_co_u32_e32 v168, vcc, s69, v166
	v_lshl_add_u64 v[152:153], v[166:167], 0, s[26:27]
	s_nop 0
	v_addc_co_u32_e32 v169, vcc, 0, v167, vcc
	global_store_dwordx4 v[168:169], v[52:55], off
	global_store_dwordx4 v[152:153], v[44:47], off offset:16
	global_store_dwordx4 v[152:153], v[32:35], off offset:512
	global_store_dwordx4 v[152:153], v[24:27], off offset:528
	v_add_co_u32_e32 v168, vcc, s70, v166
	v_lshl_add_u64 v[152:153], v[166:167], 0, s[28:29]
	s_nop 0
	v_addc_co_u32_e32 v169, vcc, 0, v167, vcc
	global_store_dwordx4 v[168:169], v[36:39], off
	global_store_dwordx4 v[152:153], v[28:31], off offset:16
	global_store_dwordx4 v[152:153], v[16:19], off offset:512
	global_store_dwordx4 v[152:153], v[8:11], off offset:528
	v_lshl_add_u64 v[152:153], v[166:167], 0, s[36:37]
	v_add_co_u32_e32 v166, vcc, 0xb0000, v166
	s_nop 1
	v_addc_co_u32_e32 v167, vcc, 0, v167, vcc
	global_store_dwordx4 v[166:167], v[20:23], off
	global_store_dwordx4 v[152:153], v[12:15], off offset:16
	global_store_dwordx4 v[152:153], v[4:7], off offset:512
	global_store_dwordx4 v[152:153], v[0:3], off offset:528
	s_cbranch_execnz .LBB0_1131
	s_branch .LBB0_1130
